# k19 + leading half's align barrier moved from epilogue entry to before the first vmcnt(0) wait (8 epilogues)
# baseline (speedup 1.0000x reference)
.LBB0_209:
.LBB0_211:
	v_lshl_or_b32 v170, s72, 7, v156
	v_ashrrev_i32_e32 v171, 31, v170
	v_lshlrev_b64 v[148:149], 2, v[170:171]
	v_lshl_add_u64 v[150:151], s[10:11], 0, v[148:149]
	v_lshl_add_u64 v[148:149], s[24:25], 0, v[148:149]
	global_load_dwordx4 v[152:155], v[150:151], off
	global_load_dwordx4 v[158:161], v[148:149], off
	global_load_dwordx4 v[162:165], v[150:151], off offset:16
	global_load_dwordx4 v[166:169], v[148:149], off offset:16
	v_lshl_add_u32 v148, s48, 8, v1
	v_ashrrev_i32_e32 v149, 31, v148
	v_lshl_add_u64 v[150:151], v[148:149], 2, s[26:27]
	global_load_dword v172, v[150:151], off
	global_load_dword v192, v[150:151], off offset:64
	global_load_dword v194, v[150:151], off offset:128
	global_load_dword v196, v[150:151], off offset:192
	global_load_dword v198, v[150:151], off offset:512
	global_load_dword v200, v[150:151], off offset:576
	global_load_dword v202, v[150:151], off offset:640
	global_load_dword v204, v[150:151], off offset:704
	v_cvt_f32_i32_e32 v175, v126
	v_cvt_f32_i32_e32 v174, v122
	v_cvt_f32_i32_e32 v177, v127
	v_cvt_f32_i32_e32 v176, v123
	v_cvt_f32_i32_e32 v179, v128
	v_cvt_f32_i32_e32 v178, v124
	v_cvt_f32_i32_e32 v180, v125
	v_cvt_f32_i32_e32 v187, v120
	v_cvt_f32_i32_e32 v189, v121
	v_cvt_f32_i32_e32 v181, v129
	v_cvt_f32_i32_e32 v183, v118
	v_cvt_f32_i32_e32 v182, v114
	v_cvt_f32_i32_e32 v185, v119
	v_cvt_f32_i32_e32 v184, v115
	v_cvt_f32_i32_e32 v186, v116
	v_cvt_f32_i32_e32 v188, v117
	v_cvt_f32_i32_e32 v111, v111
	v_cvt_f32_i32_e32 v103, v103
	v_cvt_f32_i32_e32 v113, v113
	v_cvt_f32_i32_e32 v105, v105
	v_cvt_f32_i32_e32 v95, v95
	v_cvt_f32_i32_e32 v87, v87
	v_cvt_f32_i32_e32 v97, v97
	v_cvt_f32_i32_e32 v89, v89
	v_cvt_f32_i32_e32 v79, v79
	v_cvt_f32_i32_e32 v71, v71
	v_cvt_f32_i32_e32 v81, v81
	v_cvt_f32_i32_e32 v73, v73
	v_cvt_f32_i32_e32 v63, v63
	v_cvt_f32_i32_e32 v55, v55
	v_cvt_f32_i32_e32 v65, v65
	v_cvt_f32_i32_e32 v57, v57
	v_cvt_f32_i32_e32 v47, v47
	v_cvt_f32_i32_e32 v49, v49
	v_cvt_f32_i32_e32 v39, v39
	v_cvt_f32_i32_e32 v41, v41
	v_cvt_f32_i32_e32 v31, v31
	v_cvt_f32_i32_e32 v33, v33
	v_cvt_f32_i32_e32 v23, v23
	v_cvt_f32_i32_e32 v25, v25
	v_cvt_f32_i32_e32 v15, v15
	v_cvt_f32_i32_e32 v17, v17
	v_cvt_f32_i32_e32 v7, v7
	v_cvt_f32_i32_e32 v9, v9
	s_cmp_lg_u64 s[40:41], 0
	s_cbranch_scc0 .Lalb_1
	s_barrier
.Lalb_1:
	s_andn2_b64 vcc, exec, s[6:7]
	s_waitcnt vmcnt(0)
	s_mov_b32 s98, 0x3c3a1e78
	s_mov_b32 s100, 0x3bb2d7c8
	v_pk_mul_f32 v[124:125], v[158:159], s[100:101] op_sel_hi:[1,0]
	v_pk_mul_f32 v[120:121], v[152:153], s[98:99] op_sel_hi:[1,0]
	v_pk_mul_f32 v[116:117], v[154:155], s[98:99] op_sel_hi:[1,0]
	v_pk_mul_f32 v[126:127], v[160:161], s[100:101] op_sel_hi:[1,0]
	v_pk_mul_f32 v[114:115], v[164:165], s[98:99] op_sel_hi:[1,0]
	v_pk_mul_f32 v[118:119], v[162:163], s[98:99] op_sel_hi:[1,0]
	v_pk_mul_f32 v[152:153], v[168:169], s[100:101] op_sel_hi:[1,0]
	v_pk_mul_f32 v[128:129], v[166:167], s[100:101] op_sel_hi:[1,0]
	v_mov_b32_e32 v122, v124
	v_mov_b32_e32 v123, v120
	v_mov_b32_e32 v120, v125
	v_mov_b32_e32 v124, v126
	v_mov_b32_e32 v125, v116
	v_mov_b32_e32 v116, v127
	v_mov_b32_e32 v126, v128
	v_mov_b32_e32 v127, v118
	v_mov_b32_e32 v118, v129
	v_mov_b32_e32 v128, v152
	v_mov_b32_e32 v129, v114
	v_mov_b32_e32 v114, v153
	v_pk_mul_f32 v[152:153], v[122:123], v[172:173] op_sel_hi:[1,0]
	v_pk_mul_f32 v[154:155], v[120:121], v[172:173] op_sel_hi:[1,0]
	v_pk_mul_f32 v[158:159], v[124:125], v[172:173] op_sel_hi:[1,0]
	v_pk_mul_f32 v[152:153], v[152:153], v[174:175]
	v_pk_mul_f32 v[154:155], v[154:155], v[176:177]
	v_pk_mul_f32 v[160:161], v[116:117], v[172:173] op_sel_hi:[1,0]
	v_pk_mul_f32 v[162:163], v[172:173], v[126:127] op_sel_hi:[0,1]
	v_pk_mul_f32 v[164:165], v[172:173], v[118:119] op_sel_hi:[0,1]
	v_pk_mul_f32 v[166:167], v[172:173], v[128:129] op_sel_hi:[0,1]
	v_pk_mul_f32 v[168:169], v[172:173], v[114:115] op_sel_hi:[0,1]
	v_pk_mul_f32 v[158:159], v[158:159], v[178:179]
	v_exp_f32_e64 v149, -v153
	v_exp_f32_e64 v172, -v155
	v_exp_f32_e64 v173, -v159
	v_pk_mul_f32 v[160:161], v[160:161], v[180:181]
	v_add_f32_e32 v149, 1.0, v149
	v_add_f32_e32 v172, 1.0, v172
	v_pk_mul_f32 v[162:163], v[162:163], v[182:183]
	v_add_f32_e32 v173, 1.0, v173
	v_rcp_f32_e32 v149, v149
	v_rcp_f32_e32 v172, v172
	v_rcp_f32_e32 v173, v173
	v_exp_f32_e64 v174, -v161
	v_exp_f32_e64 v175, -v163
	v_mul_f32_e32 v149, v153, v149
	v_mul_f32_e32 v153, v155, v172
	v_pk_mul_f32 v[164:165], v[164:165], v[184:185]
	v_mul_f32_e32 v155, v159, v173
	v_mul_f32_e32 v149, v152, v149
	v_mul_f32_e32 v154, v154, v153
	v_pk_mul_f32 v[152:153], v[168:169], v[188:189]
	v_pk_mul_f32 v[166:167], v[166:167], v[186:187]
	v_add_f32_e32 v174, 1.0, v174
	v_add_f32_e32 v175, 1.0, v175
	v_mul_f32_e32 v155, v158, v155
	v_exp_f32_e64 v176, -v165
	v_rcp_f32_e32 v174, v174
	v_rcp_f32_e32 v175, v175
	v_exp_f32_e64 v158, -v153
	v_exp_f32_e64 v177, -v167
	v_add_f32_e32 v176, 1.0, v176
	v_mul_f32_e32 v159, v161, v174
	v_mul_f32_e32 v161, v163, v175
	v_add_f32_e32 v158, 1.0, v158
	v_rcp_f32_e32 v176, v176
	v_mul_f32_e32 v159, v160, v159
	v_mul_f32_e32 v160, v162, v161
	v_add_f32_e32 v162, 1.0, v177
	v_rcp_f32_e32 v158, v158
	v_rcp_f32_e32 v162, v162
	v_mul_f32_e32 v161, v165, v176
	v_mul_f32_e32 v161, v164, v161
	v_mul_f32_e32 v153, v153, v158
	v_mul_f32_e32 v162, v167, v162
	v_mul_f32_e32 v152, v152, v153
	v_mul_f32_e32 v162, v166, v162
	v_cvt_pk_bf16_f32 v158, v149, v154
	v_cvt_pk_bf16_f32 v159, v155, v159
	v_cvt_pk_bf16_f32 v160, v160, v161
	v_cvt_pk_bf16_f32 v161, v162, v152
	v_mov_b64_e32 v[152:153], s[36:37]
	v_mad_i64_i32 v[162:163], s[0:1], v148, s71, v[152:153]
	v_lshlrev_b64 v[154:155], 1, v[170:171]
	v_lshl_add_u64 v[162:163], v[162:163], 0, v[154:155]
	global_store_dwordx4 v[162:163], v[158:161], off
	v_cvt_f32_i32_e32 v163, v110
	v_cvt_f32_i32_e32 v162, v106
	v_or_b32_e32 v158, 16, v148
	v_ashrrev_i32_e32 v159, 31, v158
	v_lshl_add_u64 v[160:161], v[158:159], 2, s[26:27]
	s_nop 1
	v_cvt_f32_i32_e32 v110, v107
	v_cvt_f32_i32_e32 v107, v112
	v_cvt_f32_i32_e32 v106, v108
	v_cvt_f32_i32_e32 v112, v109
	v_cvt_f32_i32_e32 v109, v102
	v_cvt_f32_i32_e32 v108, v98
	v_cvt_f32_i32_e32 v102, v99
	v_cvt_f32_i32_e32 v99, v104
	v_cvt_f32_i32_e32 v98, v100
	v_cvt_f32_i32_e32 v104, v101
	v_mov_b32_e32 v160, v192
	v_pk_mul_f32 v[170:171], v[126:127], v[160:161] op_sel_hi:[1,0]
	v_pk_mul_f32 v[100:101], v[122:123], v[160:161] op_sel_hi:[1,0]
	v_pk_mul_f32 v[108:109], v[170:171], v[108:109]
	v_pk_mul_f32 v[100:101], v[100:101], v[162:163]
	v_pk_mul_f32 v[164:165], v[120:121], v[160:161] op_sel_hi:[1,0]
	v_exp_f32_e64 v162, -v109
	v_pk_mul_f32 v[110:111], v[164:165], v[110:111]
	v_exp_f32_e64 v149, -v101
	v_exp_f32_e64 v159, -v111
	v_add_f32_e32 v162, 1.0, v162
	v_rcp_f32_e32 v162, v162
	v_pk_mul_f32 v[172:173], v[118:119], v[160:161] op_sel_hi:[1,0]
	v_pk_mul_f32 v[174:175], v[128:129], v[160:161] op_sel_hi:[1,0]
	v_pk_mul_f32 v[166:167], v[124:125], v[160:161] op_sel_hi:[1,0]
	v_pk_mul_f32 v[168:169], v[116:117], v[160:161] op_sel_hi:[1,0]
	v_pk_mul_f32 v[160:161], v[114:115], v[160:161] op_sel_hi:[1,0]
	v_pk_mul_f32 v[102:103], v[172:173], v[102:103]
	v_pk_mul_f32 v[98:99], v[174:175], v[98:99]
	v_add_f32_e32 v149, 1.0, v149
	v_add_f32_e32 v159, 1.0, v159
	v_pk_mul_f32 v[106:107], v[166:167], v[106:107]
	v_pk_mul_f32 v[112:113], v[168:169], v[112:113]
	v_pk_mul_f32 v[104:105], v[160:161], v[104:105]
	v_rcp_f32_e32 v149, v149
	v_rcp_f32_e32 v159, v159
	v_exp_f32_e64 v163, -v103
	v_exp_f32_e64 v164, -v99
	v_mul_f32_e32 v109, v109, v162
	v_exp_f32_e64 v160, -v107
	v_exp_f32_e64 v161, -v113
	v_mul_f32_e32 v108, v108, v109
	v_exp_f32_e64 v109, -v105
	v_mul_f32_e32 v101, v101, v149
	v_mul_f32_e32 v111, v111, v159
	v_add_f32_e32 v163, 1.0, v163
	v_mul_f32_e32 v100, v100, v101
	v_mul_f32_e32 v101, v110, v111
	v_add_f32_e32 v110, 1.0, v164
	v_add_f32_e32 v160, 1.0, v160
	v_add_f32_e32 v161, 1.0, v161
	v_rcp_f32_e32 v163, v163
	v_rcp_f32_e32 v110, v110
	v_add_f32_e32 v109, 1.0, v109
	v_rcp_f32_e32 v160, v160
	v_rcp_f32_e32 v161, v161
	v_rcp_f32_e32 v109, v109
	v_mul_f32_e32 v103, v103, v163
	v_mul_f32_e32 v99, v99, v110
	v_mul_f32_e32 v107, v107, v160
	v_mul_f32_e32 v113, v113, v161
	v_mul_f32_e32 v102, v102, v103
	v_mul_f32_e32 v103, v98, v99
	v_mul_f32_e32 v98, v105, v109
	v_mul_f32_e32 v106, v106, v107
	v_mul_f32_e32 v107, v112, v113
	v_mul_f32_e32 v104, v104, v98
	v_cvt_pk_bf16_f32 v98, v100, v101
	v_cvt_pk_bf16_f32 v99, v106, v107
	v_cvt_pk_bf16_f32 v100, v108, v102
	v_cvt_pk_bf16_f32 v101, v103, v104
	v_mad_i64_i32 v[102:103], s[0:1], v158, s71, v[152:153]
	v_lshl_add_u64 v[102:103], v[102:103], 0, v[154:155]
	global_store_dwordx4 v[102:103], v[98:101], off
	v_cvt_f32_i32_e32 v103, v94
	v_cvt_f32_i32_e32 v102, v90
	v_or_b32_e32 v98, 32, v148
	v_ashrrev_i32_e32 v99, 31, v98
	v_lshl_add_u64 v[100:101], v[98:99], 2, s[26:27]
	s_nop 1
	v_cvt_f32_i32_e32 v94, v91
	v_cvt_f32_i32_e32 v91, v96
	v_cvt_f32_i32_e32 v90, v92
	v_cvt_f32_i32_e32 v96, v93
	v_cvt_f32_i32_e32 v93, v86
	v_cvt_f32_i32_e32 v92, v82
	v_cvt_f32_i32_e32 v86, v83
	v_cvt_f32_i32_e32 v83, v88
	v_cvt_f32_i32_e32 v82, v84
	v_cvt_f32_i32_e32 v88, v85
	v_mov_b32_e32 v100, v194
	v_pk_mul_f32 v[110:111], v[126:127], v[100:101] op_sel_hi:[1,0]
	v_pk_mul_f32 v[84:85], v[122:123], v[100:101] op_sel_hi:[1,0]
	v_pk_mul_f32 v[92:93], v[110:111], v[92:93]
	v_pk_mul_f32 v[84:85], v[84:85], v[102:103]
	v_exp_f32_e64 v103, -v93
	v_pk_mul_f32 v[104:105], v[120:121], v[100:101] op_sel_hi:[1,0]
	v_pk_mul_f32 v[112:113], v[118:119], v[100:101] op_sel_hi:[1,0]
	v_pk_mul_f32 v[158:159], v[128:129], v[100:101] op_sel_hi:[1,0]
	v_pk_mul_f32 v[106:107], v[124:125], v[100:101] op_sel_hi:[1,0]
	v_pk_mul_f32 v[108:109], v[116:117], v[100:101] op_sel_hi:[1,0]
	v_pk_mul_f32 v[100:101], v[114:115], v[100:101] op_sel_hi:[1,0]
	v_pk_mul_f32 v[94:95], v[104:105], v[94:95]
	v_pk_mul_f32 v[86:87], v[112:113], v[86:87]
	v_pk_mul_f32 v[82:83], v[158:159], v[82:83]
	v_pk_mul_f32 v[90:91], v[106:107], v[90:91]
	v_pk_mul_f32 v[96:97], v[108:109], v[96:97]
	v_pk_mul_f32 v[88:89], v[100:101], v[88:89]
	v_add_f32_e32 v103, 1.0, v103
	v_exp_f32_e64 v99, -v85
	v_exp_f32_e64 v100, -v95
	v_exp_f32_e64 v104, -v87
	v_exp_f32_e64 v105, -v83
	v_rcp_f32_e32 v103, v103
	v_exp_f32_e64 v101, -v91
	v_exp_f32_e64 v102, -v97
	v_exp_f32_e64 v106, -v89
	v_add_f32_e32 v99, 1.0, v99
	v_add_f32_e32 v100, 1.0, v100
	v_add_f32_e32 v104, 1.0, v104
	v_add_f32_e32 v105, 1.0, v105
	v_mul_f32_e32 v93, v93, v103
	v_add_f32_e32 v101, 1.0, v101
	v_add_f32_e32 v102, 1.0, v102
	v_rcp_f32_e32 v99, v99
	v_rcp_f32_e32 v100, v100
	v_rcp_f32_e32 v104, v104
	v_rcp_f32_e32 v105, v105
	v_mul_f32_e32 v92, v92, v93
	v_add_f32_e32 v93, 1.0, v106
	v_rcp_f32_e32 v101, v101
	v_rcp_f32_e32 v102, v102
	v_rcp_f32_e32 v93, v93
	v_mul_f32_e32 v85, v85, v99
	v_mul_f32_e32 v95, v95, v100
	v_mul_f32_e32 v87, v87, v104
	v_mul_f32_e32 v83, v83, v105
	v_mul_f32_e32 v91, v91, v101
	v_mul_f32_e32 v97, v97, v102
	v_mul_f32_e32 v84, v84, v85
	v_mul_f32_e32 v85, v94, v95
	v_mul_f32_e32 v86, v86, v87
	v_mul_f32_e32 v87, v82, v83
	v_mul_f32_e32 v82, v89, v93
	v_mul_f32_e32 v90, v90, v91
	v_mul_f32_e32 v91, v96, v97
	v_mul_f32_e32 v88, v88, v82
	v_cvt_pk_bf16_f32 v82, v84, v85
	v_cvt_pk_bf16_f32 v83, v90, v91
	v_cvt_pk_bf16_f32 v84, v92, v86
	v_cvt_pk_bf16_f32 v85, v87, v88
	v_mad_i64_i32 v[86:87], s[0:1], v98, s71, v[152:153]
	v_lshl_add_u64 v[86:87], v[86:87], 0, v[154:155]
	global_store_dwordx4 v[86:87], v[82:85], off
	v_cvt_f32_i32_e32 v87, v78
	v_cvt_f32_i32_e32 v86, v74
	v_or_b32_e32 v82, 48, v148
	v_ashrrev_i32_e32 v83, 31, v82
	v_lshl_add_u64 v[84:85], v[82:83], 2, s[26:27]
	s_nop 1
	v_cvt_f32_i32_e32 v78, v75
	v_cvt_f32_i32_e32 v75, v80
	v_cvt_f32_i32_e32 v74, v76
	v_cvt_f32_i32_e32 v80, v77
	v_cvt_f32_i32_e32 v77, v70
	v_cvt_f32_i32_e32 v76, v66
	v_cvt_f32_i32_e32 v70, v67
	v_cvt_f32_i32_e32 v67, v72
	v_cvt_f32_i32_e32 v66, v68
	v_cvt_f32_i32_e32 v72, v69
	v_mov_b32_e32 v84, v196
	v_pk_mul_f32 v[68:69], v[122:123], v[84:85] op_sel_hi:[1,0]
	v_pk_mul_f32 v[88:89], v[120:121], v[84:85] op_sel_hi:[1,0]
	v_pk_mul_f32 v[96:97], v[118:119], v[84:85] op_sel_hi:[1,0]
	v_pk_mul_f32 v[98:99], v[128:129], v[84:85] op_sel_hi:[1,0]
	v_pk_mul_f32 v[90:91], v[124:125], v[84:85] op_sel_hi:[1,0]
	v_pk_mul_f32 v[92:93], v[116:117], v[84:85] op_sel_hi:[1,0]
	v_pk_mul_f32 v[94:95], v[126:127], v[84:85] op_sel_hi:[1,0]
	v_pk_mul_f32 v[84:85], v[114:115], v[84:85] op_sel_hi:[1,0]
	v_pk_mul_f32 v[68:69], v[68:69], v[86:87]
	v_pk_mul_f32 v[78:79], v[88:89], v[78:79]
	v_pk_mul_f32 v[70:71], v[96:97], v[70:71]
	v_pk_mul_f32 v[66:67], v[98:99], v[66:67]
	v_pk_mul_f32 v[74:75], v[90:91], v[74:75]
	v_pk_mul_f32 v[80:81], v[92:93], v[80:81]
	v_pk_mul_f32 v[76:77], v[94:95], v[76:77]
	v_pk_mul_f32 v[72:73], v[84:85], v[72:73]
	v_exp_f32_e64 v83, -v69
	v_exp_f32_e64 v84, -v79
	v_exp_f32_e64 v88, -v71
	v_exp_f32_e64 v89, -v67
	v_exp_f32_e64 v85, -v75
	v_exp_f32_e64 v86, -v81
	v_exp_f32_e64 v87, -v77
	v_exp_f32_e64 v90, -v73
	v_add_f32_e32 v83, 1.0, v83
	v_add_f32_e32 v84, 1.0, v84
	v_add_f32_e32 v88, 1.0, v88
	v_add_f32_e32 v89, 1.0, v89
	v_add_f32_e32 v85, 1.0, v85
	v_add_f32_e32 v86, 1.0, v86
	v_add_f32_e32 v87, 1.0, v87
	v_add_f32_e32 v90, 1.0, v90
	v_rcp_f32_e32 v83, v83
	v_rcp_f32_e32 v84, v84
	v_rcp_f32_e32 v88, v88
	v_rcp_f32_e32 v89, v89
	v_rcp_f32_e32 v85, v85
	v_rcp_f32_e32 v86, v86
	v_rcp_f32_e32 v87, v87
	v_rcp_f32_e32 v90, v90
	v_mul_f32_e32 v69, v69, v83
	v_mul_f32_e32 v79, v79, v84
	v_mul_f32_e32 v71, v71, v88
	v_mul_f32_e32 v67, v67, v89
	v_mul_f32_e32 v75, v75, v85
	v_mul_f32_e32 v81, v81, v86
	v_mul_f32_e32 v77, v77, v87
	v_mul_f32_e32 v68, v68, v69
	v_mul_f32_e32 v69, v78, v79
	v_mul_f32_e32 v70, v70, v71
	v_mul_f32_e32 v71, v66, v67
	v_mul_f32_e32 v66, v73, v90
	v_mul_f32_e32 v74, v74, v75
	v_mul_f32_e32 v75, v80, v81
	v_mul_f32_e32 v76, v76, v77
	v_mul_f32_e32 v72, v72, v66
	v_cvt_pk_bf16_f32 v66, v68, v69
	v_cvt_pk_bf16_f32 v67, v74, v75
	v_cvt_pk_bf16_f32 v68, v76, v70
	v_cvt_pk_bf16_f32 v69, v71, v72
	v_mad_i64_i32 v[70:71], s[0:1], v82, s71, v[152:153]
	v_lshl_add_u64 v[70:71], v[70:71], 0, v[154:155]
	global_store_dwordx4 v[70:71], v[66:69], off
	s_nop 1
	v_add_u32_e32 v82, 0x80, v148
	v_cvt_f32_i32_e32 v69, v62
	v_cvt_f32_i32_e32 v68, v58
	v_cvt_f32_i32_e32 v62, v59
	v_cvt_f32_i32_e32 v59, v64
	v_cvt_f32_i32_e32 v58, v60
	v_cvt_f32_i32_e32 v64, v61
	v_cvt_f32_i32_e32 v61, v54
	v_cvt_f32_i32_e32 v60, v50
	v_cvt_f32_i32_e32 v54, v51
	v_cvt_f32_i32_e32 v51, v56
	v_cvt_f32_i32_e32 v50, v52
	v_cvt_f32_i32_e32 v56, v53
	v_mov_b32_e32 v66, v198
	v_pk_mul_f32 v[52:53], v[122:123], v[66:67] op_sel_hi:[1,0]
	v_pk_mul_f32 v[70:71], v[120:121], v[66:67] op_sel_hi:[1,0]
	v_pk_mul_f32 v[78:79], v[118:119], v[66:67] op_sel_hi:[1,0]
	v_pk_mul_f32 v[80:81], v[128:129], v[66:67] op_sel_hi:[1,0]
	v_pk_mul_f32 v[72:73], v[124:125], v[66:67] op_sel_hi:[1,0]
	v_pk_mul_f32 v[74:75], v[116:117], v[66:67] op_sel_hi:[1,0]
	v_pk_mul_f32 v[76:77], v[126:127], v[66:67] op_sel_hi:[1,0]
	v_pk_mul_f32 v[66:67], v[114:115], v[66:67] op_sel_hi:[1,0]
	v_pk_mul_f32 v[52:53], v[52:53], v[68:69]
	v_pk_mul_f32 v[62:63], v[70:71], v[62:63]
	v_pk_mul_f32 v[54:55], v[78:79], v[54:55]
	v_pk_mul_f32 v[50:51], v[80:81], v[50:51]
	v_pk_mul_f32 v[58:59], v[72:73], v[58:59]
	v_pk_mul_f32 v[64:65], v[74:75], v[64:65]
	v_pk_mul_f32 v[60:61], v[76:77], v[60:61]
	v_pk_mul_f32 v[56:57], v[66:67], v[56:57]
	v_exp_f32_e64 v66, -v53
	v_exp_f32_e64 v67, -v63
	v_exp_f32_e64 v71, -v55
	v_exp_f32_e64 v72, -v51
	v_exp_f32_e64 v68, -v59
	v_exp_f32_e64 v69, -v65
	v_exp_f32_e64 v70, -v61
	v_exp_f32_e64 v73, -v57
	v_add_f32_e32 v66, 1.0, v66
	v_add_f32_e32 v67, 1.0, v67
	v_add_f32_e32 v71, 1.0, v71
	v_add_f32_e32 v72, 1.0, v72
	v_add_f32_e32 v68, 1.0, v68
	v_add_f32_e32 v69, 1.0, v69
	v_add_f32_e32 v70, 1.0, v70
	v_add_f32_e32 v73, 1.0, v73
	v_rcp_f32_e32 v66, v66
	v_rcp_f32_e32 v67, v67
	v_rcp_f32_e32 v71, v71
	v_rcp_f32_e32 v72, v72
	v_rcp_f32_e32 v68, v68
	v_rcp_f32_e32 v69, v69
	v_rcp_f32_e32 v70, v70
	v_rcp_f32_e32 v73, v73
	v_mul_f32_e32 v53, v53, v66
	v_mul_f32_e32 v63, v63, v67
	v_mul_f32_e32 v55, v55, v71
	v_mul_f32_e32 v51, v51, v72
	v_mul_f32_e32 v59, v59, v68
	v_mul_f32_e32 v65, v65, v69
	v_mul_f32_e32 v61, v61, v70
	v_mul_f32_e32 v57, v57, v73
	v_mul_f32_e32 v52, v52, v53
	v_mul_f32_e32 v53, v62, v63
	v_mul_f32_e32 v54, v54, v55
	v_mul_f32_e32 v55, v50, v51
	v_mul_f32_e32 v58, v58, v59
	v_mul_f32_e32 v59, v64, v65
	v_mul_f32_e32 v60, v60, v61
	v_mul_f32_e32 v56, v56, v57
	v_cvt_pk_bf16_f32 v50, v52, v53
	v_cvt_pk_bf16_f32 v51, v58, v59
	v_cvt_pk_bf16_f32 v52, v60, v54
	v_cvt_pk_bf16_f32 v53, v55, v56
	v_mad_i64_i32 v[54:55], s[0:1], v82, s71, v[152:153]
	v_lshl_add_u64 v[54:55], v[54:55], 0, v[154:155]
	global_store_dwordx4 v[54:55], v[50:53], off
	s_nop 1
	v_mov_b32_e32 v50, v200
	v_pk_mul_f32 v[56:57], v[120:121], v[50:51] op_sel_hi:[1,0]
	v_cvt_f32_i32_e32 v53, v46
	v_cvt_f32_i32_e32 v52, v42
	v_cvt_f32_i32_e32 v46, v43
	v_cvt_f32_i32_e32 v43, v48
	v_cvt_f32_i32_e32 v42, v44
	v_cvt_f32_i32_e32 v48, v45
	v_cvt_f32_i32_e32 v45, v38
	v_cvt_f32_i32_e32 v44, v34
	v_cvt_f32_i32_e32 v38, v35
	v_cvt_f32_i32_e32 v35, v40
	v_cvt_f32_i32_e32 v34, v36
	v_cvt_f32_i32_e32 v40, v37
	v_add_u32_e32 v36, 0x90, v148
	v_mad_i64_i32 v[36:37], s[0:1], v36, s71, v[152:153]
	v_lshl_add_u64 v[54:55], v[36:37], 0, v[154:155]
	v_pk_mul_f32 v[36:37], v[122:123], v[50:51] op_sel_hi:[1,0]
	v_pk_mul_f32 v[58:59], v[124:125], v[50:51] op_sel_hi:[1,0]
	v_pk_mul_f32 v[60:61], v[116:117], v[50:51] op_sel_hi:[1,0]
	v_pk_mul_f32 v[62:63], v[126:127], v[50:51] op_sel_hi:[1,0]
	v_pk_mul_f32 v[64:65], v[118:119], v[50:51] op_sel_hi:[1,0]
	v_pk_mul_f32 v[66:67], v[128:129], v[50:51] op_sel_hi:[1,0]
	v_pk_mul_f32 v[50:51], v[114:115], v[50:51] op_sel_hi:[1,0]
	v_pk_mul_f32 v[36:37], v[36:37], v[52:53]
	v_pk_mul_f32 v[46:47], v[56:57], v[46:47]
	v_pk_mul_f32 v[42:43], v[58:59], v[42:43]
	v_pk_mul_f32 v[48:49], v[60:61], v[48:49]
	v_pk_mul_f32 v[44:45], v[62:63], v[44:45]
	v_pk_mul_f32 v[38:39], v[64:65], v[38:39]
	v_pk_mul_f32 v[34:35], v[66:67], v[34:35]
	v_pk_mul_f32 v[40:41], v[50:51], v[40:41]
	v_exp_f32_e64 v50, -v37
	v_exp_f32_e64 v51, -v47
	v_exp_f32_e64 v52, -v43
	v_exp_f32_e64 v53, -v49
	v_exp_f32_e64 v56, -v45
	v_exp_f32_e64 v57, -v39
	v_exp_f32_e64 v58, -v35
	v_exp_f32_e64 v59, -v41
	v_add_f32_e32 v50, 1.0, v50
	v_add_f32_e32 v51, 1.0, v51
	v_add_f32_e32 v52, 1.0, v52
	v_add_f32_e32 v53, 1.0, v53
	v_add_f32_e32 v56, 1.0, v56
	v_add_f32_e32 v57, 1.0, v57
	v_add_f32_e32 v58, 1.0, v58
	v_add_f32_e32 v59, 1.0, v59
	v_rcp_f32_e32 v50, v50
	v_rcp_f32_e32 v51, v51
	v_rcp_f32_e32 v52, v52
	v_rcp_f32_e32 v53, v53
	v_rcp_f32_e32 v56, v56
	v_rcp_f32_e32 v57, v57
	v_rcp_f32_e32 v58, v58
	v_rcp_f32_e32 v59, v59
	v_mul_f32_e32 v37, v37, v50
	v_mul_f32_e32 v47, v47, v51
	v_mul_f32_e32 v43, v43, v52
	v_mul_f32_e32 v49, v49, v53
	v_mul_f32_e32 v45, v45, v56
	v_mul_f32_e32 v39, v39, v57
	v_mul_f32_e32 v35, v35, v58
	v_mul_f32_e32 v41, v41, v59
	v_mul_f32_e32 v36, v36, v37
	v_mul_f32_e32 v37, v46, v47
	v_mul_f32_e32 v42, v42, v43
	v_mul_f32_e32 v43, v48, v49
	v_mul_f32_e32 v44, v44, v45
	v_mul_f32_e32 v38, v38, v39
	v_mul_f32_e32 v39, v34, v35
	v_mul_f32_e32 v40, v40, v41
	v_cvt_pk_bf16_f32 v34, v36, v37
	v_cvt_pk_bf16_f32 v35, v42, v43
	v_cvt_pk_bf16_f32 v36, v44, v38
	v_cvt_pk_bf16_f32 v37, v39, v40
	global_store_dwordx4 v[54:55], v[34:37], off
	s_nop 1
	v_mov_b32_e32 v34, v202
	v_pk_mul_f32 v[40:41], v[120:121], v[34:35] op_sel_hi:[1,0]
	v_cvt_f32_i32_e32 v37, v30
	v_cvt_f32_i32_e32 v36, v26
	v_cvt_f32_i32_e32 v30, v27
	v_cvt_f32_i32_e32 v27, v32
	v_cvt_f32_i32_e32 v26, v28
	v_cvt_f32_i32_e32 v32, v29
	v_cvt_f32_i32_e32 v29, v22
	v_cvt_f32_i32_e32 v28, v18
	v_cvt_f32_i32_e32 v22, v19
	v_cvt_f32_i32_e32 v19, v24
	v_cvt_f32_i32_e32 v18, v20
	v_cvt_f32_i32_e32 v24, v21
	v_add_u32_e32 v20, 0xa0, v148
	v_mad_i64_i32 v[20:21], s[0:1], v20, s71, v[152:153]
	v_lshl_add_u64 v[38:39], v[20:21], 0, v[154:155]
	v_pk_mul_f32 v[20:21], v[122:123], v[34:35] op_sel_hi:[1,0]
	v_pk_mul_f32 v[42:43], v[124:125], v[34:35] op_sel_hi:[1,0]
	v_pk_mul_f32 v[44:45], v[116:117], v[34:35] op_sel_hi:[1,0]
	v_pk_mul_f32 v[46:47], v[126:127], v[34:35] op_sel_hi:[1,0]
	v_pk_mul_f32 v[48:49], v[118:119], v[34:35] op_sel_hi:[1,0]
	v_pk_mul_f32 v[50:51], v[128:129], v[34:35] op_sel_hi:[1,0]
	v_pk_mul_f32 v[34:35], v[114:115], v[34:35] op_sel_hi:[1,0]
	v_pk_mul_f32 v[20:21], v[20:21], v[36:37]
	v_pk_mul_f32 v[30:31], v[40:41], v[30:31]
	v_pk_mul_f32 v[26:27], v[42:43], v[26:27]
	v_pk_mul_f32 v[32:33], v[44:45], v[32:33]
	v_pk_mul_f32 v[28:29], v[46:47], v[28:29]
	v_pk_mul_f32 v[22:23], v[48:49], v[22:23]
	v_pk_mul_f32 v[18:19], v[50:51], v[18:19]
	v_pk_mul_f32 v[24:25], v[34:35], v[24:25]
	v_exp_f32_e64 v34, -v21
	v_exp_f32_e64 v35, -v31
	v_exp_f32_e64 v36, -v27
	v_exp_f32_e64 v37, -v33
	v_exp_f32_e64 v40, -v29
	v_exp_f32_e64 v41, -v23
	v_exp_f32_e64 v42, -v19
	v_exp_f32_e64 v43, -v25
	v_add_f32_e32 v34, 1.0, v34
	v_add_f32_e32 v35, 1.0, v35
	v_add_f32_e32 v36, 1.0, v36
	v_add_f32_e32 v37, 1.0, v37
	v_add_f32_e32 v40, 1.0, v40
	v_add_f32_e32 v41, 1.0, v41
	v_add_f32_e32 v42, 1.0, v42
	v_add_f32_e32 v43, 1.0, v43
	v_rcp_f32_e32 v34, v34
	v_rcp_f32_e32 v35, v35
	v_rcp_f32_e32 v36, v36
	v_rcp_f32_e32 v37, v37
	v_rcp_f32_e32 v40, v40
	v_rcp_f32_e32 v41, v41
	v_rcp_f32_e32 v42, v42
	v_rcp_f32_e32 v43, v43
	v_mul_f32_e32 v21, v21, v34
	v_mul_f32_e32 v31, v31, v35
	v_mul_f32_e32 v27, v27, v36
	v_mul_f32_e32 v33, v33, v37
	v_mul_f32_e32 v29, v29, v40
	v_mul_f32_e32 v23, v23, v41
	v_mul_f32_e32 v19, v19, v42
	v_mul_f32_e32 v25, v25, v43
	v_mul_f32_e32 v20, v20, v21
	v_mul_f32_e32 v21, v30, v31
	v_mul_f32_e32 v26, v26, v27
	v_mul_f32_e32 v27, v32, v33
	v_mul_f32_e32 v28, v28, v29
	v_mul_f32_e32 v22, v22, v23
	v_mul_f32_e32 v23, v18, v19
	v_mul_f32_e32 v24, v24, v25
	v_cvt_pk_bf16_f32 v18, v20, v21
	v_cvt_pk_bf16_f32 v19, v26, v27
	v_cvt_pk_bf16_f32 v20, v28, v22
	v_cvt_pk_bf16_f32 v21, v23, v24
	global_store_dwordx4 v[38:39], v[18:21], off
	s_nop 1
	v_mov_b32_e32 v18, v204
	v_pk_mul_f32 v[24:25], v[120:121], v[18:19] op_sel_hi:[1,0]
	v_cvt_f32_i32_e32 v21, v14
	v_cvt_f32_i32_e32 v20, v10
	v_cvt_f32_i32_e32 v14, v11
	v_cvt_f32_i32_e32 v11, v16
	v_cvt_f32_i32_e32 v10, v12
	v_cvt_f32_i32_e32 v16, v13
	v_cvt_f32_i32_e32 v13, v6
	v_cvt_f32_i32_e32 v12, v2
	v_cvt_f32_i32_e32 v6, v3
	v_cvt_f32_i32_e32 v3, v8
	v_cvt_f32_i32_e32 v2, v4
	v_cvt_f32_i32_e32 v8, v5
	v_add_u32_e32 v4, 0xb0, v148
	v_mad_i64_i32 v[4:5], s[0:1], v4, s71, v[152:153]
	v_lshl_add_u64 v[22:23], v[4:5], 0, v[154:155]
	v_pk_mul_f32 v[4:5], v[122:123], v[18:19] op_sel_hi:[1,0]
	v_pk_mul_f32 v[26:27], v[124:125], v[18:19] op_sel_hi:[1,0]
	v_pk_mul_f32 v[28:29], v[116:117], v[18:19] op_sel_hi:[1,0]
	v_pk_mul_f32 v[30:31], v[126:127], v[18:19] op_sel_hi:[1,0]
	v_pk_mul_f32 v[32:33], v[118:119], v[18:19] op_sel_hi:[1,0]
	v_pk_mul_f32 v[34:35], v[128:129], v[18:19] op_sel_hi:[1,0]
	v_pk_mul_f32 v[18:19], v[114:115], v[18:19] op_sel_hi:[1,0]
	v_pk_mul_f32 v[4:5], v[4:5], v[20:21]
	v_pk_mul_f32 v[14:15], v[24:25], v[14:15]
	v_pk_mul_f32 v[10:11], v[26:27], v[10:11]
	v_pk_mul_f32 v[16:17], v[28:29], v[16:17]
	v_pk_mul_f32 v[12:13], v[30:31], v[12:13]
	v_pk_mul_f32 v[6:7], v[32:33], v[6:7]
	v_pk_mul_f32 v[2:3], v[34:35], v[2:3]
	v_pk_mul_f32 v[8:9], v[18:19], v[8:9]
	v_exp_f32_e64 v18, -v5
	v_exp_f32_e64 v19, -v15
	v_exp_f32_e64 v20, -v11
	v_exp_f32_e64 v21, -v17
	v_exp_f32_e64 v24, -v13
	v_exp_f32_e64 v25, -v7
	v_exp_f32_e64 v26, -v3
	v_exp_f32_e64 v27, -v9
	v_add_f32_e32 v18, 1.0, v18
	v_add_f32_e32 v19, 1.0, v19
	v_add_f32_e32 v20, 1.0, v20
	v_add_f32_e32 v21, 1.0, v21
	v_add_f32_e32 v24, 1.0, v24
	v_add_f32_e32 v25, 1.0, v25
	v_add_f32_e32 v26, 1.0, v26
	v_add_f32_e32 v27, 1.0, v27
	v_rcp_f32_e32 v18, v18
	v_rcp_f32_e32 v19, v19
	v_rcp_f32_e32 v20, v20
	v_rcp_f32_e32 v21, v21
	v_rcp_f32_e32 v24, v24
	v_rcp_f32_e32 v25, v25
	v_rcp_f32_e32 v26, v26
	v_rcp_f32_e32 v27, v27
	v_mul_f32_e32 v5, v5, v18
	v_mul_f32_e32 v15, v15, v19
	v_mul_f32_e32 v11, v11, v20
	v_mul_f32_e32 v17, v17, v21
	v_mul_f32_e32 v13, v13, v24
	v_mul_f32_e32 v7, v7, v25
	v_mul_f32_e32 v3, v3, v26
	v_mul_f32_e32 v9, v9, v27
	v_mul_f32_e32 v4, v4, v5
	v_mul_f32_e32 v5, v14, v15
	s_mov_b64 s[0:1], -1
	v_mul_f32_e32 v10, v10, v11
	v_mul_f32_e32 v11, v16, v17
	v_mul_f32_e32 v12, v12, v13
	v_mul_f32_e32 v6, v6, v7
	v_mul_f32_e32 v7, v2, v3
	v_mul_f32_e32 v8, v8, v9
	v_cvt_pk_bf16_f32 v2, v4, v5
	v_cvt_pk_bf16_f32 v3, v10, v11
	v_cvt_pk_bf16_f32 v4, v12, v6
	v_cvt_pk_bf16_f32 v5, v7, v8
	global_store_dwordx4 v[22:23], v[2:5], off
	s_cbranch_vccnz .LBB0_188
	s_andn2_b64 vcc, exec, s[20:21]
	s_cbranch_vccnz .LBB0_187
	s_barrier
	s_branch .LBB0_187

.LBB0_412:
	v_lshl_or_b32 v164, s74, 8, v156
	v_ashrrev_i32_e32 v165, 31, v164
	v_lshl_add_u32 v166, s73, 8, v1
	v_lshl_add_u64 v[150:151], v[164:165], 2, s[16:17]
	v_ashrrev_i32_e32 v167, 31, v166
	global_load_dwordx4 v[160:163], v[150:151], off offset:16
	global_load_dwordx4 v[152:155], v[150:151], off
	v_lshl_add_u64 v[148:149], v[166:167], 2, s[34:35]
	global_load_dword v170, v[148:149], off
	global_load_dword v190, v[148:149], off
	global_load_dword v192, v[148:149], off offset:64
	global_load_dword v194, v[148:149], off offset:128
	global_load_dword v196, v[148:149], off offset:192
	global_load_dword v198, v[148:149], off offset:512
	global_load_dword v200, v[148:149], off offset:576
	global_load_dword v202, v[148:149], off offset:640
	global_load_dword v204, v[148:149], off offset:704
	global_load_dwordx4 v[206:209], v[150:151], off offset:512
	global_load_dwordx4 v[210:213], v[150:151], off offset:528
	v_cvt_f32_i32_e32 v171, v126
	v_cvt_f32_i32_e32 v172, v127
	v_cvt_f32_i32_e32 v173, v128
	v_cvt_f32_i32_e32 v174, v129
	v_cvt_f32_i32_e32 v175, v122
	v_cvt_f32_i32_e32 v176, v123
	v_cvt_f32_i32_e32 v177, v124
	v_cvt_f32_i32_e32 v178, v125
	v_lshlrev_b64 v[122:123], 13, v[166:167]
	v_or_b32_e32 v168, 16, v166
	v_lshlrev_b64 v[164:165], 1, v[164:165]
	v_lshl_add_u64 v[122:123], s[30:31], 0, v[122:123]
	v_ashrrev_i32_e32 v169, 31, v168
	v_lshl_add_u64 v[122:123], v[122:123], 0, v[164:165]
	v_lshl_add_u64 v[124:125], v[168:169], 2, s[34:35]
	v_cvt_f32_i32_e32 v118, v118
	v_cvt_f32_i32_e32 v119, v119
	v_cvt_f32_i32_e32 v120, v120
	v_cvt_f32_i32_e32 v121, v121
	v_cvt_f32_i32_e32 v110, v110
	v_cvt_f32_i32_e32 v111, v111
	v_cvt_f32_i32_e32 v112, v112
	v_cvt_f32_i32_e32 v113, v113
	v_cvt_f32_i32_e32 v102, v102
	v_cvt_f32_i32_e32 v103, v103
	v_cvt_f32_i32_e32 v104, v104
	v_cvt_f32_i32_e32 v105, v105
	v_cvt_f32_i32_e32 v100, v100
	v_cvt_f32_i32_e32 v101, v101
	v_cvt_f32_i32_e32 v93, v93
	v_cvt_f32_i32_e32 v96, v96
	v_cvt_f32_i32_e32 v97, v97
	v_cvt_f32_i32_e32 v90, v90
	v_cvt_f32_i32_e32 v91, v91
	v_cvt_f32_i32_e32 v92, v92
	v_cvt_f32_i32_e32 v85, v85
	v_cvt_f32_i32_e32 v88, v88
	v_cvt_f32_i32_e32 v89, v89
	v_cvt_f32_i32_e32 v82, v82
	v_cvt_f32_i32_e32 v83, v83
	v_cvt_f32_i32_e32 v84, v84
	v_cvt_f32_i32_e32 v77, v77
	v_cvt_f32_i32_e32 v80, v80
	v_cvt_f32_i32_e32 v81, v81
	v_cvt_f32_i32_e32 v74, v74
	v_cvt_f32_i32_e32 v75, v75
	v_cvt_f32_i32_e32 v76, v76
	v_cvt_f32_i32_e32 v69, v69
	v_cvt_f32_i32_e32 v72, v72
	v_cvt_f32_i32_e32 v73, v73
	v_cvt_f32_i32_e32 v66, v66
	v_cvt_f32_i32_e32 v67, v67
	v_cvt_f32_i32_e32 v68, v68
	v_cvt_f32_i32_e32 v53, v53
	v_cvt_f32_i32_e32 v54, v54
	v_cvt_f32_i32_e32 v55, v55
	v_cvt_f32_i32_e32 v56, v56
	v_cvt_f32_i32_e32 v57, v57
	v_cvt_f32_i32_e32 v50, v50
	v_cvt_f32_i32_e32 v51, v51
	v_cvt_f32_i32_e32 v52, v52
	v_cvt_f32_i32_e32 v45, v45
	v_cvt_f32_i32_e32 v46, v46
	v_cvt_f32_i32_e32 v47, v47
	v_cvt_f32_i32_e32 v48, v48
	v_cvt_f32_i32_e32 v49, v49
	v_cvt_f32_i32_e32 v42, v42
	v_cvt_f32_i32_e32 v43, v43
	v_cvt_f32_i32_e32 v44, v44
	v_cvt_f32_i32_e32 v37, v37
	v_cvt_f32_i32_e32 v38, v38
	v_cvt_f32_i32_e32 v39, v39
	v_cvt_f32_i32_e32 v40, v40
	v_cvt_f32_i32_e32 v41, v41
	v_cvt_f32_i32_e32 v34, v34
	v_cvt_f32_i32_e32 v35, v35
	s_cmp_lg_u64 s[20:21], 0
	s_cbranch_scc0 .Lalb_2
	s_barrier
.Lalb_2:
	s_waitcnt vmcnt(0)
	v_pk_mul_f32 v[126:127], v[162:163], s[24:25] op_sel_hi:[1,0]
	v_pk_mul_f32 v[128:129], v[154:155], s[24:25] op_sel_hi:[1,0]
	v_pk_mul_f32 v[154:155], v[152:153], s[24:25] op_sel_hi:[1,0]
	v_pk_mul_f32 v[152:153], v[160:161], s[24:25] op_sel_hi:[1,0]
	v_mul_f32_e32 v160, v154, v170
	v_mul_f32_e32 v161, v155, v170
	v_mul_f32_e32 v162, v128, v170
	v_mul_f32_e32 v163, v129, v170
	v_mul_f32_e32 v167, v170, v152
	v_mul_f32_e32 v179, v170, v153
	v_mul_f32_e32 v180, v170, v126
	v_mul_f32_e32 v170, v170, v127
	v_mul_f32_e32 v160, v160, v171
	v_mul_f32_e32 v161, v161, v172
	v_mul_f32_e32 v162, v162, v173
	v_mul_f32_e32 v163, v163, v174
	v_mul_f32_e32 v167, v167, v175
	v_mul_f32_e32 v171, v179, v176
	v_mul_f32_e32 v172, v180, v177
	v_mul_f32_e32 v170, v170, v178
	v_cvt_pk_bf16_f32 v160, v160, v161
	v_cvt_pk_bf16_f32 v161, v162, v163
	v_cvt_pk_bf16_f32 v162, v167, v171
	v_cvt_pk_bf16_f32 v163, v172, v170
	global_store_dwordx4 v[122:123], v[160:163], off
	s_nop 1
	v_cvt_f32_i32_e32 v167, v115
	v_cvt_f32_i32_e32 v163, v114
	v_cvt_f32_i32_e32 v170, v116
	v_cvt_f32_i32_e32 v171, v117
	v_lshlrev_b64 v[116:117], 13, v[168:169]
	v_or_b32_e32 v160, 32, v166
	v_lshl_add_u64 v[116:117], s[30:31], 0, v[116:117]
	v_ashrrev_i32_e32 v161, 31, v160
	v_lshl_add_u64 v[116:117], v[116:117], 0, v[164:165]
	v_lshl_add_u64 v[114:115], v[160:161], 2, s[34:35]
	v_cvt_f32_i32_e32 v36, v36
	v_cvt_f32_i32_e32 v29, v29
	v_cvt_f32_i32_e32 v32, v32
	v_cvt_f32_i32_e32 v33, v33
	v_cvt_f32_i32_e32 v26, v26
	v_cvt_f32_i32_e32 v27, v27
	v_cvt_f32_i32_e32 v28, v28
	v_cvt_f32_i32_e32 v21, v21
	v_cvt_f32_i32_e32 v24, v24
	v_cvt_f32_i32_e32 v25, v25
	v_cvt_f32_i32_e32 v18, v18
	v_cvt_f32_i32_e32 v19, v19
	v_cvt_f32_i32_e32 v20, v20
	v_cvt_f32_i32_e32 v13, v13
	v_cvt_f32_i32_e32 v16, v16
	v_cvt_f32_i32_e32 v17, v17
	v_cvt_f32_i32_e32 v10, v10
	v_cvt_f32_i32_e32 v11, v11
	v_cvt_f32_i32_e32 v12, v12
	v_cvt_f32_i32_e32 v5, v5
	v_cvt_f32_i32_e32 v8, v8
	v_cvt_f32_i32_e32 v9, v9
	v_cvt_f32_i32_e32 v2, v2
	v_cvt_f32_i32_e32 v3, v3
	v_cvt_f32_i32_e32 v4, v4
	s_mov_b64 s[0:1], -1
	v_mov_b32_e32 v162, v192
	v_mul_f32_e32 v168, v154, v162
	v_mul_f32_e32 v169, v155, v162
	v_mul_f32_e32 v172, v128, v162
	v_mul_f32_e32 v173, v129, v162
	v_mul_f32_e32 v174, v152, v162
	v_mul_f32_e32 v175, v153, v162
	v_mul_f32_e32 v176, v126, v162
	v_mul_f32_e32 v162, v127, v162
	v_mul_f32_e32 v118, v168, v118
	v_mul_f32_e32 v119, v169, v119
	v_mul_f32_e32 v120, v172, v120
	v_mul_f32_e32 v121, v173, v121
	v_mul_f32_e32 v163, v174, v163
	v_mul_f32_e32 v167, v175, v167
	v_mul_f32_e32 v168, v176, v170
	v_mul_f32_e32 v162, v162, v171
	v_cvt_pk_bf16_f32 v118, v118, v119
	v_cvt_pk_bf16_f32 v119, v120, v121
	v_cvt_pk_bf16_f32 v120, v163, v167
	v_cvt_pk_bf16_f32 v121, v168, v162
	global_store_dwordx4 v[116:117], v[118:121], off
	s_nop 1
	v_cvt_f32_i32_e32 v162, v107
	v_cvt_f32_i32_e32 v121, v106
	v_cvt_f32_i32_e32 v163, v108
	v_cvt_f32_i32_e32 v167, v109
	v_lshlrev_b64 v[108:109], 13, v[160:161]
	v_or_b32_e32 v118, 48, v166
	v_lshl_add_u64 v[108:109], s[30:31], 0, v[108:109]
	v_ashrrev_i32_e32 v119, 31, v118
	v_lshl_add_u64 v[108:109], v[108:109], 0, v[164:165]
	v_lshl_add_u64 v[106:107], v[118:119], 2, s[34:35]
	v_mov_b32_e32 v120, v194
	v_mul_f32_e32 v160, v154, v120
	v_mul_f32_e32 v161, v155, v120
	v_mul_f32_e32 v166, v128, v120
	v_mul_f32_e32 v168, v129, v120
	v_mul_f32_e32 v169, v152, v120
	v_mul_f32_e32 v170, v153, v120
	v_mul_f32_e32 v171, v126, v120
	v_mul_f32_e32 v120, v127, v120
	v_mul_f32_e32 v110, v160, v110
	v_mul_f32_e32 v111, v161, v111
	v_mul_f32_e32 v112, v166, v112
	v_mul_f32_e32 v113, v168, v113
	v_mul_f32_e32 v121, v169, v121
	v_mul_f32_e32 v160, v170, v162
	v_mul_f32_e32 v161, v171, v163
	v_mul_f32_e32 v120, v120, v167
	v_cvt_pk_bf16_f32 v110, v110, v111
	v_cvt_pk_bf16_f32 v111, v112, v113
	v_cvt_pk_bf16_f32 v112, v121, v160
	v_cvt_pk_bf16_f32 v113, v161, v120
	global_store_dwordx4 v[108:109], v[110:113], off
	s_nop 1
	v_mov_b32_e32 v110, v196
	v_mul_f32_e32 v120, v129, v110
	v_cvt_f32_i32_e32 v111, v98
	v_cvt_f32_i32_e32 v112, v99
	v_lshlrev_b64 v[98:99], 13, v[118:119]
	v_lshl_add_u64 v[98:99], s[30:31], 0, v[98:99]
	v_mul_f32_e32 v113, v154, v110
	v_mul_f32_e32 v118, v155, v110
	v_lshl_add_u64 v[98:99], v[98:99], 0, v[164:165]
	v_mul_f32_e32 v119, v128, v110
	v_mul_f32_e32 v121, v152, v110
	v_mul_f32_e32 v160, v153, v110
	v_mul_f32_e32 v161, v126, v110
	v_mul_f32_e32 v110, v127, v110
	v_mul_f32_e32 v102, v113, v102
	v_mul_f32_e32 v103, v118, v103
	v_mul_f32_e32 v104, v119, v104
	v_mul_f32_e32 v105, v120, v105
	v_mul_f32_e32 v111, v121, v111
	v_mul_f32_e32 v112, v160, v112
	v_mul_f32_e32 v113, v161, v100
	v_mul_f32_e32 v110, v110, v101
	v_cvt_pk_bf16_f32 v100, v102, v103
	v_cvt_pk_bf16_f32 v101, v104, v105
	v_cvt_pk_bf16_f32 v102, v111, v112
	v_cvt_pk_bf16_f32 v103, v113, v110
	global_store_dwordx4 v[98:99], v[100:103], off
	s_nop 1
	v_mov_b32_e32 v100, v198
	v_mul_f32_e32 v104, v155, v100
	v_cvt_f32_i32_e32 v101, v94
	v_cvt_f32_i32_e32 v102, v95
	v_add_co_u32_e32 v94, vcc, s65, v122
	v_mul_f32_e32 v103, v154, v100
	v_mul_f32_e32 v105, v128, v100
	v_mul_f32_e32 v110, v129, v100
	v_mul_f32_e32 v111, v152, v100
	v_mul_f32_e32 v112, v153, v100
	v_mul_f32_e32 v113, v126, v100
	v_mul_f32_e32 v100, v127, v100
	v_addc_co_u32_e32 v95, vcc, 0, v123, vcc
	v_mul_f32_e32 v93, v100, v93
	v_mul_f32_e32 v101, v103, v101
	v_mul_f32_e32 v102, v104, v102
	v_mul_f32_e32 v96, v105, v96
	v_mul_f32_e32 v97, v110, v97
	v_mul_f32_e32 v103, v111, v90
	v_mul_f32_e32 v104, v112, v91
	v_mul_f32_e32 v105, v113, v92
	v_cvt_pk_bf16_f32 v90, v101, v102
	v_cvt_pk_bf16_f32 v91, v96, v97
	v_cvt_pk_bf16_f32 v92, v103, v104
	v_cvt_pk_bf16_f32 v93, v105, v93
	global_store_dwordx4 v[94:95], v[90:93], off
	s_nop 1
	v_mov_b32_e32 v90, v200
	v_mul_f32_e32 v94, v155, v90
	v_cvt_f32_i32_e32 v91, v86
	v_cvt_f32_i32_e32 v92, v87
	v_add_co_u32_e32 v86, vcc, s68, v122
	v_mul_f32_e32 v93, v154, v90
	v_mul_f32_e32 v95, v128, v90
	v_mul_f32_e32 v96, v129, v90
	v_mul_f32_e32 v97, v152, v90
	v_mul_f32_e32 v100, v153, v90
	v_mul_f32_e32 v101, v126, v90
	v_mul_f32_e32 v90, v127, v90
	v_addc_co_u32_e32 v87, vcc, 0, v123, vcc
	v_mul_f32_e32 v85, v90, v85
	v_mul_f32_e32 v91, v93, v91
	v_mul_f32_e32 v92, v94, v92
	v_mul_f32_e32 v88, v95, v88
	v_mul_f32_e32 v89, v96, v89
	v_mul_f32_e32 v93, v97, v82
	v_mul_f32_e32 v94, v100, v83
	v_mul_f32_e32 v95, v101, v84
	v_cvt_pk_bf16_f32 v82, v91, v92
	v_cvt_pk_bf16_f32 v83, v88, v89
	v_cvt_pk_bf16_f32 v84, v93, v94
	v_cvt_pk_bf16_f32 v85, v95, v85
	global_store_dwordx4 v[86:87], v[82:85], off
	s_nop 1
	v_mov_b32_e32 v82, v202
	v_mul_f32_e32 v86, v155, v82
	v_cvt_f32_i32_e32 v83, v78
	v_cvt_f32_i32_e32 v84, v79
	v_add_co_u32_e32 v78, vcc, s69, v122
	v_mul_f32_e32 v85, v154, v82
	v_mul_f32_e32 v87, v128, v82
	v_mul_f32_e32 v88, v129, v82
	v_mul_f32_e32 v89, v152, v82
	v_mul_f32_e32 v90, v153, v82
	v_mul_f32_e32 v91, v126, v82
	v_mul_f32_e32 v82, v127, v82
	v_addc_co_u32_e32 v79, vcc, 0, v123, vcc
	v_mul_f32_e32 v77, v82, v77
	v_mul_f32_e32 v83, v85, v83
	v_mul_f32_e32 v84, v86, v84
	v_mul_f32_e32 v80, v87, v80
	v_mul_f32_e32 v81, v88, v81
	v_mul_f32_e32 v85, v89, v74
	v_mul_f32_e32 v86, v90, v75
	v_mul_f32_e32 v87, v91, v76
	v_cvt_pk_bf16_f32 v74, v83, v84
	v_cvt_pk_bf16_f32 v75, v80, v81
	v_cvt_pk_bf16_f32 v76, v85, v86
	v_cvt_pk_bf16_f32 v77, v87, v77
	global_store_dwordx4 v[78:79], v[74:77], off
	s_nop 1
	v_mov_b32_e32 v74, v204
	v_mul_f32_e32 v78, v155, v74
	v_cvt_f32_i32_e32 v75, v70
	v_cvt_f32_i32_e32 v76, v71
	v_add_co_u32_e32 v70, vcc, s70, v122
	v_mul_f32_e32 v77, v154, v74
	v_mul_f32_e32 v79, v128, v74
	v_mul_f32_e32 v80, v129, v74
	v_mul_f32_e32 v81, v152, v74
	v_mul_f32_e32 v82, v153, v74
	v_mul_f32_e32 v83, v126, v74
	v_mul_f32_e32 v74, v127, v74
	v_addc_co_u32_e32 v71, vcc, 0, v123, vcc
	v_mul_f32_e32 v69, v74, v69
	v_mul_f32_e32 v75, v77, v75
	v_mul_f32_e32 v76, v78, v76
	v_mul_f32_e32 v72, v79, v72
	v_mul_f32_e32 v73, v80, v73
	v_mul_f32_e32 v77, v81, v66
	v_mul_f32_e32 v78, v82, v67
	v_mul_f32_e32 v79, v83, v68
	v_cvt_pk_bf16_f32 v66, v75, v76
	v_cvt_pk_bf16_f32 v67, v72, v73
	v_cvt_pk_bf16_f32 v68, v77, v78
	v_cvt_pk_bf16_f32 v69, v79, v69
	global_store_dwordx4 v[70:71], v[66:69], off
	s_nop 1
	s_nop 1
	v_cvt_f32_i32_e32 v75, v62
	v_cvt_f32_i32_e32 v76, v63
	v_cvt_f32_i32_e32 v77, v64
	v_cvt_f32_i32_e32 v78, v65
	v_cvt_f32_i32_e32 v79, v58
	v_cvt_f32_i32_e32 v80, v59
	v_cvt_f32_i32_e32 v81, v60
	v_cvt_f32_i32_e32 v82, v61
	s_and_b64 vcc, exec, s[4:5]
	v_pk_mul_f32 v[60:61], v[208:209], s[24:25] op_sel_hi:[1,0]
	v_pk_mul_f32 v[64:65], v[206:207], s[24:25] op_sel_hi:[1,0]
	v_pk_mul_f32 v[58:59], v[212:213], s[24:25] op_sel_hi:[1,0]
	v_pk_mul_f32 v[62:63], v[210:211], s[24:25] op_sel_hi:[1,0]
	v_mov_b32_e32 v74, v190
	v_mul_f32_e32 v66, v64, v74
	v_mul_f32_e32 v67, v65, v74
	v_mul_f32_e32 v68, v60, v74
	v_mul_f32_e32 v69, v61, v74
	v_mul_f32_e32 v70, v74, v62
	v_mul_f32_e32 v71, v74, v63
	v_mul_f32_e32 v72, v74, v58
	v_mul_f32_e32 v73, v74, v59
	v_mul_f32_e32 v66, v66, v75
	v_mul_f32_e32 v67, v67, v76
	v_mul_f32_e32 v68, v68, v77
	v_mul_f32_e32 v69, v69, v78
	v_mul_f32_e32 v70, v70, v79
	v_mul_f32_e32 v71, v71, v80
	v_mul_f32_e32 v72, v72, v81
	v_mul_f32_e32 v73, v73, v82
	v_cvt_pk_bf16_f32 v66, v66, v67
	v_cvt_pk_bf16_f32 v67, v68, v69
	v_cvt_pk_bf16_f32 v68, v70, v71
	v_cvt_pk_bf16_f32 v69, v72, v73
	global_store_dwordx4 v[122:123], v[66:69], off offset:256
	s_nop 1
	v_mov_b32_e32 v66, v192
	v_mul_f32_e32 v70, v61, v66
	v_mul_f32_e32 v67, v64, v66
	v_mul_f32_e32 v68, v65, v66
	v_mul_f32_e32 v69, v60, v66
	v_mul_f32_e32 v71, v62, v66
	v_mul_f32_e32 v72, v63, v66
	v_mul_f32_e32 v73, v58, v66
	v_mul_f32_e32 v66, v59, v66
	v_mul_f32_e32 v53, v66, v53
	v_mul_f32_e32 v54, v67, v54
	v_mul_f32_e32 v55, v68, v55
	v_mul_f32_e32 v56, v69, v56
	v_mul_f32_e32 v57, v70, v57
	v_mul_f32_e32 v67, v71, v50
	v_mul_f32_e32 v68, v72, v51
	v_mul_f32_e32 v69, v73, v52
	v_cvt_pk_bf16_f32 v50, v54, v55
	v_cvt_pk_bf16_f32 v51, v56, v57
	v_cvt_pk_bf16_f32 v52, v67, v68
	v_cvt_pk_bf16_f32 v53, v69, v53
	global_store_dwordx4 v[116:117], v[50:53], off offset:256
	s_nop 1
	v_mov_b32_e32 v50, v194
	v_mul_f32_e32 v54, v61, v50
	v_mul_f32_e32 v51, v64, v50
	v_mul_f32_e32 v52, v65, v50
	v_mul_f32_e32 v53, v60, v50
	v_mul_f32_e32 v55, v62, v50
	v_mul_f32_e32 v56, v63, v50
	v_mul_f32_e32 v57, v58, v50
	v_mul_f32_e32 v50, v59, v50
	v_mul_f32_e32 v45, v50, v45
	v_mul_f32_e32 v46, v51, v46
	v_mul_f32_e32 v47, v52, v47
	v_mul_f32_e32 v48, v53, v48
	v_mul_f32_e32 v49, v54, v49
	v_mul_f32_e32 v51, v55, v42
	v_mul_f32_e32 v52, v56, v43
	v_mul_f32_e32 v53, v57, v44
	v_cvt_pk_bf16_f32 v42, v46, v47
	v_cvt_pk_bf16_f32 v43, v48, v49
	v_cvt_pk_bf16_f32 v44, v51, v52
	v_cvt_pk_bf16_f32 v45, v53, v45
	global_store_dwordx4 v[108:109], v[42:45], off offset:256
	s_nop 1
	v_mov_b32_e32 v42, v196
	v_mul_f32_e32 v46, v61, v42
	v_mul_f32_e32 v43, v64, v42
	v_mul_f32_e32 v44, v65, v42
	v_mul_f32_e32 v45, v60, v42
	v_mul_f32_e32 v47, v62, v42
	v_mul_f32_e32 v48, v63, v42
	v_mul_f32_e32 v49, v58, v42
	v_mul_f32_e32 v42, v59, v42
	v_mul_f32_e32 v37, v42, v37
	v_mul_f32_e32 v38, v43, v38
	v_mul_f32_e32 v39, v44, v39
	v_mul_f32_e32 v40, v45, v40
	v_mul_f32_e32 v41, v46, v41
	v_mul_f32_e32 v43, v47, v34
	v_mul_f32_e32 v44, v48, v35
	v_mul_f32_e32 v45, v49, v36
	v_cvt_pk_bf16_f32 v34, v38, v39
	v_cvt_pk_bf16_f32 v35, v40, v41
	v_cvt_pk_bf16_f32 v36, v43, v44
	v_cvt_pk_bf16_f32 v37, v45, v37
	global_store_dwordx4 v[98:99], v[34:37], off offset:256
	s_nop 1
	v_mov_b32_e32 v34, v198
	v_mul_f32_e32 v38, v65, v34
	v_cvt_f32_i32_e32 v35, v30
	v_cvt_f32_i32_e32 v36, v31
	v_mul_f32_e32 v37, v64, v34
	v_mul_f32_e32 v39, v60, v34
	v_mul_f32_e32 v40, v61, v34
	v_mul_f32_e32 v41, v62, v34
	v_mul_f32_e32 v42, v63, v34
	v_mul_f32_e32 v43, v58, v34
	v_mul_f32_e32 v34, v59, v34
	v_lshl_add_u64 v[30:31], v[122:123], 0, s[38:39]
	v_mul_f32_e32 v29, v34, v29
	v_mul_f32_e32 v35, v37, v35
	v_mul_f32_e32 v36, v38, v36
	v_mul_f32_e32 v32, v39, v32
	v_mul_f32_e32 v33, v40, v33
	v_mul_f32_e32 v37, v41, v26
	v_mul_f32_e32 v38, v42, v27
	v_mul_f32_e32 v39, v43, v28
	v_cvt_pk_bf16_f32 v26, v35, v36
	v_cvt_pk_bf16_f32 v27, v32, v33
	v_cvt_pk_bf16_f32 v28, v37, v38
	v_cvt_pk_bf16_f32 v29, v39, v29
	global_store_dwordx4 v[30:31], v[26:29], off offset:256
	s_nop 1
	v_mov_b32_e32 v26, v200
	v_mul_f32_e32 v30, v65, v26
	v_cvt_f32_i32_e32 v27, v22
	v_cvt_f32_i32_e32 v28, v23
	v_mul_f32_e32 v29, v64, v26
	v_mul_f32_e32 v31, v60, v26
	v_mul_f32_e32 v32, v61, v26
	v_mul_f32_e32 v33, v62, v26
	v_mul_f32_e32 v34, v63, v26
	v_mul_f32_e32 v35, v58, v26
	v_mul_f32_e32 v26, v59, v26
	v_lshl_add_u64 v[22:23], v[122:123], 0, s[40:41]
	v_mul_f32_e32 v21, v26, v21
	v_mul_f32_e32 v27, v29, v27
	v_mul_f32_e32 v28, v30, v28
	v_mul_f32_e32 v24, v31, v24
	v_mul_f32_e32 v25, v32, v25
	v_mul_f32_e32 v29, v33, v18
	v_mul_f32_e32 v30, v34, v19
	v_mul_f32_e32 v31, v35, v20
	v_cvt_pk_bf16_f32 v18, v27, v28
	v_cvt_pk_bf16_f32 v19, v24, v25
	v_cvt_pk_bf16_f32 v20, v29, v30
	v_cvt_pk_bf16_f32 v21, v31, v21
	global_store_dwordx4 v[22:23], v[18:21], off offset:256
	s_nop 1
	v_mov_b32_e32 v18, v202
	v_mul_f32_e32 v22, v65, v18
	v_cvt_f32_i32_e32 v19, v14
	v_cvt_f32_i32_e32 v20, v15
	v_mul_f32_e32 v21, v64, v18
	v_mul_f32_e32 v23, v60, v18
	v_mul_f32_e32 v24, v61, v18
	v_mul_f32_e32 v25, v62, v18
	v_mul_f32_e32 v26, v63, v18
	v_mul_f32_e32 v27, v58, v18
	v_mul_f32_e32 v18, v59, v18
	v_lshl_add_u64 v[14:15], v[122:123], 0, s[42:43]
	v_mul_f32_e32 v13, v18, v13
	v_mul_f32_e32 v19, v21, v19
	v_mul_f32_e32 v20, v22, v20
	v_mul_f32_e32 v16, v23, v16
	v_mul_f32_e32 v17, v24, v17
	v_mul_f32_e32 v21, v25, v10
	v_mul_f32_e32 v22, v26, v11
	v_mul_f32_e32 v23, v27, v12
	v_cvt_pk_bf16_f32 v10, v19, v20
	v_cvt_pk_bf16_f32 v11, v16, v17
	v_cvt_pk_bf16_f32 v12, v21, v22
	v_cvt_pk_bf16_f32 v13, v23, v13
	global_store_dwordx4 v[14:15], v[10:13], off offset:256
	s_nop 1
	v_mov_b32_e32 v10, v204
	v_mul_f32_e32 v14, v65, v10
	v_cvt_f32_i32_e32 v11, v6
	v_cvt_f32_i32_e32 v12, v7
	v_mul_f32_e32 v13, v64, v10
	v_mul_f32_e32 v15, v60, v10
	v_mul_f32_e32 v16, v61, v10
	v_mul_f32_e32 v17, v62, v10
	v_mul_f32_e32 v18, v63, v10
	v_mul_f32_e32 v19, v58, v10
	v_mul_f32_e32 v10, v59, v10
	v_lshl_add_u64 v[6:7], v[122:123], 0, s[44:45]
	v_mul_f32_e32 v5, v10, v5
	v_mul_f32_e32 v11, v13, v11
	v_mul_f32_e32 v12, v14, v12
	v_mul_f32_e32 v8, v15, v8
	v_mul_f32_e32 v9, v16, v9
	v_mul_f32_e32 v13, v17, v2
	v_mul_f32_e32 v14, v18, v3
	v_mul_f32_e32 v15, v19, v4
	v_cvt_pk_bf16_f32 v2, v11, v12
	v_cvt_pk_bf16_f32 v3, v8, v9
	v_cvt_pk_bf16_f32 v4, v13, v14
	v_cvt_pk_bf16_f32 v5, v15, v5
	global_store_dwordx4 v[6:7], v[2:5], off offset:256
	s_cbranch_vccnz .LBB0_399
	s_andn2_b64 vcc, exec, s[8:9]
	s_cbranch_vccnz .LBB0_398
	s_barrier
	s_branch .LBB0_398

.LBB0_561:
	v_lshl_or_b32 v156, s65, 8, v162
	v_ashrrev_i32_e32 v157, 31, v156
	v_lshl_add_u32 v152, s46, 8, v1
	v_lshl_add_u64 v[150:151], v[156:157], 2, s[18:19]
	v_ashrrev_i32_e32 v153, 31, v152
	global_load_dwordx4 v[166:169], v[150:151], off offset:16
	global_load_dwordx4 v[158:161], v[150:151], off
	v_lshl_add_u64 v[148:149], v[152:153], 2, s[26:27]
	global_load_dword v153, v[148:149], off
	global_load_dword v190, v[148:149], off
	global_load_dword v192, v[148:149], off offset:64
	global_load_dword v194, v[148:149], off offset:128
	global_load_dword v196, v[148:149], off offset:192
	global_load_dword v198, v[148:149], off offset:512
	global_load_dword v200, v[148:149], off offset:576
	global_load_dword v202, v[148:149], off offset:640
	global_load_dword v204, v[148:149], off offset:704
	global_load_dwordx4 v[206:209], v[150:151], off offset:512
	global_load_dwordx4 v[210:213], v[150:151], off offset:528
	v_cvt_f32_i32_e32 v172, v126
	v_cvt_f32_i32_e32 v173, v127
	v_cvt_f32_i32_e32 v174, v128
	v_cvt_f32_i32_e32 v175, v129
	v_cvt_f32_i32_e32 v176, v122
	v_cvt_f32_i32_e32 v177, v123
	v_cvt_f32_i32_e32 v178, v124
	v_cvt_f32_i32_e32 v179, v125
	v_mov_b64_e32 v[154:155], s[36:37]
	v_or_b32_e32 v170, 16, v152
	v_lshlrev_b64 v[128:129], 1, v[156:157]
	v_mad_i64_i32 v[122:123], s[0:1], v152, s64, v[154:155]
	v_ashrrev_i32_e32 v171, 31, v170
	v_lshl_add_u64 v[122:123], v[122:123], 0, v[128:129]
	v_lshl_add_u64 v[124:125], v[170:171], 2, s[26:27]
	v_cvt_f32_i32_e32 v118, v118
	v_cvt_f32_i32_e32 v119, v119
	v_cvt_f32_i32_e32 v120, v120
	v_cvt_f32_i32_e32 v121, v121
	v_cvt_f32_i32_e32 v110, v110
	v_cvt_f32_i32_e32 v111, v111
	v_cvt_f32_i32_e32 v112, v112
	v_cvt_f32_i32_e32 v113, v113
	v_cvt_f32_i32_e32 v102, v102
	v_cvt_f32_i32_e32 v103, v103
	v_cvt_f32_i32_e32 v104, v104
	v_cvt_f32_i32_e32 v105, v105
	v_cvt_f32_i32_e32 v100, v100
	v_cvt_f32_i32_e32 v101, v101
	v_cvt_f32_i32_e32 v94, v94
	v_cvt_f32_i32_e32 v95, v95
	v_cvt_f32_i32_e32 v96, v96
	v_cvt_f32_i32_e32 v97, v97
	v_cvt_f32_i32_e32 v92, v92
	v_cvt_f32_i32_e32 v93, v93
	v_cvt_f32_i32_e32 v86, v86
	v_cvt_f32_i32_e32 v87, v87
	v_cvt_f32_i32_e32 v88, v88
	v_cvt_f32_i32_e32 v89, v89
	v_cvt_f32_i32_e32 v84, v84
	v_cvt_f32_i32_e32 v85, v85
	v_cvt_f32_i32_e32 v78, v78
	v_cvt_f32_i32_e32 v79, v79
	v_cvt_f32_i32_e32 v80, v80
	v_cvt_f32_i32_e32 v81, v81
	v_cvt_f32_i32_e32 v76, v76
	v_cvt_f32_i32_e32 v77, v77
	v_cvt_f32_i32_e32 v70, v70
	v_cvt_f32_i32_e32 v71, v71
	v_cvt_f32_i32_e32 v72, v72
	v_cvt_f32_i32_e32 v73, v73
	v_cvt_f32_i32_e32 v64, v64
	v_cvt_f32_i32_e32 v65, v65
	v_cvt_f32_i32_e32 v69, v69
	v_cvt_f32_i32_e32 v68, v68
	v_cvt_f32_i32_e32 v53, v53
	v_cvt_f32_i32_e32 v54, v54
	v_cvt_f32_i32_e32 v55, v55
	v_cvt_f32_i32_e32 v56, v56
	v_cvt_f32_i32_e32 v57, v57
	v_cvt_f32_i32_e32 v50, v50
	v_cvt_f32_i32_e32 v51, v51
	v_cvt_f32_i32_e32 v52, v52
	v_cvt_f32_i32_e32 v45, v45
	v_cvt_f32_i32_e32 v46, v46
	v_cvt_f32_i32_e32 v47, v47
	v_cvt_f32_i32_e32 v48, v48
	v_cvt_f32_i32_e32 v49, v49
	v_cvt_f32_i32_e32 v42, v42
	v_cvt_f32_i32_e32 v43, v43
	v_cvt_f32_i32_e32 v44, v44
	v_cvt_f32_i32_e32 v37, v37
	v_cvt_f32_i32_e32 v38, v38
	v_cvt_f32_i32_e32 v39, v39
	v_cvt_f32_i32_e32 v40, v40
	s_cmp_lg_u64 s[24:25], 0
	s_cbranch_scc0 .Lalb_3
	s_barrier
.Lalb_3:
	s_waitcnt vmcnt(0)
	v_pk_mul_f32 v[126:127], v[168:169], s[38:39] op_sel_hi:[1,0]
	v_pk_mul_f32 v[156:157], v[160:161], s[38:39] op_sel_hi:[1,0]
	v_pk_mul_f32 v[160:161], v[158:159], s[38:39] op_sel_hi:[1,0]
	v_pk_mul_f32 v[158:159], v[166:167], s[38:39] op_sel_hi:[1,0]
	v_mul_f32_e32 v166, v160, v153
	v_mul_f32_e32 v167, v161, v153
	v_mul_f32_e32 v168, v156, v153
	v_mul_f32_e32 v169, v157, v153
	v_mul_f32_e32 v171, v153, v158
	v_mul_f32_e32 v180, v153, v159
	v_mul_f32_e32 v181, v153, v126
	v_mul_f32_e32 v153, v153, v127
	v_mul_f32_e32 v166, v166, v172
	v_mul_f32_e32 v167, v167, v173
	v_mul_f32_e32 v168, v168, v174
	v_mul_f32_e32 v169, v169, v175
	v_mul_f32_e32 v171, v171, v176
	v_mul_f32_e32 v172, v180, v177
	v_mul_f32_e32 v173, v181, v178
	v_mul_f32_e32 v153, v153, v179
	v_cvt_pk_bf16_f32 v166, v166, v167
	v_cvt_pk_bf16_f32 v167, v168, v169
	v_cvt_pk_bf16_f32 v168, v171, v172
	v_cvt_pk_bf16_f32 v169, v173, v153
	global_store_dwordx4 v[122:123], v[166:169], off
	s_nop 1
	v_cvt_f32_i32_e32 v171, v116
	v_cvt_f32_i32_e32 v168, v114
	v_cvt_f32_i32_e32 v169, v115
	v_cvt_f32_i32_e32 v172, v117
	v_or_b32_e32 v166, 32, v152
	v_ashrrev_i32_e32 v167, 31, v166
	v_mad_i64_i32 v[114:115], s[0:1], v170, s64, v[154:155]
	v_lshl_add_u64 v[116:117], v[166:167], 2, s[26:27]
	v_lshl_add_u64 v[114:115], v[114:115], 0, v[128:129]
	v_cvt_f32_i32_e32 v41, v41
	v_cvt_f32_i32_e32 v34, v34
	v_cvt_f32_i32_e32 v35, v35
	v_cvt_f32_i32_e32 v36, v36
	v_cvt_f32_i32_e32 v29, v29
	v_cvt_f32_i32_e32 v30, v30
	v_cvt_f32_i32_e32 v31, v31
	v_cvt_f32_i32_e32 v32, v32
	v_cvt_f32_i32_e32 v33, v33
	v_cvt_f32_i32_e32 v26, v26
	v_cvt_f32_i32_e32 v27, v27
	v_cvt_f32_i32_e32 v28, v28
	v_cvt_f32_i32_e32 v21, v21
	v_cvt_f32_i32_e32 v22, v22
	v_cvt_f32_i32_e32 v23, v23
	v_cvt_f32_i32_e32 v24, v24
	v_cvt_f32_i32_e32 v25, v25
	v_cvt_f32_i32_e32 v18, v18
	v_cvt_f32_i32_e32 v19, v19
	v_cvt_f32_i32_e32 v20, v20
	v_cvt_f32_i32_e32 v13, v13
	v_cvt_f32_i32_e32 v14, v14
	v_cvt_f32_i32_e32 v15, v15
	v_cvt_f32_i32_e32 v16, v16
	v_cvt_f32_i32_e32 v17, v17
	v_cvt_f32_i32_e32 v10, v10
	v_cvt_f32_i32_e32 v11, v11
	v_cvt_f32_i32_e32 v12, v12
	v_cvt_f32_i32_e32 v5, v5
	v_cvt_f32_i32_e32 v6, v6
	v_cvt_f32_i32_e32 v7, v7
	v_cvt_f32_i32_e32 v8, v8
	v_cvt_f32_i32_e32 v9, v9
	v_cvt_f32_i32_e32 v2, v2
	v_cvt_f32_i32_e32 v3, v3
	v_cvt_f32_i32_e32 v4, v4
	s_and_b64 vcc, exec, s[4:5]
	v_mov_b32_e32 v153, v192
	v_mul_f32_e32 v167, v160, v153
	v_mul_f32_e32 v170, v161, v153
	v_mul_f32_e32 v173, v156, v153
	v_mul_f32_e32 v174, v157, v153
	v_mul_f32_e32 v175, v158, v153
	v_mul_f32_e32 v176, v159, v153
	v_mul_f32_e32 v177, v126, v153
	v_mul_f32_e32 v153, v127, v153
	v_mul_f32_e32 v118, v167, v118
	v_mul_f32_e32 v119, v170, v119
	v_mul_f32_e32 v120, v173, v120
	v_mul_f32_e32 v121, v174, v121
	v_mul_f32_e32 v167, v175, v168
	v_mul_f32_e32 v168, v176, v169
	v_mul_f32_e32 v169, v177, v171
	v_mul_f32_e32 v153, v153, v172
	v_cvt_pk_bf16_f32 v118, v118, v119
	v_cvt_pk_bf16_f32 v119, v120, v121
	v_cvt_pk_bf16_f32 v120, v167, v168
	v_cvt_pk_bf16_f32 v121, v169, v153
	global_store_dwordx4 v[114:115], v[118:121], off
	s_nop 1
	v_cvt_f32_i32_e32 v153, v107
	v_cvt_f32_i32_e32 v121, v106
	v_cvt_f32_i32_e32 v167, v108
	v_cvt_f32_i32_e32 v168, v109
	v_or_b32_e32 v118, 48, v152
	v_ashrrev_i32_e32 v119, 31, v118
	v_mad_i64_i32 v[106:107], s[0:1], v166, s64, v[154:155]
	v_lshl_add_u64 v[108:109], v[118:119], 2, s[26:27]
	v_lshl_add_u64 v[106:107], v[106:107], 0, v[128:129]
	v_mov_b32_e32 v120, v194
	v_mul_f32_e32 v119, v160, v120
	v_mul_f32_e32 v166, v161, v120
	v_mul_f32_e32 v169, v156, v120
	v_mul_f32_e32 v170, v157, v120
	v_mul_f32_e32 v171, v158, v120
	v_mul_f32_e32 v172, v159, v120
	v_mul_f32_e32 v173, v126, v120
	v_mul_f32_e32 v120, v127, v120
	v_mul_f32_e32 v110, v119, v110
	v_mul_f32_e32 v111, v166, v111
	v_mul_f32_e32 v112, v169, v112
	v_mul_f32_e32 v113, v170, v113
	v_mul_f32_e32 v119, v171, v121
	v_mul_f32_e32 v121, v172, v153
	v_mul_f32_e32 v153, v173, v167
	v_mul_f32_e32 v120, v120, v168
	v_cvt_pk_bf16_f32 v110, v110, v111
	v_cvt_pk_bf16_f32 v111, v112, v113
	v_cvt_pk_bf16_f32 v112, v119, v121
	v_cvt_pk_bf16_f32 v113, v153, v120
	global_store_dwordx4 v[106:107], v[110:113], off
	s_nop 1
	v_mov_b32_e32 v110, v196
	v_mul_f32_e32 v119, v156, v110
	v_cvt_f32_i32_e32 v111, v98
	v_cvt_f32_i32_e32 v112, v99
	v_mad_i64_i32 v[98:99], s[0:1], v118, s64, v[154:155]
	v_mul_f32_e32 v113, v160, v110
	v_mul_f32_e32 v118, v161, v110
	v_lshl_add_u64 v[98:99], v[98:99], 0, v[128:129]
	v_mul_f32_e32 v120, v157, v110
	v_mul_f32_e32 v121, v158, v110
	v_mul_f32_e32 v153, v159, v110
	v_mul_f32_e32 v166, v126, v110
	v_mul_f32_e32 v110, v127, v110
	v_mul_f32_e32 v102, v113, v102
	v_mul_f32_e32 v103, v118, v103
	v_mul_f32_e32 v104, v119, v104
	v_mul_f32_e32 v105, v120, v105
	v_mul_f32_e32 v111, v121, v111
	v_mul_f32_e32 v112, v153, v112
	v_mul_f32_e32 v113, v166, v100
	v_mul_f32_e32 v110, v110, v101
	v_cvt_pk_bf16_f32 v100, v102, v103
	v_cvt_pk_bf16_f32 v101, v104, v105
	v_cvt_pk_bf16_f32 v102, v111, v112
	v_cvt_pk_bf16_f32 v103, v113, v110
	global_store_dwordx4 v[98:99], v[100:103], off
	s_nop 1
	v_mov_b32_e32 v100, v198
	v_mul_f32_e32 v104, v161, v100
	v_cvt_f32_i32_e32 v101, v90
	v_cvt_f32_i32_e32 v102, v91
	v_add_u32_e32 v90, 0x80, v152
	v_mad_i64_i32 v[90:91], s[0:1], v90, s64, v[154:155]
	v_mul_f32_e32 v103, v160, v100
	v_lshl_add_u64 v[90:91], v[90:91], 0, v[128:129]
	v_mul_f32_e32 v105, v156, v100
	v_mul_f32_e32 v110, v157, v100
	v_mul_f32_e32 v111, v158, v100
	v_mul_f32_e32 v112, v159, v100
	v_mul_f32_e32 v113, v126, v100
	v_mul_f32_e32 v100, v127, v100
	v_mul_f32_e32 v94, v103, v94
	v_mul_f32_e32 v95, v104, v95
	v_mul_f32_e32 v96, v105, v96
	v_mul_f32_e32 v97, v110, v97
	v_mul_f32_e32 v101, v111, v101
	v_mul_f32_e32 v102, v112, v102
	v_mul_f32_e32 v103, v113, v92
	v_mul_f32_e32 v100, v100, v93
	v_cvt_pk_bf16_f32 v92, v94, v95
	v_cvt_pk_bf16_f32 v93, v96, v97
	v_cvt_pk_bf16_f32 v94, v101, v102
	v_cvt_pk_bf16_f32 v95, v103, v100
	global_store_dwordx4 v[90:91], v[92:95], off
	s_nop 1
	v_mov_b32_e32 v92, v200
	v_mul_f32_e32 v96, v161, v92
	v_cvt_f32_i32_e32 v93, v82
	v_cvt_f32_i32_e32 v94, v83
	v_add_u32_e32 v82, 0x90, v152
	v_mad_i64_i32 v[82:83], s[0:1], v82, s64, v[154:155]
	v_mul_f32_e32 v95, v160, v92
	v_lshl_add_u64 v[82:83], v[82:83], 0, v[128:129]
	v_mul_f32_e32 v97, v156, v92
	v_mul_f32_e32 v100, v157, v92
	v_mul_f32_e32 v101, v158, v92
	v_mul_f32_e32 v102, v159, v92
	v_mul_f32_e32 v103, v126, v92
	v_mul_f32_e32 v92, v127, v92
	v_mul_f32_e32 v86, v95, v86
	v_mul_f32_e32 v87, v96, v87
	v_mul_f32_e32 v88, v97, v88
	v_mul_f32_e32 v89, v100, v89
	v_mul_f32_e32 v93, v101, v93
	v_mul_f32_e32 v94, v102, v94
	v_mul_f32_e32 v95, v103, v84
	v_mul_f32_e32 v92, v92, v85
	v_cvt_pk_bf16_f32 v84, v86, v87
	v_cvt_pk_bf16_f32 v85, v88, v89
	v_cvt_pk_bf16_f32 v86, v93, v94
	v_cvt_pk_bf16_f32 v87, v95, v92
	global_store_dwordx4 v[82:83], v[84:87], off
	s_nop 1
	v_mov_b32_e32 v84, v202
	v_mul_f32_e32 v88, v161, v84
	v_cvt_f32_i32_e32 v85, v74
	v_cvt_f32_i32_e32 v86, v75
	v_add_u32_e32 v74, 0xa0, v152
	v_mad_i64_i32 v[74:75], s[0:1], v74, s64, v[154:155]
	v_mul_f32_e32 v87, v160, v84
	v_lshl_add_u64 v[74:75], v[74:75], 0, v[128:129]
	v_mul_f32_e32 v89, v156, v84
	v_mul_f32_e32 v92, v157, v84
	v_mul_f32_e32 v93, v158, v84
	v_mul_f32_e32 v94, v159, v84
	v_mul_f32_e32 v95, v126, v84
	v_mul_f32_e32 v84, v127, v84
	v_mul_f32_e32 v78, v87, v78
	v_mul_f32_e32 v79, v88, v79
	v_mul_f32_e32 v80, v89, v80
	v_mul_f32_e32 v81, v92, v81
	v_mul_f32_e32 v85, v93, v85
	v_mul_f32_e32 v86, v94, v86
	v_mul_f32_e32 v87, v95, v76
	v_mul_f32_e32 v84, v84, v77
	v_cvt_pk_bf16_f32 v76, v78, v79
	v_cvt_pk_bf16_f32 v77, v80, v81
	v_cvt_pk_bf16_f32 v78, v85, v86
	v_cvt_pk_bf16_f32 v79, v87, v84
	global_store_dwordx4 v[74:75], v[76:79], off
	s_nop 1
	v_cvt_f32_i32_e32 v88, v61
	v_cvt_f32_i32_e32 v77, v62
	v_cvt_f32_i32_e32 v78, v63
	v_add_u32_e32 v62, 0xb0, v152
	v_mad_i64_i32 v[62:63], s[0:1], v62, s64, v[154:155]
	v_lshl_add_u64 v[62:63], v[62:63], 0, v[128:129]
	s_mov_b64 s[0:1], -1
	v_mov_b32_e32 v76, v204
	v_mul_f32_e32 v79, v160, v76
	v_mul_f32_e32 v80, v161, v76
	v_mul_f32_e32 v81, v156, v76
	v_mul_f32_e32 v84, v157, v76
	v_mul_f32_e32 v85, v158, v76
	v_mul_f32_e32 v86, v159, v76
	v_mul_f32_e32 v87, v126, v76
	v_mul_f32_e32 v76, v127, v76
	v_mul_f32_e32 v70, v79, v70
	v_mul_f32_e32 v71, v80, v71
	v_mul_f32_e32 v72, v81, v72
	v_mul_f32_e32 v73, v84, v73
	v_mul_f32_e32 v77, v85, v77
	v_mul_f32_e32 v78, v86, v78
	v_mul_f32_e32 v64, v87, v64
	v_mul_f32_e32 v65, v76, v65
	v_cvt_pk_bf16_f32 v70, v70, v71
	v_cvt_pk_bf16_f32 v71, v72, v73
	v_cvt_pk_bf16_f32 v72, v77, v78
	v_cvt_pk_bf16_f32 v73, v64, v65
	global_store_dwordx4 v[62:63], v[70:73], off
	s_nop 1
	s_nop 1
	v_cvt_f32_i32_e32 v81, v66
	v_cvt_f32_i32_e32 v84, v67
	v_cvt_f32_i32_e32 v85, v58
	v_cvt_f32_i32_e32 v86, v59
	v_cvt_f32_i32_e32 v87, v60
	v_pk_mul_f32 v[60:61], v[208:209], s[38:39] op_sel_hi:[1,0]
	v_pk_mul_f32 v[66:67], v[206:207], s[38:39] op_sel_hi:[1,0]
	v_pk_mul_f32 v[58:59], v[212:213], s[38:39] op_sel_hi:[1,0]
	v_pk_mul_f32 v[64:65], v[210:211], s[38:39] op_sel_hi:[1,0]
	v_mov_b32_e32 v80, v190
	v_mul_f32_e32 v70, v66, v80
	v_mul_f32_e32 v71, v67, v80
	v_mul_f32_e32 v73, v61, v80
	v_mul_f32_e32 v72, v60, v80
	v_mul_f32_e32 v76, v80, v64
	v_mul_f32_e32 v77, v80, v65
	v_mul_f32_e32 v78, v80, v58
	v_mul_f32_e32 v79, v80, v59
	v_mul_f32_e32 v70, v70, v81
	v_mul_f32_e32 v71, v71, v84
	v_mul_f32_e32 v69, v73, v69
	v_mul_f32_e32 v72, v72, v68
	v_mul_f32_e32 v73, v76, v85
	v_mul_f32_e32 v76, v77, v86
	v_mul_f32_e32 v77, v78, v87
	v_mul_f32_e32 v78, v79, v88
	v_cvt_pk_bf16_f32 v68, v70, v71
	v_cvt_pk_bf16_f32 v69, v72, v69
	v_cvt_pk_bf16_f32 v70, v73, v76
	v_cvt_pk_bf16_f32 v71, v77, v78
	global_store_dwordx4 v[122:123], v[68:71], off offset:256
	s_nop 1
	v_mov_b32_e32 v68, v192
	v_mul_f32_e32 v72, v61, v68
	v_mul_f32_e32 v69, v66, v68
	v_mul_f32_e32 v70, v67, v68
	v_mul_f32_e32 v71, v60, v68
	v_mul_f32_e32 v73, v64, v68
	v_mul_f32_e32 v76, v65, v68
	v_mul_f32_e32 v77, v58, v68
	v_mul_f32_e32 v68, v59, v68
	v_mul_f32_e32 v53, v68, v53
	v_mul_f32_e32 v54, v69, v54
	v_mul_f32_e32 v55, v70, v55
	v_mul_f32_e32 v56, v71, v56
	v_mul_f32_e32 v57, v72, v57
	v_mul_f32_e32 v69, v73, v50
	v_mul_f32_e32 v70, v76, v51
	v_mul_f32_e32 v71, v77, v52
	v_cvt_pk_bf16_f32 v50, v54, v55
	v_cvt_pk_bf16_f32 v51, v56, v57
	v_cvt_pk_bf16_f32 v52, v69, v70
	v_cvt_pk_bf16_f32 v53, v71, v53
	global_store_dwordx4 v[114:115], v[50:53], off offset:256
	s_nop 1
	v_mov_b32_e32 v50, v194
	v_mul_f32_e32 v54, v61, v50
	v_mul_f32_e32 v51, v66, v50
	v_mul_f32_e32 v52, v67, v50
	v_mul_f32_e32 v53, v60, v50
	v_mul_f32_e32 v55, v64, v50
	v_mul_f32_e32 v56, v65, v50
	v_mul_f32_e32 v57, v58, v50
	v_mul_f32_e32 v50, v59, v50
	v_mul_f32_e32 v45, v50, v45
	v_mul_f32_e32 v46, v51, v46
	v_mul_f32_e32 v47, v52, v47
	v_mul_f32_e32 v48, v53, v48
	v_mul_f32_e32 v49, v54, v49
	v_mul_f32_e32 v51, v55, v42
	v_mul_f32_e32 v52, v56, v43
	v_mul_f32_e32 v53, v57, v44
	v_cvt_pk_bf16_f32 v42, v46, v47
	v_cvt_pk_bf16_f32 v43, v48, v49
	v_cvt_pk_bf16_f32 v44, v51, v52
	v_cvt_pk_bf16_f32 v45, v53, v45
	global_store_dwordx4 v[106:107], v[42:45], off offset:256
	s_nop 1
	v_mov_b32_e32 v42, v196
	v_mul_f32_e32 v46, v61, v42
	v_mul_f32_e32 v43, v66, v42
	v_mul_f32_e32 v44, v67, v42
	v_mul_f32_e32 v45, v60, v42
	v_mul_f32_e32 v47, v64, v42
	v_mul_f32_e32 v48, v65, v42
	v_mul_f32_e32 v49, v58, v42
	v_mul_f32_e32 v42, v59, v42
	v_mul_f32_e32 v37, v42, v37
	v_mul_f32_e32 v38, v43, v38
	v_mul_f32_e32 v39, v44, v39
	v_mul_f32_e32 v40, v45, v40
	v_mul_f32_e32 v41, v46, v41
	v_mul_f32_e32 v43, v47, v34
	v_mul_f32_e32 v44, v48, v35
	v_mul_f32_e32 v45, v49, v36
	v_cvt_pk_bf16_f32 v34, v38, v39
	v_cvt_pk_bf16_f32 v35, v40, v41
	v_cvt_pk_bf16_f32 v36, v43, v44
	v_cvt_pk_bf16_f32 v37, v45, v37
	global_store_dwordx4 v[98:99], v[34:37], off offset:256
	s_nop 1
	v_mov_b32_e32 v34, v198
	v_mul_f32_e32 v38, v61, v34
	v_mul_f32_e32 v35, v66, v34
	v_mul_f32_e32 v36, v67, v34
	v_mul_f32_e32 v37, v60, v34
	v_mul_f32_e32 v39, v64, v34
	v_mul_f32_e32 v40, v65, v34
	v_mul_f32_e32 v41, v58, v34
	v_mul_f32_e32 v34, v59, v34
	v_mul_f32_e32 v29, v34, v29
	v_mul_f32_e32 v30, v35, v30
	v_mul_f32_e32 v31, v36, v31
	v_mul_f32_e32 v32, v37, v32
	v_mul_f32_e32 v33, v38, v33
	v_mul_f32_e32 v35, v39, v26
	v_mul_f32_e32 v36, v40, v27
	v_mul_f32_e32 v37, v41, v28
	v_cvt_pk_bf16_f32 v26, v30, v31
	v_cvt_pk_bf16_f32 v27, v32, v33
	v_cvt_pk_bf16_f32 v28, v35, v36
	v_cvt_pk_bf16_f32 v29, v37, v29
	global_store_dwordx4 v[90:91], v[26:29], off offset:256
	s_nop 1
	v_mov_b32_e32 v26, v200
	v_mul_f32_e32 v30, v61, v26
	v_mul_f32_e32 v27, v66, v26
	v_mul_f32_e32 v28, v67, v26
	v_mul_f32_e32 v29, v60, v26
	v_mul_f32_e32 v31, v64, v26
	v_mul_f32_e32 v32, v65, v26
	v_mul_f32_e32 v33, v58, v26
	v_mul_f32_e32 v26, v59, v26
	v_mul_f32_e32 v21, v26, v21
	v_mul_f32_e32 v22, v27, v22
	v_mul_f32_e32 v23, v28, v23
	v_mul_f32_e32 v24, v29, v24
	v_mul_f32_e32 v25, v30, v25
	v_mul_f32_e32 v27, v31, v18
	v_mul_f32_e32 v28, v32, v19
	v_mul_f32_e32 v29, v33, v20
	v_cvt_pk_bf16_f32 v18, v22, v23
	v_cvt_pk_bf16_f32 v19, v24, v25
	v_cvt_pk_bf16_f32 v20, v27, v28
	v_cvt_pk_bf16_f32 v21, v29, v21
	global_store_dwordx4 v[82:83], v[18:21], off offset:256
	s_nop 1
	v_mov_b32_e32 v18, v202
	v_mul_f32_e32 v22, v61, v18
	v_mul_f32_e32 v19, v66, v18
	v_mul_f32_e32 v20, v67, v18
	v_mul_f32_e32 v21, v60, v18
	v_mul_f32_e32 v23, v64, v18
	v_mul_f32_e32 v24, v65, v18
	v_mul_f32_e32 v25, v58, v18
	v_mul_f32_e32 v18, v59, v18
	v_mul_f32_e32 v13, v18, v13
	v_mul_f32_e32 v14, v19, v14
	v_mul_f32_e32 v15, v20, v15
	v_mul_f32_e32 v16, v21, v16
	v_mul_f32_e32 v17, v22, v17
	v_mul_f32_e32 v19, v23, v10
	v_mul_f32_e32 v20, v24, v11
	v_mul_f32_e32 v21, v25, v12
	v_cvt_pk_bf16_f32 v10, v14, v15
	v_cvt_pk_bf16_f32 v11, v16, v17
	v_cvt_pk_bf16_f32 v12, v19, v20
	v_cvt_pk_bf16_f32 v13, v21, v13
	global_store_dwordx4 v[74:75], v[10:13], off offset:256
	s_nop 1
	v_mov_b32_e32 v10, v204
	v_mul_f32_e32 v14, v61, v10
	v_mul_f32_e32 v11, v66, v10
	v_mul_f32_e32 v12, v67, v10
	v_mul_f32_e32 v13, v60, v10
	v_mul_f32_e32 v15, v64, v10
	v_mul_f32_e32 v16, v65, v10
	v_mul_f32_e32 v17, v58, v10
	v_mul_f32_e32 v10, v59, v10
	v_mul_f32_e32 v5, v10, v5
	v_mul_f32_e32 v6, v11, v6
	v_mul_f32_e32 v7, v12, v7
	v_mul_f32_e32 v8, v13, v8
	v_mul_f32_e32 v9, v14, v9
	v_mul_f32_e32 v11, v15, v2
	v_mul_f32_e32 v12, v16, v3
	v_mul_f32_e32 v13, v17, v4
	v_cvt_pk_bf16_f32 v2, v6, v7
	v_cvt_pk_bf16_f32 v3, v8, v9
	v_cvt_pk_bf16_f32 v4, v11, v12
	v_cvt_pk_bf16_f32 v5, v13, v5
	global_store_dwordx4 v[62:63], v[2:5], off offset:256
	s_cbranch_vccnz .LBB0_552
	s_andn2_b64 vcc, exec, s[16:17]
	s_cbranch_vccnz .LBB0_551
	s_barrier
	s_branch .LBB0_551

.LBB0_587:
	v_lshl_add_u32 v148, s44, 8, v1
	v_ashrrev_i32_e32 v149, 31, v148
	v_lshl_add_u64 v[152:153], v[148:149], 2, s[10:11]
	global_load_dword v160, v[152:153], off
	global_load_dword v192, v[152:153], off offset:64
	global_load_dword v194, v[152:153], off offset:128
	global_load_dword v196, v[152:153], off offset:192
	global_load_dword v198, v[152:153], off offset:512
	global_load_dword v200, v[152:153], off offset:576
	global_load_dword v202, v[152:153], off offset:640
	global_load_dword v204, v[152:153], off offset:704
	v_lshl_or_b32 v154, s63, 8, v156
	v_mov_b64_e32 v[150:151], s[18:19]
	v_ashrrev_i32_e32 v155, 31, v154
	v_mad_i64_i32 v[162:163], s[0:1], v148, s62, v[150:151]
	v_or_b32_e32 v164, 16, v148
	v_lshlrev_b64 v[154:155], 1, v[154:155]
	v_ashrrev_i32_e32 v165, 31, v164
	v_lshl_add_u64 v[162:163], v[162:163], 0, v[154:155]
	v_lshl_add_u64 v[166:167], v[164:165], 2, s[10:11]
	s_and_b64 vcc, exec, s[4:5]
	s_cmp_lg_u64 s[24:25], 0
	s_cbranch_scc0 .Lalb_4
	s_barrier
.Lalb_4:
	s_waitcnt vmcnt(0)
	v_pk_mul_f32 v[128:129], v[128:129], v[160:161] op_sel_hi:[1,0]
	v_pk_mul_f32 v[126:127], v[126:127], v[160:161] op_sel_hi:[1,0]
	v_pk_mul_f32 v[124:125], v[124:125], v[160:161] op_sel_hi:[1,0]
	v_pk_mul_f32 v[122:123], v[122:123], v[160:161] op_sel_hi:[1,0]
	v_pk_mul_f32 v[120:121], v[120:121], v[160:161] op_sel_hi:[1,0]
	v_pk_mul_f32 v[118:119], v[118:119], v[160:161] op_sel_hi:[1,0]
	v_pk_mul_f32 v[168:169], v[116:117], v[160:161] op_sel_hi:[1,0]
	v_pk_mul_f32 v[160:161], v[114:115], v[160:161] op_sel_hi:[1,0]
	v_cvt_pk_bf16_f32 v114, v126, v127
	v_cvt_pk_bf16_f32 v115, v128, v129
	v_cvt_pk_bf16_f32 v116, v122, v123
	v_cvt_pk_bf16_f32 v117, v124, v125
	global_store_dwordx4 v[162:163], v[114:117], off
	s_nop 1
	v_cvt_pk_bf16_f32 v114, v118, v119
	v_cvt_pk_bf16_f32 v115, v120, v121
	v_cvt_pk_bf16_f32 v116, v160, v161
	v_cvt_pk_bf16_f32 v117, v168, v169
	global_store_dwordx4 v[162:163], v[114:117], off offset:256
	s_nop 1
	v_mad_i64_i32 v[118:119], s[0:1], v164, s62, v[150:151]
	v_or_b32_e32 v116, 32, v148
	v_ashrrev_i32_e32 v117, 31, v116
	v_lshl_add_u64 v[118:119], v[118:119], 0, v[154:155]
	v_lshl_add_u64 v[120:121], v[116:117], 2, s[10:11]
	v_mov_b32_e32 v114, v192
	v_pk_mul_f32 v[112:113], v[112:113], v[114:115] op_sel_hi:[1,0]
	v_pk_mul_f32 v[110:111], v[110:111], v[114:115] op_sel_hi:[1,0]
	v_pk_mul_f32 v[108:109], v[108:109], v[114:115] op_sel_hi:[1,0]
	v_pk_mul_f32 v[106:107], v[106:107], v[114:115] op_sel_hi:[1,0]
	v_pk_mul_f32 v[104:105], v[104:105], v[114:115] op_sel_hi:[1,0]
	v_pk_mul_f32 v[102:103], v[102:103], v[114:115] op_sel_hi:[1,0]
	v_pk_mul_f32 v[122:123], v[100:101], v[114:115] op_sel_hi:[1,0]
	v_pk_mul_f32 v[114:115], v[98:99], v[114:115] op_sel_hi:[1,0]
	v_cvt_pk_bf16_f32 v98, v110, v111
	v_cvt_pk_bf16_f32 v99, v112, v113
	v_cvt_pk_bf16_f32 v100, v106, v107
	v_cvt_pk_bf16_f32 v101, v108, v109
	global_store_dwordx4 v[118:119], v[98:101], off
	s_nop 1
	v_cvt_pk_bf16_f32 v98, v102, v103
	v_cvt_pk_bf16_f32 v99, v104, v105
	v_cvt_pk_bf16_f32 v100, v114, v115
	v_cvt_pk_bf16_f32 v101, v122, v123
	global_store_dwordx4 v[118:119], v[98:101], off offset:256
	s_nop 1
	v_mad_i64_i32 v[102:103], s[0:1], v116, s62, v[150:151]
	v_or_b32_e32 v100, 48, v148
	v_ashrrev_i32_e32 v101, 31, v100
	v_lshl_add_u64 v[102:103], v[102:103], 0, v[154:155]
	v_lshl_add_u64 v[104:105], v[100:101], 2, s[10:11]
	v_mov_b32_e32 v98, v194
	v_pk_mul_f32 v[96:97], v[96:97], v[98:99] op_sel_hi:[1,0]
	v_pk_mul_f32 v[94:95], v[94:95], v[98:99] op_sel_hi:[1,0]
	v_pk_mul_f32 v[92:93], v[92:93], v[98:99] op_sel_hi:[1,0]
	v_pk_mul_f32 v[90:91], v[90:91], v[98:99] op_sel_hi:[1,0]
	v_pk_mul_f32 v[84:85], v[84:85], v[98:99] op_sel_hi:[1,0]
	v_pk_mul_f32 v[82:83], v[82:83], v[98:99] op_sel_hi:[1,0]
	v_pk_mul_f32 v[106:107], v[76:77], v[98:99] op_sel_hi:[1,0]
	v_pk_mul_f32 v[98:99], v[74:75], v[98:99] op_sel_hi:[1,0]
	v_cvt_pk_bf16_f32 v74, v94, v95
	v_cvt_pk_bf16_f32 v75, v96, v97
	v_cvt_pk_bf16_f32 v76, v90, v91
	v_cvt_pk_bf16_f32 v77, v92, v93
	global_store_dwordx4 v[102:103], v[74:77], off
	s_nop 1
	v_cvt_pk_bf16_f32 v74, v82, v83
	v_cvt_pk_bf16_f32 v75, v84, v85
	v_cvt_pk_bf16_f32 v76, v98, v99
	v_cvt_pk_bf16_f32 v77, v106, v107
	global_store_dwordx4 v[102:103], v[74:77], off offset:256
	s_nop 1
	v_mov_b32_e32 v74, v196
	v_pk_mul_f32 v[82:83], v[88:89], v[74:75] op_sel_hi:[1,0]
	v_mad_i64_i32 v[76:77], s[0:1], v100, s62, v[150:151]
	v_lshl_add_u64 v[76:77], v[76:77], 0, v[154:155]
	v_pk_mul_f32 v[84:85], v[86:87], v[74:75] op_sel_hi:[1,0]
	v_pk_mul_f32 v[80:81], v[80:81], v[74:75] op_sel_hi:[1,0]
	v_pk_mul_f32 v[78:79], v[78:79], v[74:75] op_sel_hi:[1,0]
	v_pk_mul_f32 v[72:73], v[72:73], v[74:75] op_sel_hi:[1,0]
	v_pk_mul_f32 v[70:71], v[70:71], v[74:75] op_sel_hi:[1,0]
	v_pk_mul_f32 v[86:87], v[68:69], v[74:75] op_sel_hi:[1,0]
	v_pk_mul_f32 v[74:75], v[66:67], v[74:75] op_sel_hi:[1,0]
	v_cvt_pk_bf16_f32 v66, v84, v85
	v_cvt_pk_bf16_f32 v67, v82, v83
	v_cvt_pk_bf16_f32 v68, v78, v79
	v_cvt_pk_bf16_f32 v69, v80, v81
	global_store_dwordx4 v[76:77], v[66:69], off
	s_nop 1
	v_cvt_pk_bf16_f32 v66, v70, v71
	v_cvt_pk_bf16_f32 v67, v72, v73
	v_cvt_pk_bf16_f32 v68, v74, v75
	v_cvt_pk_bf16_f32 v69, v86, v87
	global_store_dwordx4 v[76:77], v[66:69], off offset:256
	s_nop 1
	s_nop 0
	v_add_u32_e32 v67, 0x80, v148
	v_mad_i64_i32 v[68:69], s[0:1], v67, s62, v[150:151]
	v_lshl_add_u64 v[68:69], v[68:69], 0, v[154:155]
	v_mov_b32_e32 v66, v198
	v_pk_mul_f32 v[64:65], v[64:65], v[66:67] op_sel_hi:[1,0]
	v_pk_mul_f32 v[62:63], v[62:63], v[66:67] op_sel_hi:[1,0]
	v_pk_mul_f32 v[60:61], v[60:61], v[66:67] op_sel_hi:[1,0]
	v_pk_mul_f32 v[58:59], v[58:59], v[66:67] op_sel_hi:[1,0]
	v_pk_mul_f32 v[56:57], v[56:57], v[66:67] op_sel_hi:[1,0]
	v_pk_mul_f32 v[54:55], v[54:55], v[66:67] op_sel_hi:[1,0]
	v_pk_mul_f32 v[70:71], v[52:53], v[66:67] op_sel_hi:[1,0]
	v_pk_mul_f32 v[66:67], v[50:51], v[66:67] op_sel_hi:[1,0]
	v_cvt_pk_bf16_f32 v50, v62, v63
	v_cvt_pk_bf16_f32 v51, v64, v65
	v_cvt_pk_bf16_f32 v52, v58, v59
	v_cvt_pk_bf16_f32 v53, v60, v61
	global_store_dwordx4 v[68:69], v[50:53], off
	s_nop 1
	v_cvt_pk_bf16_f32 v50, v54, v55
	v_cvt_pk_bf16_f32 v51, v56, v57
	v_cvt_pk_bf16_f32 v52, v66, v67
	v_cvt_pk_bf16_f32 v53, v70, v71
	global_store_dwordx4 v[68:69], v[50:53], off offset:256
	s_nop 1
	s_nop 0
	v_add_u32_e32 v51, 0x90, v148
	v_mad_i64_i32 v[52:53], s[0:1], v51, s62, v[150:151]
	v_lshl_add_u64 v[52:53], v[52:53], 0, v[154:155]
	v_mov_b32_e32 v50, v200
	v_pk_mul_f32 v[48:49], v[48:49], v[50:51] op_sel_hi:[1,0]
	v_pk_mul_f32 v[46:47], v[46:47], v[50:51] op_sel_hi:[1,0]
	v_pk_mul_f32 v[44:45], v[44:45], v[50:51] op_sel_hi:[1,0]
	v_pk_mul_f32 v[42:43], v[42:43], v[50:51] op_sel_hi:[1,0]
	v_pk_mul_f32 v[40:41], v[40:41], v[50:51] op_sel_hi:[1,0]
	v_pk_mul_f32 v[38:39], v[38:39], v[50:51] op_sel_hi:[1,0]
	v_pk_mul_f32 v[54:55], v[36:37], v[50:51] op_sel_hi:[1,0]
	v_pk_mul_f32 v[50:51], v[34:35], v[50:51] op_sel_hi:[1,0]
	v_cvt_pk_bf16_f32 v34, v46, v47
	v_cvt_pk_bf16_f32 v35, v48, v49
	v_cvt_pk_bf16_f32 v36, v42, v43
	v_cvt_pk_bf16_f32 v37, v44, v45
	global_store_dwordx4 v[52:53], v[34:37], off
	s_nop 1
	v_cvt_pk_bf16_f32 v34, v38, v39
	v_cvt_pk_bf16_f32 v35, v40, v41
	v_cvt_pk_bf16_f32 v36, v50, v51
	v_cvt_pk_bf16_f32 v37, v54, v55
	global_store_dwordx4 v[52:53], v[34:37], off offset:256
	s_nop 1
	s_nop 0
	v_add_u32_e32 v35, 0xa0, v148
	v_mad_i64_i32 v[36:37], s[0:1], v35, s62, v[150:151]
	v_lshl_add_u64 v[36:37], v[36:37], 0, v[154:155]
	v_mov_b32_e32 v34, v202
	v_pk_mul_f32 v[32:33], v[32:33], v[34:35] op_sel_hi:[1,0]
	v_pk_mul_f32 v[30:31], v[30:31], v[34:35] op_sel_hi:[1,0]
	v_pk_mul_f32 v[28:29], v[28:29], v[34:35] op_sel_hi:[1,0]
	v_pk_mul_f32 v[26:27], v[26:27], v[34:35] op_sel_hi:[1,0]
	v_pk_mul_f32 v[24:25], v[24:25], v[34:35] op_sel_hi:[1,0]
	v_pk_mul_f32 v[22:23], v[22:23], v[34:35] op_sel_hi:[1,0]
	v_pk_mul_f32 v[38:39], v[20:21], v[34:35] op_sel_hi:[1,0]
	v_pk_mul_f32 v[34:35], v[18:19], v[34:35] op_sel_hi:[1,0]
	v_cvt_pk_bf16_f32 v18, v30, v31
	v_cvt_pk_bf16_f32 v19, v32, v33
	v_cvt_pk_bf16_f32 v20, v26, v27
	v_cvt_pk_bf16_f32 v21, v28, v29
	global_store_dwordx4 v[36:37], v[18:21], off
	s_nop 1
	v_cvt_pk_bf16_f32 v18, v22, v23
	v_cvt_pk_bf16_f32 v19, v24, v25
	v_cvt_pk_bf16_f32 v20, v34, v35
	v_cvt_pk_bf16_f32 v21, v38, v39
	global_store_dwordx4 v[36:37], v[18:21], off offset:256
	s_nop 1
	s_nop 0
	v_add_u32_e32 v19, 0xb0, v148
	v_mad_i64_i32 v[20:21], s[0:1], v19, s62, v[150:151]
	v_lshl_add_u64 v[20:21], v[20:21], 0, v[154:155]
	s_mov_b64 s[0:1], -1
	v_mov_b32_e32 v18, v204
	v_pk_mul_f32 v[16:17], v[16:17], v[18:19] op_sel_hi:[1,0]
	v_pk_mul_f32 v[14:15], v[14:15], v[18:19] op_sel_hi:[1,0]
	v_pk_mul_f32 v[12:13], v[12:13], v[18:19] op_sel_hi:[1,0]
	v_pk_mul_f32 v[10:11], v[10:11], v[18:19] op_sel_hi:[1,0]
	v_pk_mul_f32 v[8:9], v[8:9], v[18:19] op_sel_hi:[1,0]
	v_pk_mul_f32 v[6:7], v[6:7], v[18:19] op_sel_hi:[1,0]
	v_pk_mul_f32 v[22:23], v[4:5], v[18:19] op_sel_hi:[1,0]
	v_pk_mul_f32 v[18:19], v[2:3], v[18:19] op_sel_hi:[1,0]
	v_cvt_pk_bf16_f32 v2, v14, v15
	v_cvt_pk_bf16_f32 v3, v16, v17
	v_cvt_pk_bf16_f32 v4, v10, v11
	v_cvt_pk_bf16_f32 v5, v12, v13
	global_store_dwordx4 v[20:21], v[2:5], off
	s_nop 1
	v_cvt_pk_bf16_f32 v2, v6, v7
	v_cvt_pk_bf16_f32 v3, v8, v9
	v_cvt_pk_bf16_f32 v4, v18, v19
	v_cvt_pk_bf16_f32 v5, v22, v23
	global_store_dwordx4 v[20:21], v[2:5], off offset:256
	s_cbranch_vccnz .LBB0_574
	s_andn2_b64 vcc, exec, s[16:17]
	s_cbranch_vccnz .LBB0_573
	s_barrier
	s_branch .LBB0_573

.LBB0_613:
	v_lshl_or_b32 v156, s67, 8, v162
	v_ashrrev_i32_e32 v157, 31, v156
	v_lshl_add_u32 v152, s48, 8, v1
	v_lshl_add_u64 v[150:151], v[156:157], 2, s[18:19]
	v_ashrrev_i32_e32 v153, 31, v152
	global_load_dwordx4 v[166:169], v[150:151], off offset:16
	global_load_dwordx4 v[158:161], v[150:151], off
	v_lshl_add_u64 v[148:149], v[152:153], 2, s[26:27]
	global_load_dword v153, v[148:149], off
	global_load_dword v190, v[148:149], off
	global_load_dword v192, v[148:149], off offset:64
	global_load_dword v194, v[148:149], off offset:128
	global_load_dword v196, v[148:149], off offset:192
	global_load_dword v198, v[148:149], off offset:512
	global_load_dword v200, v[148:149], off offset:576
	global_load_dword v202, v[148:149], off offset:640
	global_load_dword v204, v[148:149], off offset:704
	global_load_dwordx4 v[206:209], v[150:151], off offset:512
	global_load_dwordx4 v[210:213], v[150:151], off offset:528
	v_cvt_f32_i32_e32 v172, v126
	v_cvt_f32_i32_e32 v173, v127
	v_cvt_f32_i32_e32 v174, v128
	v_cvt_f32_i32_e32 v175, v129
	v_cvt_f32_i32_e32 v176, v122
	v_cvt_f32_i32_e32 v177, v123
	v_cvt_f32_i32_e32 v178, v124
	v_cvt_f32_i32_e32 v179, v125
	v_or_b32_e32 v170, 16, v152
	v_lshlrev_b64 v[128:129], 1, v[156:157]
	v_ashrrev_i32_e32 v171, 31, v170
	v_lshl_add_u64 v[124:125], v[170:171], 2, s[26:27]
	s_cmp_lt_i32 s67, 0
	v_mov_b64_e32 v[154:155], s[16:17]
	v_mad_i64_i32 v[122:123], s[0:1], v152, s65, v[154:155]
	s_cselect_b64 s[6:7], -1, 0
	v_lshl_add_u64 v[122:123], v[122:123], 0, v[128:129]
	v_cvt_f32_i32_e32 v118, v118
	v_cvt_f32_i32_e32 v119, v119
	v_cvt_f32_i32_e32 v120, v120
	v_cvt_f32_i32_e32 v121, v121
	v_cvt_f32_i32_e32 v110, v110
	v_cvt_f32_i32_e32 v111, v111
	v_cvt_f32_i32_e32 v112, v112
	v_cvt_f32_i32_e32 v113, v113
	v_cvt_f32_i32_e32 v102, v102
	v_cvt_f32_i32_e32 v103, v103
	v_cvt_f32_i32_e32 v104, v104
	v_cvt_f32_i32_e32 v105, v105
	v_cvt_f32_i32_e32 v100, v100
	v_cvt_f32_i32_e32 v101, v101
	v_cvt_f32_i32_e32 v94, v94
	v_cvt_f32_i32_e32 v95, v95
	v_cvt_f32_i32_e32 v96, v96
	v_cvt_f32_i32_e32 v97, v97
	v_cvt_f32_i32_e32 v92, v92
	v_cvt_f32_i32_e32 v93, v93
	v_cvt_f32_i32_e32 v86, v86
	v_cvt_f32_i32_e32 v87, v87
	v_cvt_f32_i32_e32 v88, v88
	v_cvt_f32_i32_e32 v89, v89
	v_cvt_f32_i32_e32 v84, v84
	v_cvt_f32_i32_e32 v85, v85
	v_cvt_f32_i32_e32 v78, v78
	v_cvt_f32_i32_e32 v79, v79
	v_cvt_f32_i32_e32 v80, v80
	v_cvt_f32_i32_e32 v81, v81
	v_cvt_f32_i32_e32 v76, v76
	v_cvt_f32_i32_e32 v77, v77
	v_cvt_f32_i32_e32 v70, v70
	v_cvt_f32_i32_e32 v71, v71
	v_cvt_f32_i32_e32 v72, v72
	v_cvt_f32_i32_e32 v73, v73
	v_cvt_f32_i32_e32 v68, v68
	v_cvt_f32_i32_e32 v69, v69
	v_cvt_f32_i32_e32 v53, v53
	v_cvt_f32_i32_e32 v54, v54
	v_cvt_f32_i32_e32 v55, v55
	v_cvt_f32_i32_e32 v56, v56
	v_cvt_f32_i32_e32 v57, v57
	v_cvt_f32_i32_e32 v50, v50
	v_cvt_f32_i32_e32 v51, v51
	v_cvt_f32_i32_e32 v52, v52
	v_cvt_f32_i32_e32 v45, v45
	v_cvt_f32_i32_e32 v46, v46
	v_cvt_f32_i32_e32 v47, v47
	v_cvt_f32_i32_e32 v48, v48
	v_cvt_f32_i32_e32 v49, v49
	v_cvt_f32_i32_e32 v42, v42
	v_cvt_f32_i32_e32 v43, v43
	v_cvt_f32_i32_e32 v44, v44
	v_cvt_f32_i32_e32 v37, v37
	v_cvt_f32_i32_e32 v38, v38
	v_cvt_f32_i32_e32 v39, v39
	v_cvt_f32_i32_e32 v40, v40
	s_cmp_lg_u64 s[24:25], 0
	s_cbranch_scc0 .Lalb_5
	s_barrier
.Lalb_5:
	s_waitcnt vmcnt(0)
	s_mov_b32 s98, 0x3c3a1e78
	v_pk_mul_f32 v[126:127], v[168:169], s[98:99] op_sel_hi:[1,0]
	v_pk_mul_f32 v[156:157], v[160:161], s[98:99] op_sel_hi:[1,0]
	v_pk_mul_f32 v[160:161], v[158:159], s[98:99] op_sel_hi:[1,0]
	v_pk_mul_f32 v[158:159], v[166:167], s[98:99] op_sel_hi:[1,0]
	v_mul_f32_e32 v166, v160, v153
	v_mul_f32_e32 v167, v161, v153
	v_mul_f32_e32 v168, v156, v153
	v_mul_f32_e32 v169, v157, v153
	v_mul_f32_e32 v171, v153, v158
	v_mul_f32_e32 v180, v153, v159
	v_mul_f32_e32 v181, v153, v126
	v_mul_f32_e32 v153, v153, v127
	v_mul_f32_e32 v166, v166, v172
	v_mul_f32_e32 v167, v167, v173
	v_mul_f32_e32 v168, v168, v174
	v_mul_f32_e32 v169, v169, v175
	v_mul_f32_e32 v171, v171, v176
	v_mul_f32_e32 v172, v180, v177
	v_mul_f32_e32 v173, v181, v178
	v_mul_f32_e32 v153, v153, v179
	v_exp_f32_e64 v174, -v166
	v_exp_f32_e64 v175, -v167
	v_exp_f32_e64 v176, -v168
	v_exp_f32_e64 v177, -v169
	v_exp_f32_e64 v178, -v171
	v_exp_f32_e64 v179, -v172
	v_exp_f32_e64 v180, -v173
	v_exp_f32_e64 v181, -v153
	v_add_f32_e32 v174, 1.0, v174
	v_add_f32_e32 v175, 1.0, v175
	v_add_f32_e32 v176, 1.0, v176
	v_add_f32_e32 v177, 1.0, v177
	v_add_f32_e32 v178, 1.0, v178
	v_add_f32_e32 v179, 1.0, v179
	v_add_f32_e32 v180, 1.0, v180
	v_add_f32_e32 v181, 1.0, v181
	v_rcp_f32_e32 v174, v174
	v_rcp_f32_e32 v175, v175
	v_rcp_f32_e32 v176, v176
	v_rcp_f32_e32 v177, v177
	v_rcp_f32_e32 v178, v178
	v_rcp_f32_e32 v179, v179
	v_rcp_f32_e32 v180, v180
	v_rcp_f32_e32 v181, v181
	v_cvt_pk_bf16_f32 v166, v174, v175
	v_cvt_pk_bf16_f32 v167, v176, v177
	v_cvt_pk_bf16_f32 v168, v178, v179
	v_cvt_pk_bf16_f32 v169, v180, v181
	global_store_dwordx4 v[122:123], v[166:169], off
	s_nop 1
	v_cvt_f32_i32_e32 v171, v116
	v_cvt_f32_i32_e32 v168, v114
	v_cvt_f32_i32_e32 v169, v115
	v_cvt_f32_i32_e32 v172, v117
	v_or_b32_e32 v166, 32, v152
	v_ashrrev_i32_e32 v167, 31, v166
	v_mad_i64_i32 v[114:115], s[0:1], v170, s65, v[154:155]
	v_lshl_add_u64 v[116:117], v[166:167], 2, s[26:27]
	v_lshl_add_u64 v[114:115], v[114:115], 0, v[128:129]
	v_cvt_f32_i32_e32 v41, v41
	v_cvt_f32_i32_e32 v34, v34
	v_cvt_f32_i32_e32 v35, v35
	v_cvt_f32_i32_e32 v36, v36
	v_cvt_f32_i32_e32 v29, v29
	v_cvt_f32_i32_e32 v30, v30
	v_cvt_f32_i32_e32 v31, v31
	v_cvt_f32_i32_e32 v32, v32
	v_cvt_f32_i32_e32 v33, v33
	v_cvt_f32_i32_e32 v26, v26
	v_cvt_f32_i32_e32 v27, v27
	v_cvt_f32_i32_e32 v28, v28
	v_cvt_f32_i32_e32 v21, v21
	v_cvt_f32_i32_e32 v22, v22
	v_cvt_f32_i32_e32 v23, v23
	v_cvt_f32_i32_e32 v24, v24
	v_cvt_f32_i32_e32 v25, v25
	v_cvt_f32_i32_e32 v18, v18
	v_cvt_f32_i32_e32 v19, v19
	v_cvt_f32_i32_e32 v20, v20
	v_cvt_f32_i32_e32 v13, v13
	v_cvt_f32_i32_e32 v14, v14
	v_cvt_f32_i32_e32 v15, v15
	v_cvt_f32_i32_e32 v16, v16
	v_cvt_f32_i32_e32 v17, v17
	v_cvt_f32_i32_e32 v10, v10
	v_cvt_f32_i32_e32 v11, v11
	v_cvt_f32_i32_e32 v12, v12
	v_cvt_f32_i32_e32 v5, v5
	v_cvt_f32_i32_e32 v6, v6
	v_cvt_f32_i32_e32 v7, v7
	v_cvt_f32_i32_e32 v8, v8
	v_cvt_f32_i32_e32 v9, v9
	v_cvt_f32_i32_e32 v2, v2
	v_cvt_f32_i32_e32 v3, v3
	v_cvt_f32_i32_e32 v4, v4
	s_and_b64 vcc, exec, s[4:5]
	v_mov_b32_e32 v153, v192
	v_mul_f32_e32 v167, v160, v153
	v_mul_f32_e32 v170, v161, v153
	v_mul_f32_e32 v173, v156, v153
	v_mul_f32_e32 v174, v157, v153
	v_mul_f32_e32 v175, v158, v153
	v_mul_f32_e32 v176, v159, v153
	v_mul_f32_e32 v177, v126, v153
	v_mul_f32_e32 v153, v127, v153
	v_mul_f32_e32 v118, v167, v118
	v_mul_f32_e32 v119, v170, v119
	v_mul_f32_e32 v120, v173, v120
	v_mul_f32_e32 v121, v174, v121
	v_mul_f32_e32 v167, v175, v168
	v_mul_f32_e32 v168, v176, v169
	v_mul_f32_e32 v169, v177, v171
	v_mul_f32_e32 v153, v153, v172
	v_exp_f32_e64 v170, -v118
	v_exp_f32_e64 v171, -v119
	v_exp_f32_e64 v172, -v120
	v_exp_f32_e64 v173, -v121
	v_exp_f32_e64 v174, -v167
	v_exp_f32_e64 v175, -v168
	v_exp_f32_e64 v176, -v169
	v_exp_f32_e64 v177, -v153
	v_add_f32_e32 v170, 1.0, v170
	v_add_f32_e32 v171, 1.0, v171
	v_add_f32_e32 v172, 1.0, v172
	v_add_f32_e32 v173, 1.0, v173
	v_add_f32_e32 v174, 1.0, v174
	v_add_f32_e32 v175, 1.0, v175
	v_add_f32_e32 v176, 1.0, v176
	v_add_f32_e32 v177, 1.0, v177
	v_rcp_f32_e32 v170, v170
	v_rcp_f32_e32 v171, v171
	v_rcp_f32_e32 v172, v172
	v_rcp_f32_e32 v173, v173
	v_rcp_f32_e32 v174, v174
	v_rcp_f32_e32 v175, v175
	v_rcp_f32_e32 v176, v176
	v_rcp_f32_e32 v177, v177
	v_cvt_pk_bf16_f32 v118, v170, v171
	v_cvt_pk_bf16_f32 v119, v172, v173
	v_cvt_pk_bf16_f32 v120, v174, v175
	v_cvt_pk_bf16_f32 v121, v176, v177
	global_store_dwordx4 v[114:115], v[118:121], off
	s_nop 1
	v_cvt_f32_i32_e32 v153, v107
	v_cvt_f32_i32_e32 v121, v106
	v_cvt_f32_i32_e32 v167, v108
	v_cvt_f32_i32_e32 v168, v109
	v_or_b32_e32 v118, 48, v152
	v_ashrrev_i32_e32 v119, 31, v118
	v_mad_i64_i32 v[106:107], s[0:1], v166, s65, v[154:155]
	v_lshl_add_u64 v[108:109], v[118:119], 2, s[26:27]
	v_lshl_add_u64 v[106:107], v[106:107], 0, v[128:129]
	v_mov_b32_e32 v120, v194
	v_mul_f32_e32 v119, v160, v120
	v_mul_f32_e32 v166, v161, v120
	v_mul_f32_e32 v169, v156, v120
	v_mul_f32_e32 v170, v157, v120
	v_mul_f32_e32 v171, v158, v120
	v_mul_f32_e32 v172, v159, v120
	v_mul_f32_e32 v173, v126, v120
	v_mul_f32_e32 v120, v127, v120
	v_mul_f32_e32 v110, v119, v110
	v_mul_f32_e32 v111, v166, v111
	v_mul_f32_e32 v112, v169, v112
	v_mul_f32_e32 v113, v170, v113
	v_mul_f32_e32 v119, v171, v121
	v_mul_f32_e32 v121, v172, v153
	v_mul_f32_e32 v153, v173, v167
	v_mul_f32_e32 v120, v120, v168
	v_exp_f32_e64 v166, -v110
	v_exp_f32_e64 v167, -v111
	v_exp_f32_e64 v168, -v112
	v_exp_f32_e64 v169, -v113
	v_exp_f32_e64 v170, -v119
	v_exp_f32_e64 v171, -v121
	v_exp_f32_e64 v172, -v153
	v_exp_f32_e64 v173, -v120
	v_add_f32_e32 v166, 1.0, v166
	v_add_f32_e32 v167, 1.0, v167
	v_add_f32_e32 v168, 1.0, v168
	v_add_f32_e32 v169, 1.0, v169
	v_add_f32_e32 v170, 1.0, v170
	v_add_f32_e32 v171, 1.0, v171
	v_add_f32_e32 v172, 1.0, v172
	v_add_f32_e32 v173, 1.0, v173
	v_rcp_f32_e32 v166, v166
	v_rcp_f32_e32 v167, v167
	v_rcp_f32_e32 v168, v168
	v_rcp_f32_e32 v169, v169
	v_rcp_f32_e32 v170, v170
	v_rcp_f32_e32 v171, v171
	v_rcp_f32_e32 v172, v172
	v_rcp_f32_e32 v173, v173
	v_cvt_pk_bf16_f32 v110, v166, v167
	v_cvt_pk_bf16_f32 v111, v168, v169
	v_cvt_pk_bf16_f32 v112, v170, v171
	v_cvt_pk_bf16_f32 v113, v172, v173
	global_store_dwordx4 v[106:107], v[110:113], off
	s_nop 1
	v_mov_b32_e32 v110, v196
	v_mul_f32_e32 v119, v156, v110
	v_cvt_f32_i32_e32 v111, v98
	v_cvt_f32_i32_e32 v112, v99
	v_mad_i64_i32 v[98:99], s[0:1], v118, s65, v[154:155]
	v_mul_f32_e32 v113, v160, v110
	v_mul_f32_e32 v118, v161, v110
	v_mul_f32_e32 v120, v157, v110
	v_mul_f32_e32 v121, v158, v110
	v_mul_f32_e32 v153, v159, v110
	v_mul_f32_e32 v166, v126, v110
	v_mul_f32_e32 v110, v127, v110
	v_mul_f32_e32 v102, v113, v102
	v_mul_f32_e32 v103, v118, v103
	v_mul_f32_e32 v104, v119, v104
	v_mul_f32_e32 v105, v120, v105
	v_mul_f32_e32 v111, v121, v111
	v_mul_f32_e32 v112, v153, v112
	v_mul_f32_e32 v100, v166, v100
	v_mul_f32_e32 v101, v110, v101
	v_exp_f32_e64 v110, -v102
	v_exp_f32_e64 v113, -v103
	v_exp_f32_e64 v118, -v104
	v_exp_f32_e64 v119, -v105
	v_exp_f32_e64 v120, -v111
	v_exp_f32_e64 v121, -v112
	v_exp_f32_e64 v153, -v100
	v_exp_f32_e64 v166, -v101
	v_add_f32_e32 v110, 1.0, v110
	v_add_f32_e32 v113, 1.0, v113
	v_add_f32_e32 v118, 1.0, v118
	v_add_f32_e32 v119, 1.0, v119
	v_add_f32_e32 v120, 1.0, v120
	v_add_f32_e32 v121, 1.0, v121
	v_add_f32_e32 v153, 1.0, v153
	v_add_f32_e32 v166, 1.0, v166
	v_rcp_f32_e32 v110, v110
	v_rcp_f32_e32 v113, v113
	v_rcp_f32_e32 v118, v118
	v_rcp_f32_e32 v119, v119
	v_rcp_f32_e32 v120, v120
	v_rcp_f32_e32 v121, v121
	v_rcp_f32_e32 v153, v153
	v_rcp_f32_e32 v166, v166
	v_lshl_add_u64 v[98:99], v[98:99], 0, v[128:129]
	v_cvt_pk_bf16_f32 v100, v110, v113
	v_cvt_pk_bf16_f32 v101, v118, v119
	v_cvt_pk_bf16_f32 v102, v120, v121
	v_cvt_pk_bf16_f32 v103, v153, v166
	global_store_dwordx4 v[98:99], v[100:103], off
	s_nop 1
	v_mov_b32_e32 v100, v198
	v_mul_f32_e32 v104, v161, v100
	v_cvt_f32_i32_e32 v101, v90
	v_cvt_f32_i32_e32 v102, v91
	v_mul_f32_e32 v103, v160, v100
	v_mul_f32_e32 v105, v156, v100
	v_mul_f32_e32 v110, v157, v100
	v_mul_f32_e32 v111, v158, v100
	v_mul_f32_e32 v112, v159, v100
	v_mul_f32_e32 v113, v126, v100
	v_mul_f32_e32 v100, v127, v100
	v_mul_f32_e32 v94, v103, v94
	v_mul_f32_e32 v95, v104, v95
	v_mul_f32_e32 v96, v105, v96
	v_mul_f32_e32 v97, v110, v97
	v_mul_f32_e32 v101, v111, v101
	v_mul_f32_e32 v102, v112, v102
	v_mul_f32_e32 v92, v113, v92
	v_mul_f32_e32 v93, v100, v93
	v_exp_f32_e64 v100, -v94
	v_exp_f32_e64 v103, -v95
	v_exp_f32_e64 v104, -v96
	v_exp_f32_e64 v105, -v97
	v_exp_f32_e64 v110, -v101
	v_exp_f32_e64 v111, -v102
	v_exp_f32_e64 v112, -v92
	v_exp_f32_e64 v113, -v93
	v_add_f32_e32 v100, 1.0, v100
	v_add_f32_e32 v103, 1.0, v103
	v_add_f32_e32 v104, 1.0, v104
	v_add_f32_e32 v105, 1.0, v105
	v_add_f32_e32 v110, 1.0, v110
	v_add_f32_e32 v111, 1.0, v111
	v_add_f32_e32 v112, 1.0, v112
	v_add_f32_e32 v113, 1.0, v113
	v_rcp_f32_e32 v100, v100
	v_rcp_f32_e32 v103, v103
	v_rcp_f32_e32 v104, v104
	v_rcp_f32_e32 v105, v105
	v_rcp_f32_e32 v110, v110
	v_rcp_f32_e32 v111, v111
	v_rcp_f32_e32 v112, v112
	v_rcp_f32_e32 v113, v113
	v_add_u32_e32 v90, 0x80, v152
	v_mad_i64_i32 v[90:91], s[0:1], v90, s65, v[154:155]
	v_lshl_add_u64 v[90:91], v[90:91], 0, v[128:129]
	v_cvt_pk_bf16_f32 v92, v100, v103
	v_cvt_pk_bf16_f32 v93, v104, v105
	v_cvt_pk_bf16_f32 v94, v110, v111
	v_cvt_pk_bf16_f32 v95, v112, v113
	global_store_dwordx4 v[90:91], v[92:95], off
	s_nop 1
	v_mov_b32_e32 v92, v200
	v_mul_f32_e32 v96, v161, v92
	v_cvt_f32_i32_e32 v93, v82
	v_cvt_f32_i32_e32 v94, v83
	v_mul_f32_e32 v95, v160, v92
	v_mul_f32_e32 v97, v156, v92
	v_mul_f32_e32 v100, v157, v92
	v_mul_f32_e32 v101, v158, v92
	v_mul_f32_e32 v102, v159, v92
	v_mul_f32_e32 v103, v126, v92
	v_mul_f32_e32 v92, v127, v92
	v_mul_f32_e32 v86, v95, v86
	v_mul_f32_e32 v87, v96, v87
	v_mul_f32_e32 v88, v97, v88
	v_mul_f32_e32 v89, v100, v89
	v_mul_f32_e32 v93, v101, v93
	v_mul_f32_e32 v94, v102, v94
	v_mul_f32_e32 v84, v103, v84
	v_mul_f32_e32 v85, v92, v85
	v_exp_f32_e64 v92, -v86
	v_exp_f32_e64 v95, -v87
	v_exp_f32_e64 v96, -v88
	v_exp_f32_e64 v97, -v89
	v_exp_f32_e64 v100, -v93
	v_exp_f32_e64 v101, -v94
	v_exp_f32_e64 v102, -v84
	v_exp_f32_e64 v103, -v85
	v_add_f32_e32 v92, 1.0, v92
	v_add_f32_e32 v95, 1.0, v95
	v_add_f32_e32 v96, 1.0, v96
	v_add_f32_e32 v97, 1.0, v97
	v_add_f32_e32 v100, 1.0, v100
	v_add_f32_e32 v101, 1.0, v101
	v_add_f32_e32 v102, 1.0, v102
	v_add_f32_e32 v103, 1.0, v103
	v_rcp_f32_e32 v92, v92
	v_rcp_f32_e32 v95, v95
	v_rcp_f32_e32 v96, v96
	v_rcp_f32_e32 v97, v97
	v_rcp_f32_e32 v100, v100
	v_rcp_f32_e32 v101, v101
	v_rcp_f32_e32 v102, v102
	v_rcp_f32_e32 v103, v103
	v_add_u32_e32 v82, 0x90, v152
	v_mad_i64_i32 v[82:83], s[0:1], v82, s65, v[154:155]
	v_lshl_add_u64 v[82:83], v[82:83], 0, v[128:129]
	v_cvt_pk_bf16_f32 v84, v92, v95
	v_cvt_pk_bf16_f32 v85, v96, v97
	v_cvt_pk_bf16_f32 v86, v100, v101
	v_cvt_pk_bf16_f32 v87, v102, v103
	global_store_dwordx4 v[82:83], v[84:87], off
	s_nop 1
	v_mov_b32_e32 v84, v202
	v_mul_f32_e32 v88, v161, v84
	v_cvt_f32_i32_e32 v85, v74
	v_cvt_f32_i32_e32 v86, v75
	v_mul_f32_e32 v87, v160, v84
	v_mul_f32_e32 v89, v156, v84
	v_mul_f32_e32 v92, v157, v84
	v_mul_f32_e32 v93, v158, v84
	v_mul_f32_e32 v94, v159, v84
	v_mul_f32_e32 v95, v126, v84
	v_mul_f32_e32 v84, v127, v84
	v_mul_f32_e32 v78, v87, v78
	v_mul_f32_e32 v79, v88, v79
	v_mul_f32_e32 v80, v89, v80
	v_mul_f32_e32 v81, v92, v81
	v_mul_f32_e32 v85, v93, v85
	v_mul_f32_e32 v86, v94, v86
	v_mul_f32_e32 v76, v95, v76
	v_mul_f32_e32 v77, v84, v77
	v_exp_f32_e64 v84, -v78
	v_exp_f32_e64 v87, -v79
	v_exp_f32_e64 v88, -v80
	v_exp_f32_e64 v89, -v81
	v_exp_f32_e64 v92, -v85
	v_exp_f32_e64 v93, -v86
	v_exp_f32_e64 v94, -v76
	v_exp_f32_e64 v95, -v77
	v_add_f32_e32 v84, 1.0, v84
	v_add_f32_e32 v87, 1.0, v87
	v_add_f32_e32 v88, 1.0, v88
	v_add_f32_e32 v89, 1.0, v89
	v_add_f32_e32 v92, 1.0, v92
	v_add_f32_e32 v93, 1.0, v93
	v_add_f32_e32 v94, 1.0, v94
	v_add_f32_e32 v95, 1.0, v95
	v_rcp_f32_e32 v84, v84
	v_rcp_f32_e32 v87, v87
	v_rcp_f32_e32 v88, v88
	v_rcp_f32_e32 v89, v89
	v_rcp_f32_e32 v92, v92
	v_rcp_f32_e32 v93, v93
	v_rcp_f32_e32 v94, v94
	v_rcp_f32_e32 v95, v95
	v_add_u32_e32 v74, 0xa0, v152
	v_mad_i64_i32 v[74:75], s[0:1], v74, s65, v[154:155]
	v_lshl_add_u64 v[74:75], v[74:75], 0, v[128:129]
	v_cvt_pk_bf16_f32 v76, v84, v87
	v_cvt_pk_bf16_f32 v77, v88, v89
	v_cvt_pk_bf16_f32 v78, v92, v93
	v_cvt_pk_bf16_f32 v79, v94, v95
	global_store_dwordx4 v[74:75], v[76:79], off
	s_nop 1
	v_cvt_f32_i32_e32 v88, v61
	v_cvt_f32_i32_e32 v77, v66
	v_cvt_f32_i32_e32 v78, v67
	v_add_u32_e32 v66, 0xb0, v152
	v_mad_i64_i32 v[66:67], s[0:1], v66, s65, v[154:155]
	v_lshl_add_u64 v[66:67], v[66:67], 0, v[128:129]
	s_mov_b64 s[0:1], -1
	v_mov_b32_e32 v76, v204
	v_mul_f32_e32 v79, v160, v76
	v_mul_f32_e32 v80, v161, v76
	v_mul_f32_e32 v81, v156, v76
	v_mul_f32_e32 v84, v157, v76
	v_mul_f32_e32 v85, v158, v76
	v_mul_f32_e32 v86, v159, v76
	v_mul_f32_e32 v87, v126, v76
	v_mul_f32_e32 v76, v127, v76
	v_mul_f32_e32 v70, v79, v70
	v_mul_f32_e32 v71, v80, v71
	v_mul_f32_e32 v72, v81, v72
	v_mul_f32_e32 v73, v84, v73
	v_mul_f32_e32 v77, v85, v77
	v_mul_f32_e32 v78, v86, v78
	v_mul_f32_e32 v68, v87, v68
	v_mul_f32_e32 v69, v76, v69
	v_exp_f32_e64 v76, -v70
	v_exp_f32_e64 v79, -v71
	v_exp_f32_e64 v80, -v72
	v_exp_f32_e64 v81, -v73
	v_exp_f32_e64 v84, -v77
	v_exp_f32_e64 v85, -v78
	v_exp_f32_e64 v86, -v68
	v_exp_f32_e64 v87, -v69
	v_add_f32_e32 v76, 1.0, v76
	v_add_f32_e32 v79, 1.0, v79
	v_add_f32_e32 v80, 1.0, v80
	v_add_f32_e32 v81, 1.0, v81
	v_add_f32_e32 v84, 1.0, v84
	v_add_f32_e32 v85, 1.0, v85
	v_add_f32_e32 v86, 1.0, v86
	v_add_f32_e32 v87, 1.0, v87
	v_rcp_f32_e32 v76, v76
	v_rcp_f32_e32 v79, v79
	v_rcp_f32_e32 v80, v80
	v_rcp_f32_e32 v81, v81
	v_rcp_f32_e32 v84, v84
	v_rcp_f32_e32 v85, v85
	v_rcp_f32_e32 v86, v86
	v_rcp_f32_e32 v87, v87
	v_cvt_pk_bf16_f32 v68, v76, v79
	v_cvt_pk_bf16_f32 v69, v80, v81
	v_cvt_pk_bf16_f32 v70, v84, v85
	v_cvt_pk_bf16_f32 v71, v86, v87
	global_store_dwordx4 v[66:67], v[68:71], off
	s_nop 1
	s_nop 1
	v_cvt_f32_i32_e32 v73, v62
	v_cvt_f32_i32_e32 v80, v63
	v_cvt_f32_i32_e32 v81, v64
	v_cvt_f32_i32_e32 v84, v65
	v_cvt_f32_i32_e32 v85, v58
	v_cvt_f32_i32_e32 v86, v59
	v_cvt_f32_i32_e32 v87, v60
	v_pk_mul_f32 v[60:61], v[208:209], s[98:99] op_sel_hi:[1,0]
	v_pk_mul_f32 v[64:65], v[206:207], s[98:99] op_sel_hi:[1,0]
	v_pk_mul_f32 v[58:59], v[212:213], s[98:99] op_sel_hi:[1,0]
	v_pk_mul_f32 v[62:63], v[210:211], s[98:99] op_sel_hi:[1,0]
	v_mov_b32_e32 v72, v190
	v_mul_f32_e32 v68, v64, v72
	v_mul_f32_e32 v69, v65, v72
	v_mul_f32_e32 v70, v60, v72
	v_mul_f32_e32 v71, v61, v72
	v_mul_f32_e32 v76, v72, v62
	v_mul_f32_e32 v77, v72, v63
	v_mul_f32_e32 v78, v72, v58
	v_mul_f32_e32 v72, v72, v59
	v_mul_f32_e32 v68, v68, v73
	v_mul_f32_e32 v69, v69, v80
	v_mul_f32_e32 v70, v70, v81
	v_mul_f32_e32 v71, v71, v84
	v_mul_f32_e32 v73, v76, v85
	v_mul_f32_e32 v76, v77, v86
	v_mul_f32_e32 v77, v78, v87
	v_mul_f32_e32 v72, v72, v88
	v_exp_f32_e64 v78, -v68
	v_exp_f32_e64 v79, -v69
	v_exp_f32_e64 v80, -v70
	v_exp_f32_e64 v81, -v71
	v_exp_f32_e64 v84, -v73
	v_exp_f32_e64 v85, -v76
	v_exp_f32_e64 v86, -v77
	v_exp_f32_e64 v87, -v72
	v_add_f32_e32 v78, 1.0, v78
	v_add_f32_e32 v79, 1.0, v79
	v_add_f32_e32 v80, 1.0, v80
	v_add_f32_e32 v81, 1.0, v81
	v_add_f32_e32 v84, 1.0, v84
	v_add_f32_e32 v85, 1.0, v85
	v_add_f32_e32 v86, 1.0, v86
	v_add_f32_e32 v87, 1.0, v87
	v_rcp_f32_e32 v78, v78
	v_rcp_f32_e32 v79, v79
	v_rcp_f32_e32 v80, v80
	v_rcp_f32_e32 v81, v81
	v_rcp_f32_e32 v84, v84
	v_rcp_f32_e32 v85, v85
	v_rcp_f32_e32 v86, v86
	v_rcp_f32_e32 v87, v87
	v_cvt_pk_bf16_f32 v68, v78, v79
	v_cvt_pk_bf16_f32 v69, v80, v81
	v_cvt_pk_bf16_f32 v70, v84, v85
	v_cvt_pk_bf16_f32 v71, v86, v87
	global_store_dwordx4 v[122:123], v[68:71], off offset:256
	s_nop 1
	v_mov_b32_e32 v68, v192
	v_mul_f32_e32 v72, v61, v68
	v_mul_f32_e32 v69, v64, v68
	v_mul_f32_e32 v70, v65, v68
	v_mul_f32_e32 v71, v60, v68
	v_mul_f32_e32 v73, v62, v68
	v_mul_f32_e32 v76, v63, v68
	v_mul_f32_e32 v77, v58, v68
	v_mul_f32_e32 v68, v59, v68
	v_mul_f32_e32 v53, v68, v53
	v_mul_f32_e32 v54, v69, v54
	v_mul_f32_e32 v55, v70, v55
	v_mul_f32_e32 v56, v71, v56
	v_mul_f32_e32 v57, v72, v57
	v_mul_f32_e32 v50, v73, v50
	v_mul_f32_e32 v51, v76, v51
	v_mul_f32_e32 v52, v77, v52
	v_exp_f32_e64 v77, -v53
	v_exp_f32_e64 v68, -v54
	v_exp_f32_e64 v69, -v55
	v_exp_f32_e64 v70, -v56
	v_exp_f32_e64 v71, -v57
	v_exp_f32_e64 v72, -v50
	v_exp_f32_e64 v73, -v51
	v_exp_f32_e64 v76, -v52
	v_add_f32_e32 v77, 1.0, v77
	v_add_f32_e32 v68, 1.0, v68
	v_add_f32_e32 v69, 1.0, v69
	v_add_f32_e32 v70, 1.0, v70
	v_add_f32_e32 v71, 1.0, v71
	v_add_f32_e32 v72, 1.0, v72
	v_add_f32_e32 v73, 1.0, v73
	v_add_f32_e32 v76, 1.0, v76
	v_rcp_f32_e32 v77, v77
	v_rcp_f32_e32 v68, v68
	v_rcp_f32_e32 v69, v69
	v_rcp_f32_e32 v70, v70
	v_rcp_f32_e32 v71, v71
	v_rcp_f32_e32 v72, v72
	v_rcp_f32_e32 v73, v73
	v_rcp_f32_e32 v76, v76
	v_cvt_pk_bf16_f32 v50, v68, v69
	v_cvt_pk_bf16_f32 v51, v70, v71
	v_cvt_pk_bf16_f32 v52, v72, v73
	v_cvt_pk_bf16_f32 v53, v76, v77
	global_store_dwordx4 v[114:115], v[50:53], off offset:256
	s_nop 1
	v_mov_b32_e32 v50, v194
	v_mul_f32_e32 v54, v61, v50
	v_mul_f32_e32 v51, v64, v50
	v_mul_f32_e32 v52, v65, v50
	v_mul_f32_e32 v53, v60, v50
	v_mul_f32_e32 v55, v62, v50
	v_mul_f32_e32 v56, v63, v50
	v_mul_f32_e32 v57, v58, v50
	v_mul_f32_e32 v50, v59, v50
	v_mul_f32_e32 v45, v50, v45
	v_mul_f32_e32 v46, v51, v46
	v_mul_f32_e32 v47, v52, v47
	v_mul_f32_e32 v48, v53, v48
	v_mul_f32_e32 v49, v54, v49
	v_mul_f32_e32 v42, v55, v42
	v_mul_f32_e32 v43, v56, v43
	v_mul_f32_e32 v44, v57, v44
	v_exp_f32_e64 v57, -v45
	v_exp_f32_e64 v50, -v46
	v_exp_f32_e64 v51, -v47
	v_exp_f32_e64 v52, -v48
	v_exp_f32_e64 v53, -v49
	v_exp_f32_e64 v54, -v42
	v_exp_f32_e64 v55, -v43
	v_exp_f32_e64 v56, -v44
	v_add_f32_e32 v57, 1.0, v57
	v_add_f32_e32 v50, 1.0, v50
	v_add_f32_e32 v51, 1.0, v51
	v_add_f32_e32 v52, 1.0, v52
	v_add_f32_e32 v53, 1.0, v53
	v_add_f32_e32 v54, 1.0, v54
	v_add_f32_e32 v55, 1.0, v55
	v_add_f32_e32 v56, 1.0, v56
	v_rcp_f32_e32 v57, v57
	v_rcp_f32_e32 v50, v50
	v_rcp_f32_e32 v51, v51
	v_rcp_f32_e32 v52, v52
	v_rcp_f32_e32 v53, v53
	v_rcp_f32_e32 v54, v54
	v_rcp_f32_e32 v55, v55
	v_rcp_f32_e32 v56, v56
	v_cvt_pk_bf16_f32 v42, v50, v51
	v_cvt_pk_bf16_f32 v43, v52, v53
	v_cvt_pk_bf16_f32 v44, v54, v55
	v_cvt_pk_bf16_f32 v45, v56, v57
	global_store_dwordx4 v[106:107], v[42:45], off offset:256
	s_nop 1
	v_mov_b32_e32 v42, v196
	v_mul_f32_e32 v46, v61, v42
	v_mul_f32_e32 v43, v64, v42
	v_mul_f32_e32 v44, v65, v42
	v_mul_f32_e32 v45, v60, v42
	v_mul_f32_e32 v47, v62, v42
	v_mul_f32_e32 v48, v63, v42
	v_mul_f32_e32 v49, v58, v42
	v_mul_f32_e32 v42, v59, v42
	v_mul_f32_e32 v37, v42, v37
	v_mul_f32_e32 v38, v43, v38
	v_mul_f32_e32 v39, v44, v39
	v_mul_f32_e32 v40, v45, v40
	v_mul_f32_e32 v41, v46, v41
	v_mul_f32_e32 v34, v47, v34
	v_mul_f32_e32 v35, v48, v35
	v_mul_f32_e32 v36, v49, v36
	v_exp_f32_e64 v49, -v37
	v_exp_f32_e64 v42, -v38
	v_exp_f32_e64 v43, -v39
	v_exp_f32_e64 v44, -v40
	v_exp_f32_e64 v45, -v41
	v_exp_f32_e64 v46, -v34
	v_exp_f32_e64 v47, -v35
	v_exp_f32_e64 v48, -v36
	v_add_f32_e32 v49, 1.0, v49
	v_add_f32_e32 v42, 1.0, v42
	v_add_f32_e32 v43, 1.0, v43
	v_add_f32_e32 v44, 1.0, v44
	v_add_f32_e32 v45, 1.0, v45
	v_add_f32_e32 v46, 1.0, v46
	v_add_f32_e32 v47, 1.0, v47
	v_add_f32_e32 v48, 1.0, v48
	v_rcp_f32_e32 v49, v49
	v_rcp_f32_e32 v42, v42
	v_rcp_f32_e32 v43, v43
	v_rcp_f32_e32 v44, v44
	v_rcp_f32_e32 v45, v45
	v_rcp_f32_e32 v46, v46
	v_rcp_f32_e32 v47, v47
	v_rcp_f32_e32 v48, v48
	v_cvt_pk_bf16_f32 v34, v42, v43
	v_cvt_pk_bf16_f32 v35, v44, v45
	v_cvt_pk_bf16_f32 v36, v46, v47
	v_cvt_pk_bf16_f32 v37, v48, v49
	global_store_dwordx4 v[98:99], v[34:37], off offset:256
	s_nop 1
	v_mov_b32_e32 v34, v198
	v_mul_f32_e32 v38, v61, v34
	v_mul_f32_e32 v35, v64, v34
	v_mul_f32_e32 v36, v65, v34
	v_mul_f32_e32 v37, v60, v34
	v_mul_f32_e32 v39, v62, v34
	v_mul_f32_e32 v40, v63, v34
	v_mul_f32_e32 v41, v58, v34
	v_mul_f32_e32 v34, v59, v34
	v_mul_f32_e32 v29, v34, v29
	v_mul_f32_e32 v30, v35, v30
	v_mul_f32_e32 v31, v36, v31
	v_mul_f32_e32 v32, v37, v32
	v_mul_f32_e32 v33, v38, v33
	v_mul_f32_e32 v26, v39, v26
	v_mul_f32_e32 v27, v40, v27
	v_mul_f32_e32 v28, v41, v28
	v_exp_f32_e64 v41, -v29
	v_exp_f32_e64 v34, -v30
	v_exp_f32_e64 v35, -v31
	v_exp_f32_e64 v36, -v32
	v_exp_f32_e64 v37, -v33
	v_exp_f32_e64 v38, -v26
	v_exp_f32_e64 v39, -v27
	v_exp_f32_e64 v40, -v28
	v_add_f32_e32 v41, 1.0, v41
	v_add_f32_e32 v34, 1.0, v34
	v_add_f32_e32 v35, 1.0, v35
	v_add_f32_e32 v36, 1.0, v36
	v_add_f32_e32 v37, 1.0, v37
	v_add_f32_e32 v38, 1.0, v38
	v_add_f32_e32 v39, 1.0, v39
	v_add_f32_e32 v40, 1.0, v40
	v_rcp_f32_e32 v41, v41
	v_rcp_f32_e32 v34, v34
	v_rcp_f32_e32 v35, v35
	v_rcp_f32_e32 v36, v36
	v_rcp_f32_e32 v37, v37
	v_rcp_f32_e32 v38, v38
	v_rcp_f32_e32 v39, v39
	v_rcp_f32_e32 v40, v40
	v_cvt_pk_bf16_f32 v26, v34, v35
	v_cvt_pk_bf16_f32 v27, v36, v37
	v_cvt_pk_bf16_f32 v28, v38, v39
	v_cvt_pk_bf16_f32 v29, v40, v41
	global_store_dwordx4 v[90:91], v[26:29], off offset:256
	s_nop 1
	v_mov_b32_e32 v26, v200
	v_mul_f32_e32 v30, v61, v26
	v_mul_f32_e32 v27, v64, v26
	v_mul_f32_e32 v28, v65, v26
	v_mul_f32_e32 v29, v60, v26
	v_mul_f32_e32 v31, v62, v26
	v_mul_f32_e32 v32, v63, v26
	v_mul_f32_e32 v33, v58, v26
	v_mul_f32_e32 v26, v59, v26
	v_mul_f32_e32 v21, v26, v21
	v_mul_f32_e32 v22, v27, v22
	v_mul_f32_e32 v23, v28, v23
	v_mul_f32_e32 v24, v29, v24
	v_mul_f32_e32 v25, v30, v25
	v_mul_f32_e32 v18, v31, v18
	v_mul_f32_e32 v19, v32, v19
	v_mul_f32_e32 v20, v33, v20
	v_exp_f32_e64 v33, -v21
	v_exp_f32_e64 v26, -v22
	v_exp_f32_e64 v27, -v23
	v_exp_f32_e64 v28, -v24
	v_exp_f32_e64 v29, -v25
	v_exp_f32_e64 v30, -v18
	v_exp_f32_e64 v31, -v19
	v_exp_f32_e64 v32, -v20
	v_add_f32_e32 v33, 1.0, v33
	v_add_f32_e32 v26, 1.0, v26
	v_add_f32_e32 v27, 1.0, v27
	v_add_f32_e32 v28, 1.0, v28
	v_add_f32_e32 v29, 1.0, v29
	v_add_f32_e32 v30, 1.0, v30
	v_add_f32_e32 v31, 1.0, v31
	v_add_f32_e32 v32, 1.0, v32
	v_rcp_f32_e32 v33, v33
	v_rcp_f32_e32 v26, v26
	v_rcp_f32_e32 v27, v27
	v_rcp_f32_e32 v28, v28
	v_rcp_f32_e32 v29, v29
	v_rcp_f32_e32 v30, v30
	v_rcp_f32_e32 v31, v31
	v_rcp_f32_e32 v32, v32
	v_cvt_pk_bf16_f32 v18, v26, v27
	v_cvt_pk_bf16_f32 v19, v28, v29
	v_cvt_pk_bf16_f32 v20, v30, v31
	v_cvt_pk_bf16_f32 v21, v32, v33
	global_store_dwordx4 v[82:83], v[18:21], off offset:256
	s_nop 1
	v_mov_b32_e32 v18, v202
	v_mul_f32_e32 v22, v61, v18
	v_mul_f32_e32 v19, v64, v18
	v_mul_f32_e32 v20, v65, v18
	v_mul_f32_e32 v21, v60, v18
	v_mul_f32_e32 v23, v62, v18
	v_mul_f32_e32 v24, v63, v18
	v_mul_f32_e32 v25, v58, v18
	v_mul_f32_e32 v18, v59, v18
	v_mul_f32_e32 v13, v18, v13
	v_mul_f32_e32 v14, v19, v14
	v_mul_f32_e32 v15, v20, v15
	v_mul_f32_e32 v16, v21, v16
	v_mul_f32_e32 v17, v22, v17
	v_mul_f32_e32 v10, v23, v10
	v_mul_f32_e32 v11, v24, v11
	v_mul_f32_e32 v12, v25, v12
	v_exp_f32_e64 v25, -v13
	v_exp_f32_e64 v18, -v14
	v_exp_f32_e64 v19, -v15
	v_exp_f32_e64 v20, -v16
	v_exp_f32_e64 v21, -v17
	v_exp_f32_e64 v22, -v10
	v_exp_f32_e64 v23, -v11
	v_exp_f32_e64 v24, -v12
	v_add_f32_e32 v25, 1.0, v25
	v_add_f32_e32 v18, 1.0, v18
	v_add_f32_e32 v19, 1.0, v19
	v_add_f32_e32 v20, 1.0, v20
	v_add_f32_e32 v21, 1.0, v21
	v_add_f32_e32 v22, 1.0, v22
	v_add_f32_e32 v23, 1.0, v23
	v_add_f32_e32 v24, 1.0, v24
	v_rcp_f32_e32 v25, v25
	v_rcp_f32_e32 v18, v18
	v_rcp_f32_e32 v19, v19
	v_rcp_f32_e32 v20, v20
	v_rcp_f32_e32 v21, v21
	v_rcp_f32_e32 v22, v22
	v_rcp_f32_e32 v23, v23
	v_rcp_f32_e32 v24, v24
	v_cvt_pk_bf16_f32 v10, v18, v19
	v_cvt_pk_bf16_f32 v11, v20, v21
	v_cvt_pk_bf16_f32 v12, v22, v23
	v_cvt_pk_bf16_f32 v13, v24, v25
	global_store_dwordx4 v[74:75], v[10:13], off offset:256
	s_nop 1
	v_mov_b32_e32 v10, v204
	v_mul_f32_e32 v14, v61, v10
	v_mul_f32_e32 v11, v64, v10
	v_mul_f32_e32 v12, v65, v10
	v_mul_f32_e32 v13, v60, v10
	v_mul_f32_e32 v15, v62, v10
	v_mul_f32_e32 v16, v63, v10
	v_mul_f32_e32 v17, v58, v10
	v_mul_f32_e32 v10, v59, v10
	v_mul_f32_e32 v5, v10, v5
	v_mul_f32_e32 v6, v11, v6
	v_mul_f32_e32 v7, v12, v7
	v_mul_f32_e32 v8, v13, v8
	v_mul_f32_e32 v9, v14, v9
	v_mul_f32_e32 v2, v15, v2
	v_mul_f32_e32 v3, v16, v3
	v_mul_f32_e32 v4, v17, v4
	v_exp_f32_e64 v17, -v5
	v_exp_f32_e64 v10, -v6
	v_exp_f32_e64 v11, -v7
	v_exp_f32_e64 v12, -v8
	v_exp_f32_e64 v13, -v9
	v_exp_f32_e64 v14, -v2
	v_exp_f32_e64 v15, -v3
	v_exp_f32_e64 v16, -v4
	v_add_f32_e32 v17, 1.0, v17
	v_add_f32_e32 v10, 1.0, v10
	v_add_f32_e32 v11, 1.0, v11
	v_add_f32_e32 v12, 1.0, v12
	v_add_f32_e32 v13, 1.0, v13
	v_add_f32_e32 v14, 1.0, v14
	v_add_f32_e32 v15, 1.0, v15
	v_add_f32_e32 v16, 1.0, v16
	v_rcp_f32_e32 v17, v17
	v_rcp_f32_e32 v10, v10
	v_rcp_f32_e32 v11, v11
	v_rcp_f32_e32 v12, v12
	v_rcp_f32_e32 v13, v13
	v_rcp_f32_e32 v14, v14
	v_rcp_f32_e32 v15, v15
	v_rcp_f32_e32 v16, v16
	v_cvt_pk_bf16_f32 v2, v10, v11
	v_cvt_pk_bf16_f32 v3, v12, v13
	v_cvt_pk_bf16_f32 v4, v14, v15
	v_cvt_pk_bf16_f32 v5, v16, v17
	global_store_dwordx4 v[66:67], v[2:5], off offset:256
	s_cbranch_vccnz .LBB0_600
	s_andn2_b64 vcc, exec, s[10:11]
	s_cbranch_vccnz .LBB0_599
	s_barrier
	s_branch .LBB0_599

.LBB0_1106:
	v_mov_b32_e32 v156, v0
	s_lshl_b32 s0, s48, 8
	v_lshrrev_b32_e32 v130, 1, v156
	v_and_b32_e32 v130, 0x78, v130
	v_lshl_or_b32 v154, s80, 8, v130
	v_ashrrev_i32_e32 v155, 31, v154
	v_lshl_add_u64 v[152:153], v[154:155], 2, s[18:19]
	global_load_dwordx4 v[134:137], v[152:153], off
	global_load_dwordx4 v[130:133], v[152:153], off offset:16
	v_ashrrev_i32_e32 v157, 2, v156
	v_and_or_b32 v156, v156, 15, s0
	v_and_b32_e32 v157, 0xffffffc0, v157
	v_add_u32_e32 v156, v156, v157
	v_ashrrev_i32_e32 v157, 31, v156
	v_or_b32_e32 v158, 16, v156
	v_or_b32_e32 v160, 32, v156
	v_or_b32_e32 v164, 48, v156
	v_lshlrev_b64 v[156:157], 11, v[156:157]
	v_ashrrev_i32_e32 v159, 31, v158
	v_ashrrev_i32_e32 v161, 31, v160
	v_lshlrev_b64 v[154:155], 1, v[154:155]
	v_lshl_add_u64 v[156:157], s[10:11], 0, v[156:157]
	v_lshlrev_b64 v[158:159], 11, v[158:159]
	v_lshlrev_b64 v[166:167], 11, v[160:161]
	v_ashrrev_i32_e32 v165, 31, v164
	v_lshl_add_u64 v[160:161], v[156:157], 0, v[154:155]
	v_lshl_add_u64 v[156:157], s[10:11], 0, v[158:159]
	v_lshl_add_u64 v[166:167], s[10:11], 0, v[166:167]
	v_lshlrev_b64 v[164:165], 11, v[164:165]
	v_lshl_add_u64 v[158:159], v[156:157], 0, v[154:155]
	v_lshl_add_u64 v[156:157], v[166:167], 0, v[154:155]
	s_mov_b32 s1, 0x40000
	v_lshl_add_u64 v[164:165], s[10:11], 0, v[164:165]
	v_lshl_add_u64 v[154:155], v[164:165], 0, v[154:155]
	v_add_co_u32_e32 v164, vcc, s1, v160
	s_mov_b32 s45, 0x48000
	s_nop 0
	v_addc_co_u32_e32 v165, vcc, 0, v161, vcc
	s_mov_b32 s0, 0x50000
	s_mov_b64 s[50:51], 0x48000
	s_mov_b64 s[52:53], 0x50000
	s_mov_b64 s[54:55], 0x58000
	s_cmp_lg_u64 s[42:43], 0
	s_cbranch_scc0 .Lalb_6
	s_barrier
.Lalb_6:
	s_waitcnt vmcnt(0)
	v_pk_mul_f32 v[126:127], v[126:127], v[134:135]
	v_pk_mul_f32 v[168:169], v[82:83], v[130:131]
	v_cvt_pk_bf16_f32 v82, v126, v127
	v_pk_mul_f32 v[128:129], v[128:129], v[136:137]
	v_pk_mul_f32 v[124:125], v[124:125], v[132:133]
	v_pk_mul_f32 v[122:123], v[122:123], v[130:131]
	v_pk_mul_f32 v[118:119], v[118:119], v[134:135]
	v_pk_mul_f32 v[166:167], v[84:85], v[132:133]
	v_cvt_pk_bf16_f32 v83, v128, v129
	v_cvt_pk_bf16_f32 v84, v122, v123
	v_cvt_pk_bf16_f32 v85, v124, v125
	global_store_dwordx4 v[160:161], v[82:85], off
	v_pk_mul_f32 v[120:121], v[120:121], v[136:137]
	v_pk_mul_f32 v[116:117], v[116:117], v[132:133]
	v_cvt_pk_bf16_f32 v82, v118, v119
	v_pk_mul_f32 v[114:115], v[114:115], v[130:131]
	v_pk_mul_f32 v[110:111], v[110:111], v[134:135]
	v_cvt_pk_bf16_f32 v83, v120, v121
	v_cvt_pk_bf16_f32 v84, v114, v115
	v_cvt_pk_bf16_f32 v85, v116, v117
	global_store_dwordx4 v[158:159], v[82:85], off
	v_pk_mul_f32 v[112:113], v[112:113], v[136:137]
	v_pk_mul_f32 v[108:109], v[108:109], v[132:133]
	v_cvt_pk_bf16_f32 v82, v110, v111
	v_pk_mul_f32 v[106:107], v[106:107], v[130:131]
	v_pk_mul_f32 v[102:103], v[102:103], v[134:135]
	v_cvt_pk_bf16_f32 v83, v112, v113
	v_cvt_pk_bf16_f32 v84, v106, v107
	v_cvt_pk_bf16_f32 v85, v108, v109
	global_store_dwordx4 v[156:157], v[82:85], off
	v_pk_mul_f32 v[104:105], v[104:105], v[136:137]
	v_pk_mul_f32 v[100:101], v[100:101], v[132:133]
	v_cvt_pk_bf16_f32 v82, v102, v103
	v_pk_mul_f32 v[98:99], v[98:99], v[130:131]
	v_pk_mul_f32 v[94:95], v[94:95], v[134:135]
	v_pk_mul_f32 v[86:87], v[86:87], v[134:135]
	v_cvt_pk_bf16_f32 v83, v104, v105
	v_cvt_pk_bf16_f32 v84, v98, v99
	v_cvt_pk_bf16_f32 v85, v100, v101
	global_store_dwordx4 v[154:155], v[82:85], off
	v_pk_mul_f32 v[96:97], v[96:97], v[136:137]
	v_pk_mul_f32 v[92:93], v[92:93], v[132:133]
	v_cvt_pk_bf16_f32 v82, v94, v95
	v_pk_mul_f32 v[90:91], v[90:91], v[130:131]
	v_cvt_pk_bf16_f32 v83, v96, v97
	v_pk_mul_f32 v[88:89], v[88:89], v[136:137]
	v_cvt_pk_bf16_f32 v84, v90, v91
	v_cvt_pk_bf16_f32 v85, v92, v93
	global_store_dwordx4 v[164:165], v[82:85], off
	v_pk_mul_f32 v[78:79], v[78:79], v[134:135]
	v_pk_mul_f32 v[80:81], v[80:81], v[136:137]
	v_cvt_pk_bf16_f32 v82, v86, v87
	v_add_co_u32_e32 v86, vcc, s45, v160
	v_cvt_pk_bf16_f32 v83, v88, v89
	v_cvt_pk_bf16_f32 v84, v168, v169
	v_cvt_pk_bf16_f32 v85, v166, v167
	v_pk_mul_f32 v[62:63], v[62:63], v[134:135]
	s_nop 0
	v_addc_co_u32_e32 v87, vcc, 0, v161, vcc
	global_store_dwordx4 v[86:87], v[82:85], off
	v_pk_mul_f32 v[64:65], v[64:65], v[136:137]
	s_nop 0
	v_pk_mul_f32 v[82:83], v[76:77], v[132:133]
	v_pk_mul_f32 v[76:77], v[74:75], v[130:131]
	v_cvt_pk_bf16_f32 v74, v78, v79
	v_add_co_u32_e32 v78, vcc, s0, v160
	v_cvt_pk_bf16_f32 v75, v80, v81
	s_mov_b32 s0, 0x58000
	s_nop 0
	v_addc_co_u32_e32 v79, vcc, 0, v161, vcc
	v_cvt_pk_bf16_f32 v76, v76, v77
	v_cvt_pk_bf16_f32 v77, v82, v83
	global_store_dwordx4 v[78:79], v[74:77], off
	v_lshl_add_u64 v[78:79], v[160:161], 0, s[52:53]
	v_lshl_add_u64 v[80:81], v[160:161], 0, s[54:55]
	v_pk_mul_f32 v[74:75], v[60:61], v[132:133]
	v_pk_mul_f32 v[60:61], v[58:59], v[130:131]
	v_cvt_pk_bf16_f32 v58, v62, v63
	v_add_co_u32_e32 v62, vcc, s0, v160
	v_cvt_pk_bf16_f32 v59, v64, v65
	v_cvt_pk_bf16_f32 v60, v60, v61
	v_cvt_pk_bf16_f32 v61, v74, v75
	s_mov_b64 s[0:1], 0x40000
	s_nop 0
	v_addc_co_u32_e32 v63, vcc, 0, v161, vcc
	global_store_dwordx4 v[62:63], v[58:61], off
	global_load_dwordx4 v[58:61], v[152:153], off offset:512
	s_nop 0
	global_load_dwordx4 v[62:65], v[152:153], off offset:528
	v_lshl_add_u64 v[74:75], v[160:161], 0, s[0:1]
	v_lshl_add_u64 v[76:77], v[160:161], 0, s[50:51]
	s_and_b64 vcc, exec, s[4:5]
	s_mov_b64 s[0:1], -1
	s_waitcnt vmcnt(1)
	v_pk_mul_f32 v[72:73], v[72:73], v[60:61]
	v_pk_mul_f32 v[70:71], v[70:71], v[58:59]
	s_waitcnt vmcnt(0)
	v_pk_mul_f32 v[84:85], v[12:13], v[64:65]
	v_cvt_pk_bf16_f32 v12, v70, v71
	v_cvt_pk_bf16_f32 v13, v72, v73
	v_pk_mul_f32 v[68:69], v[68:69], v[64:65]
	v_pk_mul_f32 v[66:67], v[66:67], v[62:63]
	v_pk_mul_f32 v[56:57], v[56:57], v[60:61]
	v_pk_mul_f32 v[54:55], v[54:55], v[58:59]
	v_pk_mul_f32 v[82:83], v[14:15], v[58:59]
	v_cvt_pk_bf16_f32 v14, v66, v67
	v_cvt_pk_bf16_f32 v15, v68, v69
	global_store_dwordx4 v[160:161], v[12:15], off offset:256
	v_pk_mul_f32 v[52:53], v[52:53], v[64:65]
	v_pk_mul_f32 v[50:51], v[50:51], v[62:63]
	v_cvt_pk_bf16_f32 v12, v54, v55
	v_cvt_pk_bf16_f32 v13, v56, v57
	v_pk_mul_f32 v[48:49], v[48:49], v[60:61]
	v_pk_mul_f32 v[46:47], v[46:47], v[58:59]
	v_cvt_pk_bf16_f32 v14, v50, v51
	v_cvt_pk_bf16_f32 v15, v52, v53
	global_store_dwordx4 v[158:159], v[12:15], off offset:256
	v_pk_mul_f32 v[44:45], v[44:45], v[64:65]
	v_pk_mul_f32 v[42:43], v[42:43], v[62:63]
	v_cvt_pk_bf16_f32 v12, v46, v47
	v_cvt_pk_bf16_f32 v13, v48, v49
	v_pk_mul_f32 v[40:41], v[40:41], v[60:61]
	v_pk_mul_f32 v[38:39], v[38:39], v[58:59]
	v_cvt_pk_bf16_f32 v14, v42, v43
	v_cvt_pk_bf16_f32 v15, v44, v45
	global_store_dwordx4 v[156:157], v[12:15], off offset:256
	v_pk_mul_f32 v[36:37], v[36:37], v[64:65]
	v_pk_mul_f32 v[34:35], v[34:35], v[62:63]
	v_cvt_pk_bf16_f32 v12, v38, v39
	v_cvt_pk_bf16_f32 v13, v40, v41
	v_pk_mul_f32 v[32:33], v[32:33], v[60:61]
	v_pk_mul_f32 v[30:31], v[30:31], v[58:59]
	v_cvt_pk_bf16_f32 v14, v34, v35
	v_cvt_pk_bf16_f32 v15, v36, v37
	global_store_dwordx4 v[154:155], v[12:15], off offset:256
	v_pk_mul_f32 v[28:29], v[28:29], v[64:65]
	v_pk_mul_f32 v[26:27], v[26:27], v[62:63]
	v_cvt_pk_bf16_f32 v12, v30, v31
	v_cvt_pk_bf16_f32 v13, v32, v33
	v_pk_mul_f32 v[24:25], v[24:25], v[60:61]
	v_pk_mul_f32 v[22:23], v[22:23], v[58:59]
	v_cvt_pk_bf16_f32 v14, v26, v27
	v_cvt_pk_bf16_f32 v15, v28, v29
	global_store_dwordx4 v[74:75], v[12:15], off offset:256
	v_pk_mul_f32 v[20:21], v[20:21], v[64:65]
	v_pk_mul_f32 v[18:19], v[18:19], v[62:63]
	v_cvt_pk_bf16_f32 v12, v22, v23
	v_cvt_pk_bf16_f32 v13, v24, v25
	v_pk_mul_f32 v[16:17], v[16:17], v[60:61]
	v_cvt_pk_bf16_f32 v14, v18, v19
	v_cvt_pk_bf16_f32 v15, v20, v21
	global_store_dwordx4 v[76:77], v[12:15], off offset:256
	v_pk_mul_f32 v[8:9], v[8:9], v[60:61]
	v_pk_mul_f32 v[6:7], v[6:7], v[58:59]
	v_pk_mul_f32 v[12:13], v[10:11], v[62:63]
	v_cvt_pk_bf16_f32 v10, v82, v83
	v_cvt_pk_bf16_f32 v11, v16, v17
	s_nop 0
	v_cvt_pk_bf16_f32 v12, v12, v13
	v_cvt_pk_bf16_f32 v13, v84, v85
	global_store_dwordx4 v[78:79], v[10:13], off offset:256
	s_nop 1
	v_pk_mul_f32 v[10:11], v[4:5], v[64:65]
	v_pk_mul_f32 v[4:5], v[2:3], v[62:63]
	v_cvt_pk_bf16_f32 v2, v6, v7
	v_cvt_pk_bf16_f32 v3, v8, v9
	s_nop 0
	v_cvt_pk_bf16_f32 v4, v4, v5
	v_cvt_pk_bf16_f32 v5, v10, v11
	global_store_dwordx4 v[80:81], v[2:5], off offset:256
	s_cbranch_vccnz .LBB0_1093
	s_andn2_b64 vcc, exec, s[20:21]
	s_cbranch_vccnz .LBB0_1092
	s_barrier
	s_branch .LBB0_1092

.LBB0_1433:
.LBB0_1435:
	v_lshl_or_b32 v170, s77, 7, v156
	v_ashrrev_i32_e32 v171, 31, v170
	v_lshlrev_b64 v[148:149], 2, v[170:171]
	v_lshl_add_u64 v[150:151], s[20:21], 0, v[148:149]
	v_lshl_add_u64 v[148:149], s[24:25], 0, v[148:149]
	global_load_dwordx4 v[152:155], v[150:151], off
	global_load_dwordx4 v[158:161], v[148:149], off
	global_load_dwordx4 v[162:165], v[150:151], off offset:16
	global_load_dwordx4 v[166:169], v[148:149], off offset:16
	v_lshl_add_u32 v148, s52, 8, v1
	v_ashrrev_i32_e32 v149, 31, v148
	v_lshl_add_u64 v[150:151], v[148:149], 2, s[26:27]
	global_load_dword v172, v[150:151], off
	global_load_dword v192, v[150:151], off offset:64
	global_load_dword v194, v[150:151], off offset:128
	global_load_dword v196, v[150:151], off offset:192
	global_load_dword v198, v[150:151], off offset:512
	global_load_dword v200, v[150:151], off offset:576
	global_load_dword v202, v[150:151], off offset:640
	global_load_dword v204, v[150:151], off offset:704
	v_cvt_f32_i32_e32 v175, v126
	v_cvt_f32_i32_e32 v174, v122
	v_cvt_f32_i32_e32 v177, v127
	v_cvt_f32_i32_e32 v176, v123
	v_cvt_f32_i32_e32 v179, v128
	v_cvt_f32_i32_e32 v178, v124
	v_cvt_f32_i32_e32 v180, v125
	v_cvt_f32_i32_e32 v187, v120
	v_cvt_f32_i32_e32 v189, v121
	v_cvt_f32_i32_e32 v181, v129
	v_cvt_f32_i32_e32 v183, v118
	v_cvt_f32_i32_e32 v182, v114
	v_cvt_f32_i32_e32 v185, v119
	v_cvt_f32_i32_e32 v184, v115
	v_cvt_f32_i32_e32 v186, v116
	v_cvt_f32_i32_e32 v188, v117
	v_cvt_f32_i32_e32 v111, v111
	v_cvt_f32_i32_e32 v103, v103
	v_cvt_f32_i32_e32 v113, v113
	v_cvt_f32_i32_e32 v105, v105
	v_cvt_f32_i32_e32 v95, v95
	v_cvt_f32_i32_e32 v87, v87
	v_cvt_f32_i32_e32 v97, v97
	v_cvt_f32_i32_e32 v89, v89
	v_cvt_f32_i32_e32 v79, v79
	v_cvt_f32_i32_e32 v71, v71
	v_cvt_f32_i32_e32 v81, v81
	v_cvt_f32_i32_e32 v73, v73
	v_cvt_f32_i32_e32 v63, v63
	v_cvt_f32_i32_e32 v55, v55
	v_cvt_f32_i32_e32 v65, v65
	v_cvt_f32_i32_e32 v57, v57
	v_cvt_f32_i32_e32 v47, v47
	v_cvt_f32_i32_e32 v49, v49
	v_cvt_f32_i32_e32 v39, v39
	v_cvt_f32_i32_e32 v41, v41
	v_cvt_f32_i32_e32 v31, v31
	v_cvt_f32_i32_e32 v33, v33
	v_cvt_f32_i32_e32 v23, v23
	v_cvt_f32_i32_e32 v25, v25
	v_cvt_f32_i32_e32 v15, v15
	v_cvt_f32_i32_e32 v17, v17
	v_cvt_f32_i32_e32 v7, v7
	v_cvt_f32_i32_e32 v9, v9
	s_cmp_lg_u64 s[44:45], 0
	s_cbranch_scc0 .Lalb_7
	s_barrier
.Lalb_7:
	s_andn2_b64 vcc, exec, s[6:7]
	s_waitcnt vmcnt(0)
	s_mov_b32 s98, 0x3c3a1e78
	s_mov_b32 s100, 0x3bb2d7c8
	v_pk_mul_f32 v[124:125], v[158:159], s[100:101] op_sel_hi:[1,0]
	v_pk_mul_f32 v[120:121], v[152:153], s[98:99] op_sel_hi:[1,0]
	v_pk_mul_f32 v[116:117], v[154:155], s[98:99] op_sel_hi:[1,0]
	v_pk_mul_f32 v[126:127], v[160:161], s[100:101] op_sel_hi:[1,0]
	v_pk_mul_f32 v[114:115], v[164:165], s[98:99] op_sel_hi:[1,0]
	v_pk_mul_f32 v[118:119], v[162:163], s[98:99] op_sel_hi:[1,0]
	v_pk_mul_f32 v[152:153], v[168:169], s[100:101] op_sel_hi:[1,0]
	v_pk_mul_f32 v[128:129], v[166:167], s[100:101] op_sel_hi:[1,0]
	v_mov_b32_e32 v122, v124
	v_mov_b32_e32 v123, v120
	v_mov_b32_e32 v120, v125
	v_mov_b32_e32 v124, v126
	v_mov_b32_e32 v125, v116
	v_mov_b32_e32 v116, v127
	v_mov_b32_e32 v126, v128
	v_mov_b32_e32 v127, v118
	v_mov_b32_e32 v118, v129
	v_mov_b32_e32 v128, v152
	v_mov_b32_e32 v129, v114
	v_mov_b32_e32 v114, v153
	v_pk_mul_f32 v[152:153], v[122:123], v[172:173] op_sel_hi:[1,0]
	v_pk_mul_f32 v[154:155], v[120:121], v[172:173] op_sel_hi:[1,0]
	v_pk_mul_f32 v[158:159], v[124:125], v[172:173] op_sel_hi:[1,0]
	v_pk_mul_f32 v[152:153], v[152:153], v[174:175]
	v_pk_mul_f32 v[154:155], v[154:155], v[176:177]
	v_pk_mul_f32 v[160:161], v[116:117], v[172:173] op_sel_hi:[1,0]
	v_pk_mul_f32 v[162:163], v[172:173], v[126:127] op_sel_hi:[0,1]
	v_pk_mul_f32 v[164:165], v[172:173], v[118:119] op_sel_hi:[0,1]
	v_pk_mul_f32 v[166:167], v[172:173], v[128:129] op_sel_hi:[0,1]
	v_pk_mul_f32 v[168:169], v[172:173], v[114:115] op_sel_hi:[0,1]
	v_pk_mul_f32 v[158:159], v[158:159], v[178:179]
	v_exp_f32_e64 v149, -v153
	v_exp_f32_e64 v172, -v155
	v_exp_f32_e64 v173, -v159
	v_pk_mul_f32 v[160:161], v[160:161], v[180:181]
	v_add_f32_e32 v149, 1.0, v149
	v_add_f32_e32 v172, 1.0, v172
	v_pk_mul_f32 v[162:163], v[162:163], v[182:183]
	v_add_f32_e32 v173, 1.0, v173
	v_rcp_f32_e32 v149, v149
	v_rcp_f32_e32 v172, v172
	v_rcp_f32_e32 v173, v173
	v_exp_f32_e64 v174, -v161
	v_exp_f32_e64 v175, -v163
	v_mul_f32_e32 v149, v153, v149
	v_mul_f32_e32 v153, v155, v172
	v_pk_mul_f32 v[164:165], v[164:165], v[184:185]
	v_mul_f32_e32 v155, v159, v173
	v_mul_f32_e32 v149, v152, v149
	v_mul_f32_e32 v154, v154, v153
	v_pk_mul_f32 v[152:153], v[168:169], v[188:189]
	v_pk_mul_f32 v[166:167], v[166:167], v[186:187]
	v_add_f32_e32 v174, 1.0, v174
	v_add_f32_e32 v175, 1.0, v175
	v_mul_f32_e32 v155, v158, v155
	v_exp_f32_e64 v176, -v165
	v_rcp_f32_e32 v174, v174
	v_rcp_f32_e32 v175, v175
	v_exp_f32_e64 v158, -v153
	v_exp_f32_e64 v177, -v167
	v_add_f32_e32 v176, 1.0, v176
	v_mul_f32_e32 v159, v161, v174
	v_mul_f32_e32 v161, v163, v175
	v_add_f32_e32 v158, 1.0, v158
	v_rcp_f32_e32 v176, v176
	v_mul_f32_e32 v159, v160, v159
	v_mul_f32_e32 v160, v162, v161
	v_add_f32_e32 v162, 1.0, v177
	v_rcp_f32_e32 v158, v158
	v_rcp_f32_e32 v162, v162
	v_mul_f32_e32 v161, v165, v176
	v_mul_f32_e32 v161, v164, v161
	v_mul_f32_e32 v153, v153, v158
	v_mul_f32_e32 v162, v167, v162
	v_mul_f32_e32 v152, v152, v153
	v_mul_f32_e32 v162, v166, v162
	v_cvt_pk_bf16_f32 v158, v149, v154
	v_cvt_pk_bf16_f32 v159, v155, v159
	v_cvt_pk_bf16_f32 v160, v160, v161
	v_cvt_pk_bf16_f32 v161, v162, v152
	v_mov_b64_e32 v[152:153], s[36:37]
	v_mad_i64_i32 v[162:163], s[0:1], v148, s76, v[152:153]
	v_lshlrev_b64 v[154:155], 1, v[170:171]
	v_lshl_add_u64 v[162:163], v[162:163], 0, v[154:155]
	global_store_dwordx4 v[162:163], v[158:161], off
	v_cvt_f32_i32_e32 v163, v110
	v_cvt_f32_i32_e32 v162, v106
	v_or_b32_e32 v158, 16, v148
	v_ashrrev_i32_e32 v159, 31, v158
	v_lshl_add_u64 v[160:161], v[158:159], 2, s[26:27]
	s_nop 1
	v_cvt_f32_i32_e32 v110, v107
	v_cvt_f32_i32_e32 v107, v112
	v_cvt_f32_i32_e32 v106, v108
	v_cvt_f32_i32_e32 v112, v109
	v_cvt_f32_i32_e32 v109, v102
	v_cvt_f32_i32_e32 v108, v98
	v_cvt_f32_i32_e32 v102, v99
	v_cvt_f32_i32_e32 v99, v104
	v_cvt_f32_i32_e32 v98, v100
	v_cvt_f32_i32_e32 v104, v101
	v_mov_b32_e32 v160, v192
	v_pk_mul_f32 v[170:171], v[126:127], v[160:161] op_sel_hi:[1,0]
	v_pk_mul_f32 v[100:101], v[122:123], v[160:161] op_sel_hi:[1,0]
	v_pk_mul_f32 v[108:109], v[170:171], v[108:109]
	v_pk_mul_f32 v[100:101], v[100:101], v[162:163]
	v_pk_mul_f32 v[164:165], v[120:121], v[160:161] op_sel_hi:[1,0]
	v_exp_f32_e64 v162, -v109
	v_pk_mul_f32 v[110:111], v[164:165], v[110:111]
	v_exp_f32_e64 v149, -v101
	v_exp_f32_e64 v159, -v111
	v_add_f32_e32 v162, 1.0, v162
	v_rcp_f32_e32 v162, v162
	v_pk_mul_f32 v[172:173], v[118:119], v[160:161] op_sel_hi:[1,0]
	v_pk_mul_f32 v[174:175], v[128:129], v[160:161] op_sel_hi:[1,0]
	v_pk_mul_f32 v[166:167], v[124:125], v[160:161] op_sel_hi:[1,0]
	v_pk_mul_f32 v[168:169], v[116:117], v[160:161] op_sel_hi:[1,0]
	v_pk_mul_f32 v[160:161], v[114:115], v[160:161] op_sel_hi:[1,0]
	v_pk_mul_f32 v[102:103], v[172:173], v[102:103]
	v_pk_mul_f32 v[98:99], v[174:175], v[98:99]
	v_add_f32_e32 v149, 1.0, v149
	v_add_f32_e32 v159, 1.0, v159
	v_pk_mul_f32 v[106:107], v[166:167], v[106:107]
	v_pk_mul_f32 v[112:113], v[168:169], v[112:113]
	v_pk_mul_f32 v[104:105], v[160:161], v[104:105]
	v_rcp_f32_e32 v149, v149
	v_rcp_f32_e32 v159, v159
	v_exp_f32_e64 v163, -v103
	v_exp_f32_e64 v164, -v99
	v_mul_f32_e32 v109, v109, v162
	v_exp_f32_e64 v160, -v107
	v_exp_f32_e64 v161, -v113
	v_mul_f32_e32 v108, v108, v109
	v_exp_f32_e64 v109, -v105
	v_mul_f32_e32 v101, v101, v149
	v_mul_f32_e32 v111, v111, v159
	v_add_f32_e32 v163, 1.0, v163
	v_mul_f32_e32 v100, v100, v101
	v_mul_f32_e32 v101, v110, v111
	v_add_f32_e32 v110, 1.0, v164
	v_add_f32_e32 v160, 1.0, v160
	v_add_f32_e32 v161, 1.0, v161
	v_rcp_f32_e32 v163, v163
	v_rcp_f32_e32 v110, v110
	v_add_f32_e32 v109, 1.0, v109
	v_rcp_f32_e32 v160, v160
	v_rcp_f32_e32 v161, v161
	v_rcp_f32_e32 v109, v109
	v_mul_f32_e32 v103, v103, v163
	v_mul_f32_e32 v99, v99, v110
	v_mul_f32_e32 v107, v107, v160
	v_mul_f32_e32 v113, v113, v161
	v_mul_f32_e32 v102, v102, v103
	v_mul_f32_e32 v103, v98, v99
	v_mul_f32_e32 v98, v105, v109
	v_mul_f32_e32 v106, v106, v107
	v_mul_f32_e32 v107, v112, v113
	v_mul_f32_e32 v104, v104, v98
	v_cvt_pk_bf16_f32 v98, v100, v101
	v_cvt_pk_bf16_f32 v99, v106, v107
	v_cvt_pk_bf16_f32 v100, v108, v102
	v_cvt_pk_bf16_f32 v101, v103, v104
	v_mad_i64_i32 v[102:103], s[0:1], v158, s76, v[152:153]
	v_lshl_add_u64 v[102:103], v[102:103], 0, v[154:155]
	global_store_dwordx4 v[102:103], v[98:101], off
	v_cvt_f32_i32_e32 v103, v94
	v_cvt_f32_i32_e32 v102, v90
	v_or_b32_e32 v98, 32, v148
	v_ashrrev_i32_e32 v99, 31, v98
	v_lshl_add_u64 v[100:101], v[98:99], 2, s[26:27]
	s_nop 1
	v_cvt_f32_i32_e32 v94, v91
	v_cvt_f32_i32_e32 v91, v96
	v_cvt_f32_i32_e32 v90, v92
	v_cvt_f32_i32_e32 v96, v93
	v_cvt_f32_i32_e32 v93, v86
	v_cvt_f32_i32_e32 v92, v82
	v_cvt_f32_i32_e32 v86, v83
	v_cvt_f32_i32_e32 v83, v88
	v_cvt_f32_i32_e32 v82, v84
	v_cvt_f32_i32_e32 v88, v85
	v_mov_b32_e32 v100, v194
	v_pk_mul_f32 v[110:111], v[126:127], v[100:101] op_sel_hi:[1,0]
	v_pk_mul_f32 v[84:85], v[122:123], v[100:101] op_sel_hi:[1,0]
	v_pk_mul_f32 v[92:93], v[110:111], v[92:93]
	v_pk_mul_f32 v[84:85], v[84:85], v[102:103]
	v_exp_f32_e64 v103, -v93
	v_pk_mul_f32 v[104:105], v[120:121], v[100:101] op_sel_hi:[1,0]
	v_pk_mul_f32 v[112:113], v[118:119], v[100:101] op_sel_hi:[1,0]
	v_pk_mul_f32 v[158:159], v[128:129], v[100:101] op_sel_hi:[1,0]
	v_pk_mul_f32 v[106:107], v[124:125], v[100:101] op_sel_hi:[1,0]
	v_pk_mul_f32 v[108:109], v[116:117], v[100:101] op_sel_hi:[1,0]
	v_pk_mul_f32 v[100:101], v[114:115], v[100:101] op_sel_hi:[1,0]
	v_pk_mul_f32 v[94:95], v[104:105], v[94:95]
	v_pk_mul_f32 v[86:87], v[112:113], v[86:87]
	v_pk_mul_f32 v[82:83], v[158:159], v[82:83]
	v_pk_mul_f32 v[90:91], v[106:107], v[90:91]
	v_pk_mul_f32 v[96:97], v[108:109], v[96:97]
	v_pk_mul_f32 v[88:89], v[100:101], v[88:89]
	v_add_f32_e32 v103, 1.0, v103
	v_exp_f32_e64 v99, -v85
	v_exp_f32_e64 v100, -v95
	v_exp_f32_e64 v104, -v87
	v_exp_f32_e64 v105, -v83
	v_rcp_f32_e32 v103, v103
	v_exp_f32_e64 v101, -v91
	v_exp_f32_e64 v102, -v97
	v_exp_f32_e64 v106, -v89
	v_add_f32_e32 v99, 1.0, v99
	v_add_f32_e32 v100, 1.0, v100
	v_add_f32_e32 v104, 1.0, v104
	v_add_f32_e32 v105, 1.0, v105
	v_mul_f32_e32 v93, v93, v103
	v_add_f32_e32 v101, 1.0, v101
	v_add_f32_e32 v102, 1.0, v102
	v_rcp_f32_e32 v99, v99
	v_rcp_f32_e32 v100, v100
	v_rcp_f32_e32 v104, v104
	v_rcp_f32_e32 v105, v105
	v_mul_f32_e32 v92, v92, v93
	v_add_f32_e32 v93, 1.0, v106
	v_rcp_f32_e32 v101, v101
	v_rcp_f32_e32 v102, v102
	v_rcp_f32_e32 v93, v93
	v_mul_f32_e32 v85, v85, v99
	v_mul_f32_e32 v95, v95, v100
	v_mul_f32_e32 v87, v87, v104
	v_mul_f32_e32 v83, v83, v105
	v_mul_f32_e32 v91, v91, v101
	v_mul_f32_e32 v97, v97, v102
	v_mul_f32_e32 v84, v84, v85
	v_mul_f32_e32 v85, v94, v95
	v_mul_f32_e32 v86, v86, v87
	v_mul_f32_e32 v87, v82, v83
	v_mul_f32_e32 v82, v89, v93
	v_mul_f32_e32 v90, v90, v91
	v_mul_f32_e32 v91, v96, v97
	v_mul_f32_e32 v88, v88, v82
	v_cvt_pk_bf16_f32 v82, v84, v85
	v_cvt_pk_bf16_f32 v83, v90, v91
	v_cvt_pk_bf16_f32 v84, v92, v86
	v_cvt_pk_bf16_f32 v85, v87, v88
	v_mad_i64_i32 v[86:87], s[0:1], v98, s76, v[152:153]
	v_lshl_add_u64 v[86:87], v[86:87], 0, v[154:155]
	global_store_dwordx4 v[86:87], v[82:85], off
	v_cvt_f32_i32_e32 v87, v78
	v_cvt_f32_i32_e32 v86, v74
	v_or_b32_e32 v82, 48, v148
	v_ashrrev_i32_e32 v83, 31, v82
	v_lshl_add_u64 v[84:85], v[82:83], 2, s[26:27]
	s_nop 1
	v_cvt_f32_i32_e32 v78, v75
	v_cvt_f32_i32_e32 v75, v80
	v_cvt_f32_i32_e32 v74, v76
	v_cvt_f32_i32_e32 v80, v77
	v_cvt_f32_i32_e32 v77, v70
	v_cvt_f32_i32_e32 v76, v66
	v_cvt_f32_i32_e32 v70, v67
	v_cvt_f32_i32_e32 v67, v72
	v_cvt_f32_i32_e32 v66, v68
	v_cvt_f32_i32_e32 v72, v69
	v_mov_b32_e32 v84, v196
	v_pk_mul_f32 v[68:69], v[122:123], v[84:85] op_sel_hi:[1,0]
	v_pk_mul_f32 v[88:89], v[120:121], v[84:85] op_sel_hi:[1,0]
	v_pk_mul_f32 v[96:97], v[118:119], v[84:85] op_sel_hi:[1,0]
	v_pk_mul_f32 v[98:99], v[128:129], v[84:85] op_sel_hi:[1,0]
	v_pk_mul_f32 v[90:91], v[124:125], v[84:85] op_sel_hi:[1,0]
	v_pk_mul_f32 v[92:93], v[116:117], v[84:85] op_sel_hi:[1,0]
	v_pk_mul_f32 v[94:95], v[126:127], v[84:85] op_sel_hi:[1,0]
	v_pk_mul_f32 v[84:85], v[114:115], v[84:85] op_sel_hi:[1,0]
	v_pk_mul_f32 v[68:69], v[68:69], v[86:87]
	v_pk_mul_f32 v[78:79], v[88:89], v[78:79]
	v_pk_mul_f32 v[70:71], v[96:97], v[70:71]
	v_pk_mul_f32 v[66:67], v[98:99], v[66:67]
	v_pk_mul_f32 v[74:75], v[90:91], v[74:75]
	v_pk_mul_f32 v[80:81], v[92:93], v[80:81]
	v_pk_mul_f32 v[76:77], v[94:95], v[76:77]
	v_pk_mul_f32 v[72:73], v[84:85], v[72:73]
	v_exp_f32_e64 v83, -v69
	v_exp_f32_e64 v84, -v79
	v_exp_f32_e64 v88, -v71
	v_exp_f32_e64 v89, -v67
	v_exp_f32_e64 v85, -v75
	v_exp_f32_e64 v86, -v81
	v_exp_f32_e64 v87, -v77
	v_exp_f32_e64 v90, -v73
	v_add_f32_e32 v83, 1.0, v83
	v_add_f32_e32 v84, 1.0, v84
	v_add_f32_e32 v88, 1.0, v88
	v_add_f32_e32 v89, 1.0, v89
	v_add_f32_e32 v85, 1.0, v85
	v_add_f32_e32 v86, 1.0, v86
	v_add_f32_e32 v87, 1.0, v87
	v_add_f32_e32 v90, 1.0, v90
	v_rcp_f32_e32 v83, v83
	v_rcp_f32_e32 v84, v84
	v_rcp_f32_e32 v88, v88
	v_rcp_f32_e32 v89, v89
	v_rcp_f32_e32 v85, v85
	v_rcp_f32_e32 v86, v86
	v_rcp_f32_e32 v87, v87
	v_rcp_f32_e32 v90, v90
	v_mul_f32_e32 v69, v69, v83
	v_mul_f32_e32 v79, v79, v84
	v_mul_f32_e32 v71, v71, v88
	v_mul_f32_e32 v67, v67, v89
	v_mul_f32_e32 v75, v75, v85
	v_mul_f32_e32 v81, v81, v86
	v_mul_f32_e32 v77, v77, v87
	v_mul_f32_e32 v68, v68, v69
	v_mul_f32_e32 v69, v78, v79
	v_mul_f32_e32 v70, v70, v71
	v_mul_f32_e32 v71, v66, v67
	v_mul_f32_e32 v66, v73, v90
	v_mul_f32_e32 v74, v74, v75
	v_mul_f32_e32 v75, v80, v81
	v_mul_f32_e32 v76, v76, v77
	v_mul_f32_e32 v72, v72, v66
	v_cvt_pk_bf16_f32 v66, v68, v69
	v_cvt_pk_bf16_f32 v67, v74, v75
	v_cvt_pk_bf16_f32 v68, v76, v70
	v_cvt_pk_bf16_f32 v69, v71, v72
	v_mad_i64_i32 v[70:71], s[0:1], v82, s76, v[152:153]
	v_lshl_add_u64 v[70:71], v[70:71], 0, v[154:155]
	global_store_dwordx4 v[70:71], v[66:69], off
	s_nop 1
	v_add_u32_e32 v82, 0x80, v148
	v_cvt_f32_i32_e32 v69, v62
	v_cvt_f32_i32_e32 v68, v58
	v_cvt_f32_i32_e32 v62, v59
	v_cvt_f32_i32_e32 v59, v64
	v_cvt_f32_i32_e32 v58, v60
	v_cvt_f32_i32_e32 v64, v61
	v_cvt_f32_i32_e32 v61, v54
	v_cvt_f32_i32_e32 v60, v50
	v_cvt_f32_i32_e32 v54, v51
	v_cvt_f32_i32_e32 v51, v56
	v_cvt_f32_i32_e32 v50, v52
	v_cvt_f32_i32_e32 v56, v53
	v_mov_b32_e32 v66, v198
	v_pk_mul_f32 v[52:53], v[122:123], v[66:67] op_sel_hi:[1,0]
	v_pk_mul_f32 v[70:71], v[120:121], v[66:67] op_sel_hi:[1,0]
	v_pk_mul_f32 v[78:79], v[118:119], v[66:67] op_sel_hi:[1,0]
	v_pk_mul_f32 v[80:81], v[128:129], v[66:67] op_sel_hi:[1,0]
	v_pk_mul_f32 v[72:73], v[124:125], v[66:67] op_sel_hi:[1,0]
	v_pk_mul_f32 v[74:75], v[116:117], v[66:67] op_sel_hi:[1,0]
	v_pk_mul_f32 v[76:77], v[126:127], v[66:67] op_sel_hi:[1,0]
	v_pk_mul_f32 v[66:67], v[114:115], v[66:67] op_sel_hi:[1,0]
	v_pk_mul_f32 v[52:53], v[52:53], v[68:69]
	v_pk_mul_f32 v[62:63], v[70:71], v[62:63]
	v_pk_mul_f32 v[54:55], v[78:79], v[54:55]
	v_pk_mul_f32 v[50:51], v[80:81], v[50:51]
	v_pk_mul_f32 v[58:59], v[72:73], v[58:59]
	v_pk_mul_f32 v[64:65], v[74:75], v[64:65]
	v_pk_mul_f32 v[60:61], v[76:77], v[60:61]
	v_pk_mul_f32 v[56:57], v[66:67], v[56:57]
	v_exp_f32_e64 v66, -v53
	v_exp_f32_e64 v67, -v63
	v_exp_f32_e64 v71, -v55
	v_exp_f32_e64 v72, -v51
	v_exp_f32_e64 v68, -v59
	v_exp_f32_e64 v69, -v65
	v_exp_f32_e64 v70, -v61
	v_exp_f32_e64 v73, -v57
	v_add_f32_e32 v66, 1.0, v66
	v_add_f32_e32 v67, 1.0, v67
	v_add_f32_e32 v71, 1.0, v71
	v_add_f32_e32 v72, 1.0, v72
	v_add_f32_e32 v68, 1.0, v68
	v_add_f32_e32 v69, 1.0, v69
	v_add_f32_e32 v70, 1.0, v70
	v_add_f32_e32 v73, 1.0, v73
	v_rcp_f32_e32 v66, v66
	v_rcp_f32_e32 v67, v67
	v_rcp_f32_e32 v71, v71
	v_rcp_f32_e32 v72, v72
	v_rcp_f32_e32 v68, v68
	v_rcp_f32_e32 v69, v69
	v_rcp_f32_e32 v70, v70
	v_rcp_f32_e32 v73, v73
	v_mul_f32_e32 v53, v53, v66
	v_mul_f32_e32 v63, v63, v67
	v_mul_f32_e32 v55, v55, v71
	v_mul_f32_e32 v51, v51, v72
	v_mul_f32_e32 v59, v59, v68
	v_mul_f32_e32 v65, v65, v69
	v_mul_f32_e32 v61, v61, v70
	v_mul_f32_e32 v57, v57, v73
	v_mul_f32_e32 v52, v52, v53
	v_mul_f32_e32 v53, v62, v63
	v_mul_f32_e32 v54, v54, v55
	v_mul_f32_e32 v55, v50, v51
	v_mul_f32_e32 v58, v58, v59
	v_mul_f32_e32 v59, v64, v65
	v_mul_f32_e32 v60, v60, v61
	v_mul_f32_e32 v56, v56, v57
	v_cvt_pk_bf16_f32 v50, v52, v53
	v_cvt_pk_bf16_f32 v51, v58, v59
	v_cvt_pk_bf16_f32 v52, v60, v54
	v_cvt_pk_bf16_f32 v53, v55, v56
	v_mad_i64_i32 v[54:55], s[0:1], v82, s76, v[152:153]
	v_lshl_add_u64 v[54:55], v[54:55], 0, v[154:155]
	global_store_dwordx4 v[54:55], v[50:53], off
	s_nop 1
	v_mov_b32_e32 v50, v200
	v_pk_mul_f32 v[56:57], v[120:121], v[50:51] op_sel_hi:[1,0]
	v_cvt_f32_i32_e32 v53, v46
	v_cvt_f32_i32_e32 v52, v42
	v_cvt_f32_i32_e32 v46, v43
	v_cvt_f32_i32_e32 v43, v48
	v_cvt_f32_i32_e32 v42, v44
	v_cvt_f32_i32_e32 v48, v45
	v_cvt_f32_i32_e32 v45, v38
	v_cvt_f32_i32_e32 v44, v34
	v_cvt_f32_i32_e32 v38, v35
	v_cvt_f32_i32_e32 v35, v40
	v_cvt_f32_i32_e32 v34, v36
	v_cvt_f32_i32_e32 v40, v37
	v_add_u32_e32 v36, 0x90, v148
	v_mad_i64_i32 v[36:37], s[0:1], v36, s76, v[152:153]
	v_lshl_add_u64 v[54:55], v[36:37], 0, v[154:155]
	v_pk_mul_f32 v[36:37], v[122:123], v[50:51] op_sel_hi:[1,0]
	v_pk_mul_f32 v[58:59], v[124:125], v[50:51] op_sel_hi:[1,0]
	v_pk_mul_f32 v[60:61], v[116:117], v[50:51] op_sel_hi:[1,0]
	v_pk_mul_f32 v[62:63], v[126:127], v[50:51] op_sel_hi:[1,0]
	v_pk_mul_f32 v[64:65], v[118:119], v[50:51] op_sel_hi:[1,0]
	v_pk_mul_f32 v[66:67], v[128:129], v[50:51] op_sel_hi:[1,0]
	v_pk_mul_f32 v[50:51], v[114:115], v[50:51] op_sel_hi:[1,0]
	v_pk_mul_f32 v[36:37], v[36:37], v[52:53]
	v_pk_mul_f32 v[46:47], v[56:57], v[46:47]
	v_pk_mul_f32 v[42:43], v[58:59], v[42:43]
	v_pk_mul_f32 v[48:49], v[60:61], v[48:49]
	v_pk_mul_f32 v[44:45], v[62:63], v[44:45]
	v_pk_mul_f32 v[38:39], v[64:65], v[38:39]
	v_pk_mul_f32 v[34:35], v[66:67], v[34:35]
	v_pk_mul_f32 v[40:41], v[50:51], v[40:41]
	v_exp_f32_e64 v50, -v37
	v_exp_f32_e64 v51, -v47
	v_exp_f32_e64 v52, -v43
	v_exp_f32_e64 v53, -v49
	v_exp_f32_e64 v56, -v45
	v_exp_f32_e64 v57, -v39
	v_exp_f32_e64 v58, -v35
	v_exp_f32_e64 v59, -v41
	v_add_f32_e32 v50, 1.0, v50
	v_add_f32_e32 v51, 1.0, v51
	v_add_f32_e32 v52, 1.0, v52
	v_add_f32_e32 v53, 1.0, v53
	v_add_f32_e32 v56, 1.0, v56
	v_add_f32_e32 v57, 1.0, v57
	v_add_f32_e32 v58, 1.0, v58
	v_add_f32_e32 v59, 1.0, v59
	v_rcp_f32_e32 v50, v50
	v_rcp_f32_e32 v51, v51
	v_rcp_f32_e32 v52, v52
	v_rcp_f32_e32 v53, v53
	v_rcp_f32_e32 v56, v56
	v_rcp_f32_e32 v57, v57
	v_rcp_f32_e32 v58, v58
	v_rcp_f32_e32 v59, v59
	v_mul_f32_e32 v37, v37, v50
	v_mul_f32_e32 v47, v47, v51
	v_mul_f32_e32 v43, v43, v52
	v_mul_f32_e32 v49, v49, v53
	v_mul_f32_e32 v45, v45, v56
	v_mul_f32_e32 v39, v39, v57
	v_mul_f32_e32 v35, v35, v58
	v_mul_f32_e32 v41, v41, v59
	v_mul_f32_e32 v36, v36, v37
	v_mul_f32_e32 v37, v46, v47
	v_mul_f32_e32 v42, v42, v43
	v_mul_f32_e32 v43, v48, v49
	v_mul_f32_e32 v44, v44, v45
	v_mul_f32_e32 v38, v38, v39
	v_mul_f32_e32 v39, v34, v35
	v_mul_f32_e32 v40, v40, v41
	v_cvt_pk_bf16_f32 v34, v36, v37
	v_cvt_pk_bf16_f32 v35, v42, v43
	v_cvt_pk_bf16_f32 v36, v44, v38
	v_cvt_pk_bf16_f32 v37, v39, v40
	global_store_dwordx4 v[54:55], v[34:37], off
	s_nop 1
	v_mov_b32_e32 v34, v202
	v_pk_mul_f32 v[40:41], v[120:121], v[34:35] op_sel_hi:[1,0]
	v_cvt_f32_i32_e32 v37, v30
	v_cvt_f32_i32_e32 v36, v26
	v_cvt_f32_i32_e32 v30, v27
	v_cvt_f32_i32_e32 v27, v32
	v_cvt_f32_i32_e32 v26, v28
	v_cvt_f32_i32_e32 v32, v29
	v_cvt_f32_i32_e32 v29, v22
	v_cvt_f32_i32_e32 v28, v18
	v_cvt_f32_i32_e32 v22, v19
	v_cvt_f32_i32_e32 v19, v24
	v_cvt_f32_i32_e32 v18, v20
	v_cvt_f32_i32_e32 v24, v21
	v_add_u32_e32 v20, 0xa0, v148
	v_mad_i64_i32 v[20:21], s[0:1], v20, s76, v[152:153]
	v_lshl_add_u64 v[38:39], v[20:21], 0, v[154:155]
	v_pk_mul_f32 v[20:21], v[122:123], v[34:35] op_sel_hi:[1,0]
	v_pk_mul_f32 v[42:43], v[124:125], v[34:35] op_sel_hi:[1,0]
	v_pk_mul_f32 v[44:45], v[116:117], v[34:35] op_sel_hi:[1,0]
	v_pk_mul_f32 v[46:47], v[126:127], v[34:35] op_sel_hi:[1,0]
	v_pk_mul_f32 v[48:49], v[118:119], v[34:35] op_sel_hi:[1,0]
	v_pk_mul_f32 v[50:51], v[128:129], v[34:35] op_sel_hi:[1,0]
	v_pk_mul_f32 v[34:35], v[114:115], v[34:35] op_sel_hi:[1,0]
	v_pk_mul_f32 v[20:21], v[20:21], v[36:37]
	v_pk_mul_f32 v[30:31], v[40:41], v[30:31]
	v_pk_mul_f32 v[26:27], v[42:43], v[26:27]
	v_pk_mul_f32 v[32:33], v[44:45], v[32:33]
	v_pk_mul_f32 v[28:29], v[46:47], v[28:29]
	v_pk_mul_f32 v[22:23], v[48:49], v[22:23]
	v_pk_mul_f32 v[18:19], v[50:51], v[18:19]
	v_pk_mul_f32 v[24:25], v[34:35], v[24:25]
	v_exp_f32_e64 v34, -v21
	v_exp_f32_e64 v35, -v31
	v_exp_f32_e64 v36, -v27
	v_exp_f32_e64 v37, -v33
	v_exp_f32_e64 v40, -v29
	v_exp_f32_e64 v41, -v23
	v_exp_f32_e64 v42, -v19
	v_exp_f32_e64 v43, -v25
	v_add_f32_e32 v34, 1.0, v34
	v_add_f32_e32 v35, 1.0, v35
	v_add_f32_e32 v36, 1.0, v36
	v_add_f32_e32 v37, 1.0, v37
	v_add_f32_e32 v40, 1.0, v40
	v_add_f32_e32 v41, 1.0, v41
	v_add_f32_e32 v42, 1.0, v42
	v_add_f32_e32 v43, 1.0, v43
	v_rcp_f32_e32 v34, v34
	v_rcp_f32_e32 v35, v35
	v_rcp_f32_e32 v36, v36
	v_rcp_f32_e32 v37, v37
	v_rcp_f32_e32 v40, v40
	v_rcp_f32_e32 v41, v41
	v_rcp_f32_e32 v42, v42
	v_rcp_f32_e32 v43, v43
	v_mul_f32_e32 v21, v21, v34
	v_mul_f32_e32 v31, v31, v35
	v_mul_f32_e32 v27, v27, v36
	v_mul_f32_e32 v33, v33, v37
	v_mul_f32_e32 v29, v29, v40
	v_mul_f32_e32 v23, v23, v41
	v_mul_f32_e32 v19, v19, v42
	v_mul_f32_e32 v25, v25, v43
	v_mul_f32_e32 v20, v20, v21
	v_mul_f32_e32 v21, v30, v31
	v_mul_f32_e32 v26, v26, v27
	v_mul_f32_e32 v27, v32, v33
	v_mul_f32_e32 v28, v28, v29
	v_mul_f32_e32 v22, v22, v23
	v_mul_f32_e32 v23, v18, v19
	v_mul_f32_e32 v24, v24, v25
	v_cvt_pk_bf16_f32 v18, v20, v21
	v_cvt_pk_bf16_f32 v19, v26, v27
	v_cvt_pk_bf16_f32 v20, v28, v22
	v_cvt_pk_bf16_f32 v21, v23, v24
	global_store_dwordx4 v[38:39], v[18:21], off
	s_nop 1
	v_mov_b32_e32 v18, v204
	v_pk_mul_f32 v[24:25], v[120:121], v[18:19] op_sel_hi:[1,0]
	v_cvt_f32_i32_e32 v21, v14
	v_cvt_f32_i32_e32 v20, v10
	v_cvt_f32_i32_e32 v14, v11
	v_cvt_f32_i32_e32 v11, v16
	v_cvt_f32_i32_e32 v10, v12
	v_cvt_f32_i32_e32 v16, v13
	v_cvt_f32_i32_e32 v13, v6
	v_cvt_f32_i32_e32 v12, v2
	v_cvt_f32_i32_e32 v6, v3
	v_cvt_f32_i32_e32 v3, v8
	v_cvt_f32_i32_e32 v2, v4
	v_cvt_f32_i32_e32 v8, v5
	v_add_u32_e32 v4, 0xb0, v148
	v_mad_i64_i32 v[4:5], s[0:1], v4, s76, v[152:153]
	v_lshl_add_u64 v[22:23], v[4:5], 0, v[154:155]
	v_pk_mul_f32 v[4:5], v[122:123], v[18:19] op_sel_hi:[1,0]
	v_pk_mul_f32 v[26:27], v[124:125], v[18:19] op_sel_hi:[1,0]
	v_pk_mul_f32 v[28:29], v[116:117], v[18:19] op_sel_hi:[1,0]
	v_pk_mul_f32 v[30:31], v[126:127], v[18:19] op_sel_hi:[1,0]
	v_pk_mul_f32 v[32:33], v[118:119], v[18:19] op_sel_hi:[1,0]
	v_pk_mul_f32 v[34:35], v[128:129], v[18:19] op_sel_hi:[1,0]
	v_pk_mul_f32 v[18:19], v[114:115], v[18:19] op_sel_hi:[1,0]
	v_pk_mul_f32 v[4:5], v[4:5], v[20:21]
	v_pk_mul_f32 v[14:15], v[24:25], v[14:15]
	v_pk_mul_f32 v[10:11], v[26:27], v[10:11]
	v_pk_mul_f32 v[16:17], v[28:29], v[16:17]
	v_pk_mul_f32 v[12:13], v[30:31], v[12:13]
	v_pk_mul_f32 v[6:7], v[32:33], v[6:7]
	v_pk_mul_f32 v[2:3], v[34:35], v[2:3]
	v_pk_mul_f32 v[8:9], v[18:19], v[8:9]
	v_exp_f32_e64 v18, -v5
	v_exp_f32_e64 v19, -v15
	v_exp_f32_e64 v20, -v11
	v_exp_f32_e64 v21, -v17
	v_exp_f32_e64 v24, -v13
	v_exp_f32_e64 v25, -v7
	v_exp_f32_e64 v26, -v3
	v_exp_f32_e64 v27, -v9
	v_add_f32_e32 v18, 1.0, v18
	v_add_f32_e32 v19, 1.0, v19
	v_add_f32_e32 v20, 1.0, v20
	v_add_f32_e32 v21, 1.0, v21
	v_add_f32_e32 v24, 1.0, v24
	v_add_f32_e32 v25, 1.0, v25
	v_add_f32_e32 v26, 1.0, v26
	v_add_f32_e32 v27, 1.0, v27
	v_rcp_f32_e32 v18, v18
	v_rcp_f32_e32 v19, v19
	v_rcp_f32_e32 v20, v20
	v_rcp_f32_e32 v21, v21
	v_rcp_f32_e32 v24, v24
	v_rcp_f32_e32 v25, v25
	v_rcp_f32_e32 v26, v26
	v_rcp_f32_e32 v27, v27
	v_mul_f32_e32 v5, v5, v18
	v_mul_f32_e32 v15, v15, v19
	v_mul_f32_e32 v11, v11, v20
	v_mul_f32_e32 v17, v17, v21
	v_mul_f32_e32 v13, v13, v24
	v_mul_f32_e32 v7, v7, v25
	v_mul_f32_e32 v3, v3, v26
	v_mul_f32_e32 v9, v9, v27
	v_mul_f32_e32 v4, v4, v5
	v_mul_f32_e32 v5, v14, v15
	s_mov_b64 s[0:1], -1
	v_mul_f32_e32 v10, v10, v11
	v_mul_f32_e32 v11, v16, v17
	v_mul_f32_e32 v12, v12, v13
	v_mul_f32_e32 v6, v6, v7
	v_mul_f32_e32 v7, v2, v3
	v_mul_f32_e32 v8, v8, v9
	v_cvt_pk_bf16_f32 v2, v4, v5
	v_cvt_pk_bf16_f32 v3, v10, v11
	v_cvt_pk_bf16_f32 v4, v12, v6
	v_cvt_pk_bf16_f32 v5, v7, v8
	global_store_dwordx4 v[22:23], v[2:5], off
	s_cbranch_vccnz .LBB0_1412
	s_andn2_b64 vcc, exec, s[18:19]
	s_cbranch_vccnz .LBB0_1411
	s_barrier
	s_branch .LBB0_1411

.LBB0_1603:
	v_lshl_or_b32 v164, s67, 8, v155
	v_ashrrev_i32_e32 v165, 31, v164
	v_lshl_add_u32 v166, s66, 8, v1
	v_lshl_add_u64 v[148:149], v[164:165], 2, s[16:17]
	v_ashrrev_i32_e32 v167, 31, v166
	global_load_dwordx4 v[160:163], v[148:149], off offset:16
	global_load_dwordx4 v[150:153], v[148:149], off
	v_lshl_add_u64 v[146:147], v[166:167], 2, s[34:35]
	global_load_dword v159, v[146:147], off
	global_load_dword v190, v[146:147], off
	global_load_dword v192, v[146:147], off offset:64
	global_load_dword v194, v[146:147], off offset:128
	global_load_dword v196, v[146:147], off offset:192
	global_load_dword v198, v[146:147], off offset:512
	global_load_dword v200, v[146:147], off offset:576
	global_load_dword v202, v[146:147], off offset:640
	global_load_dword v204, v[146:147], off offset:704
	global_load_dwordx4 v[206:209], v[148:149], off offset:512
	global_load_dwordx4 v[210:213], v[148:149], off offset:528
	v_cvt_f32_i32_e32 v170, v126
	v_cvt_f32_i32_e32 v171, v127
	v_cvt_f32_i32_e32 v172, v128
	v_cvt_f32_i32_e32 v173, v129
	v_cvt_f32_i32_e32 v174, v122
	v_cvt_f32_i32_e32 v175, v123
	v_cvt_f32_i32_e32 v176, v124
	v_cvt_f32_i32_e32 v177, v125
	v_lshlrev_b64 v[122:123], 13, v[166:167]
	v_or_b32_e32 v168, 16, v166
	v_lshlrev_b64 v[164:165], 1, v[164:165]
	v_lshl_add_u64 v[122:123], s[30:31], 0, v[122:123]
	v_ashrrev_i32_e32 v169, 31, v168
	v_lshl_add_u64 v[122:123], v[122:123], 0, v[164:165]
	v_lshl_add_u64 v[124:125], v[168:169], 2, s[34:35]
	v_cvt_f32_i32_e32 v118, v118
	v_cvt_f32_i32_e32 v119, v119
	v_cvt_f32_i32_e32 v120, v120
	v_cvt_f32_i32_e32 v121, v121
	v_cvt_f32_i32_e32 v110, v110
	v_cvt_f32_i32_e32 v111, v111
	v_cvt_f32_i32_e32 v112, v112
	v_cvt_f32_i32_e32 v113, v113
	v_cvt_f32_i32_e32 v102, v102
	v_cvt_f32_i32_e32 v103, v103
	v_cvt_f32_i32_e32 v104, v104
	v_cvt_f32_i32_e32 v105, v105
	v_cvt_f32_i32_e32 v100, v100
	v_cvt_f32_i32_e32 v101, v101
	v_cvt_f32_i32_e32 v93, v93
	v_cvt_f32_i32_e32 v96, v96
	v_cvt_f32_i32_e32 v97, v97
	v_cvt_f32_i32_e32 v90, v90
	v_cvt_f32_i32_e32 v91, v91
	v_cvt_f32_i32_e32 v92, v92
	v_cvt_f32_i32_e32 v85, v85
	v_cvt_f32_i32_e32 v88, v88
	v_cvt_f32_i32_e32 v89, v89
	v_cvt_f32_i32_e32 v82, v82
	v_cvt_f32_i32_e32 v83, v83
	v_cvt_f32_i32_e32 v84, v84
	v_cvt_f32_i32_e32 v77, v77
	v_cvt_f32_i32_e32 v80, v80
	v_cvt_f32_i32_e32 v81, v81
	v_cvt_f32_i32_e32 v74, v74
	v_cvt_f32_i32_e32 v75, v75
	v_cvt_f32_i32_e32 v76, v76
	v_cvt_f32_i32_e32 v69, v69
	v_cvt_f32_i32_e32 v72, v72
	v_cvt_f32_i32_e32 v73, v73
	v_cvt_f32_i32_e32 v66, v66
	v_cvt_f32_i32_e32 v67, v67
	v_cvt_f32_i32_e32 v68, v68
	v_cvt_f32_i32_e32 v53, v53
	v_cvt_f32_i32_e32 v54, v54
	v_cvt_f32_i32_e32 v55, v55
	v_cvt_f32_i32_e32 v56, v56
	v_cvt_f32_i32_e32 v57, v57
	v_cvt_f32_i32_e32 v50, v50
	v_cvt_f32_i32_e32 v51, v51
	v_cvt_f32_i32_e32 v52, v52
	v_cvt_f32_i32_e32 v45, v45
	v_cvt_f32_i32_e32 v46, v46
	v_cvt_f32_i32_e32 v47, v47
	v_cvt_f32_i32_e32 v48, v48
	v_cvt_f32_i32_e32 v49, v49
	v_cvt_f32_i32_e32 v42, v42
	v_cvt_f32_i32_e32 v43, v43
	v_cvt_f32_i32_e32 v44, v44
	v_cvt_f32_i32_e32 v37, v37
	v_cvt_f32_i32_e32 v38, v38
	v_cvt_f32_i32_e32 v39, v39
	v_cvt_f32_i32_e32 v40, v40
	v_cvt_f32_i32_e32 v41, v41
	v_cvt_f32_i32_e32 v34, v34
	v_cvt_f32_i32_e32 v35, v35
	s_cmp_lg_u64 s[20:21], 0
	s_cbranch_scc0 .Lalb_8
	s_barrier
.Lalb_8:
	s_waitcnt vmcnt(0)
	v_pk_mul_f32 v[126:127], v[162:163], s[24:25] op_sel_hi:[1,0]
	v_pk_mul_f32 v[128:129], v[152:153], s[24:25] op_sel_hi:[1,0]
	v_pk_mul_f32 v[152:153], v[150:151], s[24:25] op_sel_hi:[1,0]
	v_pk_mul_f32 v[150:151], v[160:161], s[24:25] op_sel_hi:[1,0]
	v_mul_f32_e32 v160, v152, v159
	v_mul_f32_e32 v161, v153, v159
	v_mul_f32_e32 v162, v128, v159
	v_mul_f32_e32 v163, v129, v159
	v_mul_f32_e32 v167, v159, v150
	v_mul_f32_e32 v178, v159, v151
	v_mul_f32_e32 v179, v159, v126
	v_mul_f32_e32 v159, v159, v127
	v_mul_f32_e32 v160, v160, v170
	v_mul_f32_e32 v161, v161, v171
	v_mul_f32_e32 v162, v162, v172
	v_mul_f32_e32 v163, v163, v173
	v_mul_f32_e32 v167, v167, v174
	v_mul_f32_e32 v170, v178, v175
	v_mul_f32_e32 v171, v179, v176
	v_mul_f32_e32 v159, v159, v177
	v_cvt_pk_bf16_f32 v160, v160, v161
	v_cvt_pk_bf16_f32 v161, v162, v163
	v_cvt_pk_bf16_f32 v162, v167, v170
	v_cvt_pk_bf16_f32 v163, v171, v159
	global_store_dwordx4 v[122:123], v[160:163], off
	s_nop 1
	v_cvt_f32_i32_e32 v167, v116
	v_cvt_f32_i32_e32 v162, v114
	v_cvt_f32_i32_e32 v163, v115
	v_cvt_f32_i32_e32 v170, v117
	v_lshlrev_b64 v[116:117], 13, v[168:169]
	v_or_b32_e32 v160, 32, v166
	v_lshl_add_u64 v[116:117], s[30:31], 0, v[116:117]
	v_ashrrev_i32_e32 v161, 31, v160
	v_lshl_add_u64 v[116:117], v[116:117], 0, v[164:165]
	v_lshl_add_u64 v[114:115], v[160:161], 2, s[34:35]
	v_cvt_f32_i32_e32 v36, v36
	v_cvt_f32_i32_e32 v29, v29
	v_cvt_f32_i32_e32 v32, v32
	v_cvt_f32_i32_e32 v33, v33
	v_cvt_f32_i32_e32 v26, v26
	v_cvt_f32_i32_e32 v27, v27
	v_cvt_f32_i32_e32 v28, v28
	v_cvt_f32_i32_e32 v21, v21
	v_cvt_f32_i32_e32 v24, v24
	v_cvt_f32_i32_e32 v25, v25
	v_cvt_f32_i32_e32 v18, v18
	v_cvt_f32_i32_e32 v19, v19
	v_cvt_f32_i32_e32 v20, v20
	v_cvt_f32_i32_e32 v13, v13
	v_cvt_f32_i32_e32 v16, v16
	v_cvt_f32_i32_e32 v17, v17
	v_cvt_f32_i32_e32 v10, v10
	v_cvt_f32_i32_e32 v11, v11
	v_cvt_f32_i32_e32 v12, v12
	v_cvt_f32_i32_e32 v5, v5
	v_cvt_f32_i32_e32 v8, v8
	v_cvt_f32_i32_e32 v9, v9
	v_cvt_f32_i32_e32 v2, v2
	v_cvt_f32_i32_e32 v3, v3
	v_cvt_f32_i32_e32 v4, v4
	s_mov_b64 s[0:1], -1
	v_mov_b32_e32 v159, v192
	v_mul_f32_e32 v168, v152, v159
	v_mul_f32_e32 v169, v153, v159
	v_mul_f32_e32 v171, v128, v159
	v_mul_f32_e32 v172, v129, v159
	v_mul_f32_e32 v173, v150, v159
	v_mul_f32_e32 v174, v151, v159
	v_mul_f32_e32 v175, v126, v159
	v_mul_f32_e32 v159, v127, v159
	v_mul_f32_e32 v118, v168, v118
	v_mul_f32_e32 v119, v169, v119
	v_mul_f32_e32 v120, v171, v120
	v_mul_f32_e32 v121, v172, v121
	v_mul_f32_e32 v162, v173, v162
	v_mul_f32_e32 v163, v174, v163
	v_mul_f32_e32 v167, v175, v167
	v_mul_f32_e32 v159, v159, v170
	v_cvt_pk_bf16_f32 v118, v118, v119
	v_cvt_pk_bf16_f32 v119, v120, v121
	v_cvt_pk_bf16_f32 v120, v162, v163
	v_cvt_pk_bf16_f32 v121, v167, v159
	global_store_dwordx4 v[116:117], v[118:121], off
	s_nop 1
	v_cvt_f32_i32_e32 v159, v107
	v_cvt_f32_i32_e32 v121, v106
	v_cvt_f32_i32_e32 v162, v108
	v_cvt_f32_i32_e32 v163, v109
	v_lshlrev_b64 v[108:109], 13, v[160:161]
	v_or_b32_e32 v118, 48, v166
	v_lshl_add_u64 v[108:109], s[30:31], 0, v[108:109]
	v_ashrrev_i32_e32 v119, 31, v118
	v_lshl_add_u64 v[108:109], v[108:109], 0, v[164:165]
	v_lshl_add_u64 v[106:107], v[118:119], 2, s[34:35]
	v_mov_b32_e32 v120, v194
	v_mul_f32_e32 v160, v152, v120
	v_mul_f32_e32 v161, v153, v120
	v_mul_f32_e32 v166, v128, v120
	v_mul_f32_e32 v167, v129, v120
	v_mul_f32_e32 v168, v150, v120
	v_mul_f32_e32 v169, v151, v120
	v_mul_f32_e32 v170, v126, v120
	v_mul_f32_e32 v120, v127, v120
	v_mul_f32_e32 v110, v160, v110
	v_mul_f32_e32 v111, v161, v111
	v_mul_f32_e32 v112, v166, v112
	v_mul_f32_e32 v113, v167, v113
	v_mul_f32_e32 v121, v168, v121
	v_mul_f32_e32 v159, v169, v159
	v_mul_f32_e32 v160, v170, v162
	v_mul_f32_e32 v120, v120, v163
	v_cvt_pk_bf16_f32 v110, v110, v111
	v_cvt_pk_bf16_f32 v111, v112, v113
	v_cvt_pk_bf16_f32 v112, v121, v159
	v_cvt_pk_bf16_f32 v113, v160, v120
	global_store_dwordx4 v[108:109], v[110:113], off
	s_nop 1
	v_mov_b32_e32 v110, v196
	v_mul_f32_e32 v120, v129, v110
	v_cvt_f32_i32_e32 v111, v98
	v_cvt_f32_i32_e32 v112, v99
	v_lshlrev_b64 v[98:99], 13, v[118:119]
	v_lshl_add_u64 v[98:99], s[30:31], 0, v[98:99]
	v_mul_f32_e32 v113, v152, v110
	v_mul_f32_e32 v118, v153, v110
	v_lshl_add_u64 v[98:99], v[98:99], 0, v[164:165]
	v_mul_f32_e32 v119, v128, v110
	v_mul_f32_e32 v121, v150, v110
	v_mul_f32_e32 v159, v151, v110
	v_mul_f32_e32 v160, v126, v110
	v_mul_f32_e32 v110, v127, v110
	v_mul_f32_e32 v102, v113, v102
	v_mul_f32_e32 v103, v118, v103
	v_mul_f32_e32 v104, v119, v104
	v_mul_f32_e32 v105, v120, v105
	v_mul_f32_e32 v111, v121, v111
	v_mul_f32_e32 v112, v159, v112
	v_mul_f32_e32 v113, v160, v100
	v_mul_f32_e32 v110, v110, v101
	v_cvt_pk_bf16_f32 v100, v102, v103
	v_cvt_pk_bf16_f32 v101, v104, v105
	v_cvt_pk_bf16_f32 v102, v111, v112
	v_cvt_pk_bf16_f32 v103, v113, v110
	global_store_dwordx4 v[98:99], v[100:103], off
	s_nop 1
	v_mov_b32_e32 v100, v198
	v_mul_f32_e32 v104, v153, v100
	v_cvt_f32_i32_e32 v101, v94
	v_cvt_f32_i32_e32 v102, v95
	v_add_co_u32_e32 v94, vcc, s59, v122
	v_mul_f32_e32 v103, v152, v100
	v_mul_f32_e32 v105, v128, v100
	v_mul_f32_e32 v110, v129, v100
	v_mul_f32_e32 v111, v150, v100
	v_mul_f32_e32 v112, v151, v100
	v_mul_f32_e32 v113, v126, v100
	v_mul_f32_e32 v100, v127, v100
	v_addc_co_u32_e32 v95, vcc, 0, v123, vcc
	v_mul_f32_e32 v93, v100, v93
	v_mul_f32_e32 v101, v103, v101
	v_mul_f32_e32 v102, v104, v102
	v_mul_f32_e32 v96, v105, v96
	v_mul_f32_e32 v97, v110, v97
	v_mul_f32_e32 v103, v111, v90
	v_mul_f32_e32 v104, v112, v91
	v_mul_f32_e32 v105, v113, v92
	v_cvt_pk_bf16_f32 v90, v101, v102
	v_cvt_pk_bf16_f32 v91, v96, v97
	v_cvt_pk_bf16_f32 v92, v103, v104
	v_cvt_pk_bf16_f32 v93, v105, v93
	global_store_dwordx4 v[94:95], v[90:93], off
	s_nop 1
	v_mov_b32_e32 v90, v200
	v_mul_f32_e32 v94, v153, v90
	v_cvt_f32_i32_e32 v91, v86
	v_cvt_f32_i32_e32 v92, v87
	v_add_co_u32_e32 v86, vcc, s61, v122
	v_mul_f32_e32 v93, v152, v90
	v_mul_f32_e32 v95, v128, v90
	v_mul_f32_e32 v96, v129, v90
	v_mul_f32_e32 v97, v150, v90
	v_mul_f32_e32 v100, v151, v90
	v_mul_f32_e32 v101, v126, v90
	v_mul_f32_e32 v90, v127, v90
	v_addc_co_u32_e32 v87, vcc, 0, v123, vcc
	v_mul_f32_e32 v85, v90, v85
	v_mul_f32_e32 v91, v93, v91
	v_mul_f32_e32 v92, v94, v92
	v_mul_f32_e32 v88, v95, v88
	v_mul_f32_e32 v89, v96, v89
	v_mul_f32_e32 v93, v97, v82
	v_mul_f32_e32 v94, v100, v83
	v_mul_f32_e32 v95, v101, v84
	v_cvt_pk_bf16_f32 v82, v91, v92
	v_cvt_pk_bf16_f32 v83, v88, v89
	v_cvt_pk_bf16_f32 v84, v93, v94
	v_cvt_pk_bf16_f32 v85, v95, v85
	global_store_dwordx4 v[86:87], v[82:85], off
	s_nop 1
	v_mov_b32_e32 v82, v202
	v_mul_f32_e32 v86, v153, v82
	v_cvt_f32_i32_e32 v83, v78
	v_cvt_f32_i32_e32 v84, v79
	v_add_co_u32_e32 v78, vcc, s62, v122
	v_mul_f32_e32 v85, v152, v82
	v_mul_f32_e32 v87, v128, v82
	v_mul_f32_e32 v88, v129, v82
	v_mul_f32_e32 v89, v150, v82
	v_mul_f32_e32 v90, v151, v82
	v_mul_f32_e32 v91, v126, v82
	v_mul_f32_e32 v82, v127, v82
	v_addc_co_u32_e32 v79, vcc, 0, v123, vcc
	v_mul_f32_e32 v77, v82, v77
	v_mul_f32_e32 v83, v85, v83
	v_mul_f32_e32 v84, v86, v84
	v_mul_f32_e32 v80, v87, v80
	v_mul_f32_e32 v81, v88, v81
	v_mul_f32_e32 v85, v89, v74
	v_mul_f32_e32 v86, v90, v75
	v_mul_f32_e32 v87, v91, v76
	v_cvt_pk_bf16_f32 v74, v83, v84
	v_cvt_pk_bf16_f32 v75, v80, v81
	v_cvt_pk_bf16_f32 v76, v85, v86
	v_cvt_pk_bf16_f32 v77, v87, v77
	global_store_dwordx4 v[78:79], v[74:77], off
	s_nop 1
	v_mov_b32_e32 v74, v204
	v_mul_f32_e32 v78, v153, v74
	v_cvt_f32_i32_e32 v75, v70
	v_cvt_f32_i32_e32 v76, v71
	v_add_co_u32_e32 v70, vcc, s63, v122
	v_mul_f32_e32 v77, v152, v74
	v_mul_f32_e32 v79, v128, v74
	v_mul_f32_e32 v80, v129, v74
	v_mul_f32_e32 v81, v150, v74
	v_mul_f32_e32 v82, v151, v74
	v_mul_f32_e32 v83, v126, v74
	v_mul_f32_e32 v74, v127, v74
	v_addc_co_u32_e32 v71, vcc, 0, v123, vcc
	v_mul_f32_e32 v69, v74, v69
	v_mul_f32_e32 v75, v77, v75
	v_mul_f32_e32 v76, v78, v76
	v_mul_f32_e32 v72, v79, v72
	v_mul_f32_e32 v73, v80, v73
	v_mul_f32_e32 v77, v81, v66
	v_mul_f32_e32 v78, v82, v67
	v_mul_f32_e32 v79, v83, v68
	v_cvt_pk_bf16_f32 v66, v75, v76
	v_cvt_pk_bf16_f32 v67, v72, v73
	v_cvt_pk_bf16_f32 v68, v77, v78
	v_cvt_pk_bf16_f32 v69, v79, v69
	global_store_dwordx4 v[70:71], v[66:69], off
	s_nop 1
	s_nop 1
	v_cvt_f32_i32_e32 v75, v62
	v_cvt_f32_i32_e32 v76, v63
	v_cvt_f32_i32_e32 v77, v64
	v_cvt_f32_i32_e32 v78, v65
	v_cvt_f32_i32_e32 v79, v58
	v_cvt_f32_i32_e32 v80, v59
	v_cvt_f32_i32_e32 v81, v60
	v_cvt_f32_i32_e32 v82, v61
	s_and_b64 vcc, exec, s[4:5]
	v_pk_mul_f32 v[60:61], v[208:209], s[24:25] op_sel_hi:[1,0]
	v_pk_mul_f32 v[64:65], v[206:207], s[24:25] op_sel_hi:[1,0]
	v_pk_mul_f32 v[58:59], v[212:213], s[24:25] op_sel_hi:[1,0]
	v_pk_mul_f32 v[62:63], v[210:211], s[24:25] op_sel_hi:[1,0]
	v_mov_b32_e32 v74, v190
	v_mul_f32_e32 v66, v64, v74
	v_mul_f32_e32 v67, v65, v74
	v_mul_f32_e32 v68, v60, v74
	v_mul_f32_e32 v69, v61, v74
	v_mul_f32_e32 v70, v74, v62
	v_mul_f32_e32 v71, v74, v63
	v_mul_f32_e32 v72, v74, v58
	v_mul_f32_e32 v73, v74, v59
	v_mul_f32_e32 v66, v66, v75
	v_mul_f32_e32 v67, v67, v76
	v_mul_f32_e32 v68, v68, v77
	v_mul_f32_e32 v69, v69, v78
	v_mul_f32_e32 v70, v70, v79
	v_mul_f32_e32 v71, v71, v80
	v_mul_f32_e32 v72, v72, v81
	v_mul_f32_e32 v73, v73, v82
	v_cvt_pk_bf16_f32 v66, v66, v67
	v_cvt_pk_bf16_f32 v67, v68, v69
	v_cvt_pk_bf16_f32 v68, v70, v71
	v_cvt_pk_bf16_f32 v69, v72, v73
	global_store_dwordx4 v[122:123], v[66:69], off offset:256
	s_nop 1
	v_mov_b32_e32 v66, v192
	v_mul_f32_e32 v70, v61, v66
	v_mul_f32_e32 v67, v64, v66
	v_mul_f32_e32 v68, v65, v66
	v_mul_f32_e32 v69, v60, v66
	v_mul_f32_e32 v71, v62, v66
	v_mul_f32_e32 v72, v63, v66
	v_mul_f32_e32 v73, v58, v66
	v_mul_f32_e32 v66, v59, v66
	v_mul_f32_e32 v53, v66, v53
	v_mul_f32_e32 v54, v67, v54
	v_mul_f32_e32 v55, v68, v55
	v_mul_f32_e32 v56, v69, v56
	v_mul_f32_e32 v57, v70, v57
	v_mul_f32_e32 v67, v71, v50
	v_mul_f32_e32 v68, v72, v51
	v_mul_f32_e32 v69, v73, v52
	v_cvt_pk_bf16_f32 v50, v54, v55
	v_cvt_pk_bf16_f32 v51, v56, v57
	v_cvt_pk_bf16_f32 v52, v67, v68
	v_cvt_pk_bf16_f32 v53, v69, v53
	global_store_dwordx4 v[116:117], v[50:53], off offset:256
	s_nop 1
	v_mov_b32_e32 v50, v194
	v_mul_f32_e32 v54, v61, v50
	v_mul_f32_e32 v51, v64, v50
	v_mul_f32_e32 v52, v65, v50
	v_mul_f32_e32 v53, v60, v50
	v_mul_f32_e32 v55, v62, v50
	v_mul_f32_e32 v56, v63, v50
	v_mul_f32_e32 v57, v58, v50
	v_mul_f32_e32 v50, v59, v50
	v_mul_f32_e32 v45, v50, v45
	v_mul_f32_e32 v46, v51, v46
	v_mul_f32_e32 v47, v52, v47
	v_mul_f32_e32 v48, v53, v48
	v_mul_f32_e32 v49, v54, v49
	v_mul_f32_e32 v51, v55, v42
	v_mul_f32_e32 v52, v56, v43
	v_mul_f32_e32 v53, v57, v44
	v_cvt_pk_bf16_f32 v42, v46, v47
	v_cvt_pk_bf16_f32 v43, v48, v49
	v_cvt_pk_bf16_f32 v44, v51, v52
	v_cvt_pk_bf16_f32 v45, v53, v45
	global_store_dwordx4 v[108:109], v[42:45], off offset:256
	s_nop 1
	v_mov_b32_e32 v42, v196
	v_mul_f32_e32 v46, v61, v42
	v_mul_f32_e32 v43, v64, v42
	v_mul_f32_e32 v44, v65, v42
	v_mul_f32_e32 v45, v60, v42
	v_mul_f32_e32 v47, v62, v42
	v_mul_f32_e32 v48, v63, v42
	v_mul_f32_e32 v49, v58, v42
	v_mul_f32_e32 v42, v59, v42
	v_mul_f32_e32 v37, v42, v37
	v_mul_f32_e32 v38, v43, v38
	v_mul_f32_e32 v39, v44, v39
	v_mul_f32_e32 v40, v45, v40
	v_mul_f32_e32 v41, v46, v41
	v_mul_f32_e32 v43, v47, v34
	v_mul_f32_e32 v44, v48, v35
	v_mul_f32_e32 v45, v49, v36
	v_cvt_pk_bf16_f32 v34, v38, v39
	v_cvt_pk_bf16_f32 v35, v40, v41
	v_cvt_pk_bf16_f32 v36, v43, v44
	v_cvt_pk_bf16_f32 v37, v45, v37
	global_store_dwordx4 v[98:99], v[34:37], off offset:256
	s_nop 1
	v_mov_b32_e32 v34, v198
	v_mul_f32_e32 v38, v65, v34
	v_cvt_f32_i32_e32 v35, v30
	v_cvt_f32_i32_e32 v36, v31
	v_mul_f32_e32 v37, v64, v34
	v_mul_f32_e32 v39, v60, v34
	v_mul_f32_e32 v40, v61, v34
	v_mul_f32_e32 v41, v62, v34
	v_mul_f32_e32 v42, v63, v34
	v_mul_f32_e32 v43, v58, v34
	v_mul_f32_e32 v34, v59, v34
	v_lshl_add_u64 v[30:31], v[122:123], 0, s[26:27]
	v_mul_f32_e32 v29, v34, v29
	v_mul_f32_e32 v35, v37, v35
	v_mul_f32_e32 v36, v38, v36
	v_mul_f32_e32 v32, v39, v32
	v_mul_f32_e32 v33, v40, v33
	v_mul_f32_e32 v37, v41, v26
	v_mul_f32_e32 v38, v42, v27
	v_mul_f32_e32 v39, v43, v28
	v_cvt_pk_bf16_f32 v26, v35, v36
	v_cvt_pk_bf16_f32 v27, v32, v33
	v_cvt_pk_bf16_f32 v28, v37, v38
	v_cvt_pk_bf16_f32 v29, v39, v29
	global_store_dwordx4 v[30:31], v[26:29], off offset:256
	s_nop 1
	v_mov_b32_e32 v26, v200
	v_mul_f32_e32 v30, v65, v26
	v_cvt_f32_i32_e32 v27, v22
	v_cvt_f32_i32_e32 v28, v23
	v_mul_f32_e32 v29, v64, v26
	v_mul_f32_e32 v31, v60, v26
	v_mul_f32_e32 v32, v61, v26
	v_mul_f32_e32 v33, v62, v26
	v_mul_f32_e32 v34, v63, v26
	v_mul_f32_e32 v35, v58, v26
	v_mul_f32_e32 v26, v59, v26
	v_lshl_add_u64 v[22:23], v[122:123], 0, s[28:29]
	v_mul_f32_e32 v21, v26, v21
	v_mul_f32_e32 v27, v29, v27
	v_mul_f32_e32 v28, v30, v28
	v_mul_f32_e32 v24, v31, v24
	v_mul_f32_e32 v25, v32, v25
	v_mul_f32_e32 v29, v33, v18
	v_mul_f32_e32 v30, v34, v19
	v_mul_f32_e32 v31, v35, v20
	v_cvt_pk_bf16_f32 v18, v27, v28
	v_cvt_pk_bf16_f32 v19, v24, v25
	v_cvt_pk_bf16_f32 v20, v29, v30
	v_cvt_pk_bf16_f32 v21, v31, v21
	global_store_dwordx4 v[22:23], v[18:21], off offset:256
	s_nop 1
	v_mov_b32_e32 v18, v202
	v_mul_f32_e32 v22, v65, v18
	v_cvt_f32_i32_e32 v19, v14
	v_cvt_f32_i32_e32 v20, v15
	v_mul_f32_e32 v21, v64, v18
	v_mul_f32_e32 v23, v60, v18
	v_mul_f32_e32 v24, v61, v18
	v_mul_f32_e32 v25, v62, v18
	v_mul_f32_e32 v26, v63, v18
	v_mul_f32_e32 v27, v58, v18
	v_mul_f32_e32 v18, v59, v18
	v_lshl_add_u64 v[14:15], v[122:123], 0, s[36:37]
	v_mul_f32_e32 v13, v18, v13
	v_mul_f32_e32 v19, v21, v19
	v_mul_f32_e32 v20, v22, v20
	v_mul_f32_e32 v16, v23, v16
	v_mul_f32_e32 v17, v24, v17
	v_mul_f32_e32 v21, v25, v10
	v_mul_f32_e32 v22, v26, v11
	v_mul_f32_e32 v23, v27, v12
	v_cvt_pk_bf16_f32 v10, v19, v20
	v_cvt_pk_bf16_f32 v11, v16, v17
	v_cvt_pk_bf16_f32 v12, v21, v22
	v_cvt_pk_bf16_f32 v13, v23, v13
	global_store_dwordx4 v[14:15], v[10:13], off offset:256
	s_nop 1
	v_mov_b32_e32 v10, v204
	v_mul_f32_e32 v14, v65, v10
	v_cvt_f32_i32_e32 v11, v6
	v_cvt_f32_i32_e32 v12, v7
	v_mul_f32_e32 v13, v64, v10
	v_mul_f32_e32 v15, v60, v10
	v_mul_f32_e32 v16, v61, v10
	v_mul_f32_e32 v17, v62, v10
	v_mul_f32_e32 v18, v63, v10
	v_mul_f32_e32 v19, v58, v10
	v_mul_f32_e32 v10, v59, v10
	v_lshl_add_u64 v[6:7], v[122:123], 0, s[38:39]
	v_mul_f32_e32 v5, v10, v5
	v_mul_f32_e32 v11, v13, v11
	v_mul_f32_e32 v12, v14, v12
	v_mul_f32_e32 v8, v15, v8
	v_mul_f32_e32 v9, v16, v9
	v_mul_f32_e32 v13, v17, v2
	v_mul_f32_e32 v14, v18, v3
	v_mul_f32_e32 v15, v19, v4
	v_cvt_pk_bf16_f32 v2, v11, v12
	v_cvt_pk_bf16_f32 v3, v8, v9
	v_cvt_pk_bf16_f32 v4, v13, v14
	v_cvt_pk_bf16_f32 v5, v15, v5
	global_store_dwordx4 v[6:7], v[2:5], off offset:256
	s_cbranch_vccnz .LBB0_1590
	s_andn2_b64 vcc, exec, s[8:9]
	s_cbranch_vccnz .LBB0_1589
	s_barrier
	s_branch .LBB0_1589
